# GEMM ping-pong phases: the barrier closing a wave's MFMA block is issued 6 MFMAs before the block's end (release latency under the last MFMAs)
# baseline (speedup 1.0000x reference)
; #define PG8_STAGE(bufoff, gbase, voff) do { if constexpr (ABL & 1) break; glds16s<(bufoff)>((voff)[0], (const void*)(gbase), ldsbw); glds16s<(bufoff) + 8192>((voff)[1], (const void*)(gbase), ldsbw); } while (0)
; #define PG8_LDA(dst, b, h) do { if constexpr (ABL & 4) break; _Pragma("unroll") for (int m = 0; m < 4; ++m) _Pragma("unroll") for (int k = 0; k < 2; ++k) dst[m][k] = *(const LAS f16x8*)(lds + PG8_SA(b, h) + aoff + m * 2048 + k * 1024); } while (0)
; #define PG8_LDB(dst, b, h) do { if constexpr (ABL & 4) break; _Pragma("unroll") for (int n = 0; n < 2; ++n) _Pragma("unroll") for (int k = 0; k < 2; ++k) dst[n][k] = *(const LAS f16x8*)(lds + PG8_SB(b, h) + boff + n * 2048 + k * 1024); } while (0)
; #define PG8_MMA(ai, bj, At, Bt) do { if constexpr (ABL & 2) break; __builtin_amdgcn_s_setprio(1); _Pragma("unroll") for (int m = 0; m < 4; ++m) _Pragma("unroll") for (int n = 0; n < 2; ++n) _Pragma("unroll") for (int k = 0; k < 2; ++k) \
;         acc[ai][bj][m][n] = __builtin_amdgcn_mfma_f32_16x16x32_f16(Bt[n][k], At[m][k], acc[ai][bj][m][n], 0, 0, 0); __builtin_amdgcn_s_setprio(0); } while (0)
; #define PG8_MMAF(ai, bj, At, Bt) do { if (t == 0) PG8_MMA0(ai, bj, At, Bt); else PG8_MMA(ai, bj, At, Bt); } while (0)
; #define PG8_WAIT_V(n) asm volatile("s_waitcnt vmcnt(" #n ")" ::: "memory")
; #define PG8_WAIT_L(n) asm volatile("s_waitcnt lgkmcnt(" #n ")" ::: "memory")
; #define PG8_BAR __builtin_amdgcn_s_barrier()
;     ...
;             if constexpr (SP2) {
;             PG8_LDB(B0, 0, 0); PG8_LDB(B1, 0, 1); PG8_SCHED; PG8_LDA(At, 0, 0); PG8_STAGE(PG8_SA(1, 1), a1 + hstep, voffA);
;             PG8_WAIT_V(8); PG8_WAIT_L(0); PG8_BAR; PG8_MMAF(0, 0, At, B0); PG8_MMAF(0, 1, At, B1); PG8_BAR; PG8_SCHED;
;             const bool fin = last && !has_next;
;             PG8_LDA(At, 0, 1); if (!fin) { PG8_STAGE(PG8_SB(0, 0), b2, voffB); PG8_STAGE(PG8_SB(0, 1), b2 + hstep, voffB); PG8_STAGE(PG8_SA(0, 0), a2, voffA); }
;             if (!fin) PG8_WAIT_V(8); else PG8_WAIT_V(2); PG8_WAIT_L(0); PG8_BAR; PG8_MMAF(1, 0, At, B0); PG8_MMAF(1, 1, At, B1); PG8_BAR; PG8_SCHED;
;             PG8_LDB(B0, 1, 0); PG8_LDB(B1, 1, 1); PG8_SCHED; PG8_LDA(At, 1, 0); if (!fin) PG8_STAGE(PG8_SA(0, 1), a2 + hstep, voffA);
;             if (!fin) PG8_WAIT_V(8); else PG8_WAIT_V(0); PG8_WAIT_L(0); PG8_BAR; PG8_MMA(0, 0, At, B0); PG8_MMA(0, 1, At, B1); PG8_BAR; PG8_SCHED;
.LBB0_229:
	s_ashr_i32 s53, s52, 31
	s_lshl_b64 s[8:9], s[52:53], 19
	s_add_u32 s54, s74, s8
	s_addc_u32 s55, s75, s9
	s_and_b64 s[8:9], exec, s[4:5]
	ds_read_b128 v[2:5], v236
	ds_read_b128 v[6:9], v236 offset:1024
	ds_read_b128 v[10:13], v236 offset:2048
	ds_read_b128 v[14:17], v236 offset:3072
	ds_read_b128 v[18:21], v237
	ds_read_b128 v[22:25], v237 offset:1024
	ds_read_b128 v[26:29], v237 offset:2048
	ds_read_b128 v[30:33], v237 offset:3072
	s_cselect_b32 s11, s63, s55
	s_cselect_b32 s35, s62, s54
	s_ashr_i32 s1, s0, 31
	s_lshl_b64 s[8:9], s[0:1], 19
	s_add_u32 s56, s90, s8
	s_addc_u32 s57, s91, s9
	s_and_b64 s[8:9], exec, s[4:5]
	s_cselect_b32 s1, s7, s57
	s_cselect_b32 s46, s6, s56
	s_add_u32 s8, s62, 0x100
	s_addc_u32 s9, s63, 0
	s_add_u32 s64, s6, 0x100
	s_addc_u32 s65, s7, 0
	s_add_u32 s24, s62, 0x180
	s_addc_u32 s25, s63, 0
	ds_read_b128 v[34:37], v238
	ds_read_b128 v[38:41], v238 offset:1024
	ds_read_b128 v[42:45], v238 offset:2048
	ds_read_b128 v[46:49], v238 offset:3072
	ds_read_b128 v[50:53], v238 offset:4096
	ds_read_b128 v[54:57], v238 offset:5120
	ds_read_b128 v[58:61], v238 offset:6144
	ds_read_b128 v[62:65], v238 offset:7168
	s_add_u32 s26, s6, 0x180
	s_addc_u32 s27, s7, 0
	s_add_u32 s76, s62, 0x40080
	s_addc_u32 s77, s63, 0
	s_add_u32 m0, s28, 0xc000
	s_nop 0
	global_load_lds_dwordx4 v232, s[76:77]
	s_nop 0
	s_add_u32 m0, s28, 0xe000
	s_nop 0
	global_load_lds_dwordx4 v234, s[76:77]
	s_waitcnt vmcnt(8)
	s_waitcnt lgkmcnt(0)
	s_barrier
	v_mfma_f32_16x16x32_f16 v[86:89], v[10:13], v[50:53], 0
	s_setprio 1
	v_mfma_f32_16x16x32_f16 v[90:93], v[14:17], v[54:57], v[86:89]
	v_mfma_f32_16x16x32_f16 v[86:89], v[2:5], v[58:61], 0
	v_mfma_f32_16x16x32_f16 v[94:97], v[6:9], v[62:65], v[86:89]
	v_mfma_f32_16x16x32_f16 v[66:69], v[2:5], v[34:37], 0
	v_mfma_f32_16x16x32_f16 v[66:69], v[6:9], v[38:41], v[66:69]
	v_mfma_f32_16x16x32_f16 v[70:73], v[10:13], v[34:37], 0
	v_mfma_f32_16x16x32_f16 v[70:73], v[14:17], v[38:41], v[70:73]
	v_mfma_f32_16x16x32_f16 v[74:77], v[2:5], v[42:45], 0
	v_mfma_f32_16x16x32_f16 v[74:77], v[6:9], v[46:49], v[74:77]
	v_mfma_f32_16x16x32_f16 v[78:81], v[10:13], v[42:45], 0
	v_mfma_f32_16x16x32_f16 v[78:81], v[14:17], v[46:49], v[78:81]
	v_mfma_f32_16x16x32_f16 v[82:85], v[2:5], v[50:53], 0
	v_mfma_f32_16x16x32_f16 v[82:85], v[6:9], v[54:57], v[82:85]
	v_mfma_f32_16x16x32_f16 v[86:89], v[10:13], v[58:61], 0
	v_mfma_f32_16x16x32_f16 v[106:109], v[14:17], v[62:65], v[86:89]
	v_mfma_f32_16x16x32_f16 v[86:89], v[18:21], v[34:37], 0
	v_mfma_f32_16x16x32_f16 v[34:37], v[26:29], v[34:37], 0
	v_mfma_f32_16x16x32_f16 v[110:113], v[22:25], v[38:41], v[86:89]
	v_mfma_f32_16x16x32_f16 v[34:37], v[30:33], v[38:41], v[34:37]
	v_mfma_f32_16x16x32_f16 v[38:41], v[18:21], v[42:45], 0
	v_mfma_f32_16x16x32_f16 v[42:45], v[26:29], v[42:45], 0
	v_mfma_f32_16x16x32_f16 v[38:41], v[22:25], v[46:49], v[38:41]
	v_mfma_f32_16x16x32_f16 v[42:45], v[30:33], v[46:49], v[42:45]
	v_mfma_f32_16x16x32_f16 v[46:49], v[18:21], v[50:53], 0
	v_mfma_f32_16x16x32_f16 v[50:53], v[26:29], v[50:53], 0
	s_barrier
	v_mfma_f32_16x16x32_f16 v[46:49], v[22:25], v[54:57], v[46:49]
	v_mfma_f32_16x16x32_f16 v[54:57], v[30:33], v[54:57], v[50:53]
	v_mfma_f32_16x16x32_f16 v[50:53], v[18:21], v[58:61], 0
	v_mfma_f32_16x16x32_f16 v[130:133], v[22:25], v[62:65], v[50:53]
	v_mfma_f32_16x16x32_f16 v[50:53], v[26:29], v[58:61], 0
	v_mfma_f32_16x16x32_f16 v[62:65], v[30:33], v[62:65], v[50:53]
	s_setprio 0
	s_nop 4
	ds_read_b128 v[50:53], v238 offset:16384
	ds_read_b128 v[58:61], v238 offset:17408
	ds_read_b128 v[86:89], v238 offset:18432
	ds_read_b128 v[98:101], v238 offset:19456
	ds_read_b128 v[102:105], v238 offset:20480
	ds_read_b128 v[114:117], v238 offset:21504
	ds_read_b128 v[118:121], v238 offset:22528
	ds_read_b128 v[122:125], v238 offset:23552
	s_add_u32 m0, s28, 0x10000
	s_nop 0
	global_load_lds_dwordx4 v233, s[64:65]
	s_nop 0
	s_add_u32 m0, s28, 0x12000
	s_nop 0
	global_load_lds_dwordx4 v235, s[64:65]
	s_add_u32 s64, s6, 0x40100
	s_addc_u32 s65, s7, 0
	s_add_u32 m0, s28, 0x14000
	s_nop 0
	global_load_lds_dwordx4 v233, s[64:65]
	s_nop 0
	s_add_u32 m0, s28, 0x16000
	s_nop 0
	global_load_lds_dwordx4 v235, s[64:65]
	s_nop 0
	s_add_u32 m0, s28, 0
	s_nop 0
	global_load_lds_dwordx4 v232, s[8:9]
	s_nop 0
	s_add_u32 m0, s28, 0x2000
	s_nop 0
	global_load_lds_dwordx4 v234, s[8:9]
	s_waitcnt vmcnt(8)
	s_waitcnt lgkmcnt(0)
	s_barrier
	v_mfma_f32_16x16x32_f16 v[126:129], v[2:5], v[50:53], 0
	s_setprio 1
	v_mfma_f32_16x16x32_f16 v[134:137], v[6:9], v[58:61], v[126:129]
	v_mfma_f32_16x16x32_f16 v[126:129], v[10:13], v[50:53], 0
	v_mfma_f32_16x16x32_f16 v[138:141], v[14:17], v[58:61], v[126:129]
	v_mfma_f32_16x16x32_f16 v[126:129], v[2:5], v[86:89], 0
	v_mfma_f32_16x16x32_f16 v[142:145], v[6:9], v[98:101], v[126:129]
	v_mfma_f32_16x16x32_f16 v[126:129], v[10:13], v[86:89], 0
	v_mfma_f32_16x16x32_f16 v[146:149], v[14:17], v[98:101], v[126:129]
	v_mfma_f32_16x16x32_f16 v[126:129], v[2:5], v[102:105], 0
	v_mfma_f32_16x16x32_f16 v[150:153], v[6:9], v[114:117], v[126:129]
	v_mfma_f32_16x16x32_f16 v[2:5], v[2:5], v[118:121], 0
	v_mfma_f32_16x16x32_f16 v[2:5], v[6:9], v[122:125], v[2:5]
	v_mfma_f32_16x16x32_f16 v[6:9], v[10:13], v[118:121], 0
	v_mfma_f32_16x16x32_f16 v[126:129], v[10:13], v[102:105], 0
	v_mfma_f32_16x16x32_f16 v[154:157], v[14:17], v[114:117], v[126:129]
	v_mfma_f32_16x16x32_f16 v[10:13], v[14:17], v[122:125], v[6:9]
	v_mfma_f32_16x16x32_f16 v[6:9], v[18:21], v[50:53], 0
	v_mfma_f32_16x16x32_f16 v[158:161], v[22:25], v[58:61], v[6:9]
	v_mfma_f32_16x16x32_f16 v[6:9], v[26:29], v[50:53], 0
	v_mfma_f32_16x16x32_f16 v[162:165], v[30:33], v[58:61], v[6:9]
	v_mfma_f32_16x16x32_f16 v[6:9], v[18:21], v[86:89], 0
	v_mfma_f32_16x16x32_f16 v[166:169], v[22:25], v[98:101], v[6:9]
	v_mfma_f32_16x16x32_f16 v[6:9], v[26:29], v[86:89], 0
	v_mfma_f32_16x16x32_f16 v[170:173], v[30:33], v[98:101], v[6:9]
	v_mfma_f32_16x16x32_f16 v[6:9], v[18:21], v[102:105], 0
	v_mfma_f32_16x16x32_f16 v[174:177], v[22:25], v[114:117], v[6:9]
	s_barrier
; #define PG8_STAGE(bufoff, gbase, voff) do { if constexpr (ABL & 1) break; glds16s<(bufoff)>((voff)[0], (const void*)(gbase), ldsbw); glds16s<(bufoff) + 8192>((voff)[1], (const void*)(gbase), ldsbw); } while (0)
; #define PG8_LDA(dst, b, h) do { if constexpr (ABL & 4) break; _Pragma("unroll") for (int m = 0; m < 4; ++m) _Pragma("unroll") for (int k = 0; k < 2; ++k) dst[m][k] = *(const LAS f16x8*)(lds + PG8_SA(b, h) + aoff + m * 2048 + k * 1024); } while (0)
; #define PG8_LDB(dst, b, h) do { if constexpr (ABL & 4) break; _Pragma("unroll") for (int n = 0; n < 2; ++n) _Pragma("unroll") for (int k = 0; k < 2; ++k) dst[n][k] = *(const LAS f16x8*)(lds + PG8_SB(b, h) + boff + n * 2048 + k * 1024); } while (0)
; #define PG8_MMA(ai, bj, At, Bt) do { if constexpr (ABL & 2) break; __builtin_amdgcn_s_setprio(1); _Pragma("unroll") for (int m = 0; m < 4; ++m) _Pragma("unroll") for (int n = 0; n < 2; ++n) _Pragma("unroll") for (int k = 0; k < 2; ++k) \
;         acc[ai][bj][m][n] = __builtin_amdgcn_mfma_f32_16x16x32_f16(Bt[n][k], At[m][k], acc[ai][bj][m][n], 0, 0, 0); __builtin_amdgcn_s_setprio(0); } while (0)
; #define PG8_BAR __builtin_amdgcn_s_barrier()
;     ...
;             if constexpr (SP2) {
;             PG8_LDB(B0, 0, 0); PG8_LDB(B1, 0, 1); PG8_SCHED; PG8_LDA(At, 0, 0); PG8_STAGE(PG8_SA(1, 1), a1 + hstep, voffA);
;             PG8_WAIT_V(8); PG8_WAIT_L(0); PG8_BAR; PG8_MMAF(0, 0, At, B0); PG8_MMAF(0, 1, At, B1); PG8_BAR; PG8_SCHED;
;             const bool fin = last && !has_next;
;             PG8_LDA(At, 0, 1); if (!fin) { PG8_STAGE(PG8_SB(0, 0), b2, voffB); PG8_STAGE(PG8_SB(0, 1), b2 + hstep, voffB); PG8_STAGE(PG8_SA(0, 0), a2, voffA); }
;             if (!fin) PG8_WAIT_V(8); else PG8_WAIT_V(2); PG8_WAIT_L(0); PG8_BAR; PG8_MMAF(1, 0, At, B0); PG8_MMAF(1, 1, At, B1); PG8_BAR; PG8_SCHED;
;             PG8_LDB(B0, 1, 0); PG8_LDB(B1, 1, 1); PG8_SCHED; PG8_LDA(At, 1, 0); if (!fin) PG8_STAGE(PG8_SA(0, 1), a2 + hstep, voffA);
;             if (!fin) PG8_WAIT_V(8); else PG8_WAIT_V(0); PG8_WAIT_L(0); PG8_BAR; PG8_MMA(0, 0, At, B0); PG8_MMA(0, 1, At, B1); PG8_BAR; PG8_SCHED;
;             PG8_LDA(At, 1, 1); if (!fin) { PG8_STAGE(PG8_SB(1, 0), b3, voffB); PG8_STAGE(PG8_SB(1, 1), b3 + hstep, voffB); PG8_STAGE(PG8_SA(1, 0), a3, voffA); }
;             if (!fin) PG8_WAIT_V(8); PG8_WAIT_L(0); PG8_BAR; PG8_MMA(1, 0, At, B0); PG8_MMA(1, 1, At, B1); PG8_BAR; PG8_SCHED;
	v_mfma_f32_16x16x32_f16 v[6:9], v[26:29], v[102:105], 0
	v_mfma_f32_16x16x32_f16 v[178:181], v[30:33], v[114:117], v[6:9]
	v_mfma_f32_16x16x32_f16 v[6:9], v[18:21], v[118:121], 0
	v_mfma_f32_16x16x32_f16 v[22:25], v[22:25], v[122:125], v[6:9]
	v_mfma_f32_16x16x32_f16 v[6:9], v[26:29], v[118:121], 0
	v_mfma_f32_16x16x32_f16 v[182:185], v[30:33], v[122:125], v[6:9]
	s_setprio 0
	s_nop 4
	ds_read_b128 v[6:9], v239
	ds_read_b128 v[26:29], v239 offset:1024
	ds_read_b128 v[186:189], v239 offset:2048
	ds_read_b128 v[190:193], v239 offset:3072
	ds_read_b128 v[206:209], v240
	ds_read_b128 v[210:213], v240 offset:1024
	ds_read_b128 v[214:217], v240 offset:2048
	ds_read_b128 v[218:221], v240 offset:3072
	ds_read_b128 v[14:17], v238 offset:32768
	ds_read_b128 v[18:21], v238 offset:33792
	ds_read_b128 v[30:33], v238 offset:34816
	ds_read_b128 v[222:225], v238 offset:35840
	ds_read_b128 v[226:229], v238 offset:36864
	ds_read_b128 v[242:245], v238 offset:37888
	ds_read_b128 v[246:249], v238 offset:38912
	ds_read_b128 v[250:253], v238 offset:39936
	s_add_u32 s62, s62, 0x40100
	s_addc_u32 s63, s63, 0
	s_add_u32 m0, s28, 0x4000
	s_nop 0
	global_load_lds_dwordx4 v232, s[62:63]
	s_nop 0
	s_add_u32 m0, s28, 0x6000
	s_nop 0
	global_load_lds_dwordx4 v234, s[62:63]
	s_waitcnt vmcnt(8)
	s_waitcnt lgkmcnt(0)
	s_barrier
	v_mfma_f32_16x16x32_f16 v[50:53], v[6:9], v[14:17], v[66:69]
	s_setprio 1
	v_mfma_f32_16x16x32_f16 v[118:121], v[26:29], v[18:21], v[50:53]
	v_mfma_f32_16x16x32_f16 v[50:53], v[186:189], v[14:17], v[70:73]
	v_mfma_f32_16x16x32_f16 v[114:117], v[190:193], v[18:21], v[50:53]
	v_mfma_f32_16x16x32_f16 v[50:53], v[6:9], v[30:33], v[74:77]
	v_mfma_f32_16x16x32_f16 v[102:105], v[26:29], v[222:225], v[50:53]
	v_mfma_f32_16x16x32_f16 v[50:53], v[186:189], v[30:33], v[78:81]
	v_mfma_f32_16x16x32_f16 v[98:101], v[190:193], v[222:225], v[50:53]
	v_mfma_f32_16x16x32_f16 v[50:53], v[6:9], v[226:229], v[82:85]
	v_mfma_f32_16x16x32_f16 v[86:89], v[26:29], v[242:245], v[50:53]
	v_mfma_f32_16x16x32_f16 v[50:53], v[186:189], v[226:229], v[90:93]
	v_mfma_f32_16x16x32_f16 v[78:81], v[190:193], v[242:245], v[50:53]
	v_mfma_f32_16x16x32_f16 v[50:53], v[6:9], v[246:249], v[94:97]
	v_mfma_f32_16x16x32_f16 v[58:61], v[26:29], v[250:253], v[50:53]
	v_mfma_f32_16x16x32_f16 v[50:53], v[186:189], v[246:249], v[106:109]
	v_mfma_f32_16x16x32_f16 v[50:53], v[190:193], v[250:253], v[50:53]
	v_mfma_f32_16x16x32_f16 v[66:69], v[206:209], v[14:17], v[110:113]
	v_mfma_f32_16x16x32_f16 v[126:129], v[210:213], v[18:21], v[66:69]
	v_mfma_f32_16x16x32_f16 v[14:17], v[214:217], v[14:17], v[34:37]
	v_mfma_f32_16x16x32_f16 v[122:125], v[218:221], v[18:21], v[14:17]
	v_mfma_f32_16x16x32_f16 v[14:17], v[206:209], v[30:33], v[38:41]
	v_mfma_f32_16x16x32_f16 v[110:113], v[210:213], v[222:225], v[14:17]
	v_mfma_f32_16x16x32_f16 v[14:17], v[214:217], v[30:33], v[42:45]
	v_mfma_f32_16x16x32_f16 v[106:109], v[218:221], v[222:225], v[14:17]
	v_mfma_f32_16x16x32_f16 v[14:17], v[206:209], v[226:229], v[46:49]
	v_mfma_f32_16x16x32_f16 v[94:97], v[210:213], v[242:245], v[14:17]
	s_barrier
	v_mfma_f32_16x16x32_f16 v[14:17], v[214:217], v[226:229], v[54:57]
	v_mfma_f32_16x16x32_f16 v[90:93], v[218:221], v[242:245], v[14:17]
	v_mfma_f32_16x16x32_f16 v[14:17], v[206:209], v[246:249], v[130:133]
	v_mfma_f32_16x16x32_f16 v[74:77], v[210:213], v[250:253], v[14:17]
	v_mfma_f32_16x16x32_f16 v[14:17], v[214:217], v[246:249], v[62:65]
	v_mfma_f32_16x16x32_f16 v[66:69], v[218:221], v[250:253], v[14:17]
	s_setprio 0
	ds_read_b128 v[38:41], v238 offset:49152
	ds_read_b128 v[42:45], v238 offset:50176
	ds_read_b128 v[130:133], v238 offset:51200
	ds_read_b128 v[222:225], v238 offset:52224
	ds_read_b128 v[226:229], v238 offset:53248
	ds_read_b128 v[242:245], v238 offset:54272
	ds_read_b128 v[246:249], v238 offset:55296
	ds_read_b128 v[250:253], v238 offset:56320
	s_add_u32 m0, s28, 0x18000
	s_nop 0
	global_load_lds_dwordx4 v233, s[26:27]
	s_nop 0
	s_add_u32 m0, s28, 0x1a000
	s_nop 0
	global_load_lds_dwordx4 v235, s[26:27]
	s_add_u32 s26, s6, 0x40180
	s_addc_u32 s27, s7, 0
	s_add_u32 m0, s28, 0x1c000
	s_nop 0
	global_load_lds_dwordx4 v233, s[26:27]
	s_nop 0
	s_add_u32 m0, s28, 0x1e000
	s_nop 0
	global_load_lds_dwordx4 v235, s[26:27]
	s_nop 0
	s_add_u32 m0, s28, 0x8000
	s_nop 0
	global_load_lds_dwordx4 v232, s[24:25]
	s_nop 0
	s_add_u32 m0, s28, 0xa000
	s_nop 0
	global_load_lds_dwordx4 v234, s[24:25]
	s_waitcnt vmcnt(8)
	s_waitcnt lgkmcnt(0)
	s_barrier
	v_mfma_f32_16x16x32_f16 v[14:17], v[6:9], v[38:41], v[134:137]
	s_setprio 1
	v_mfma_f32_16x16x32_f16 v[54:57], v[26:29], v[42:45], v[14:17]
	v_mfma_f32_16x16x32_f16 v[14:17], v[190:193], v[42:45], v[138:141]
	v_mfma_f32_16x16x32_f16 v[46:49], v[186:189], v[38:41], v[14:17]
	v_mfma_f32_16x16x32_f16 v[14:17], v[6:9], v[130:133], v[142:145]
	v_mfma_f32_16x16x32_f16 v[34:37], v[26:29], v[222:225], v[14:17]
	v_mfma_f32_16x16x32_f16 v[14:17], v[190:193], v[222:225], v[146:149]
	v_mfma_f32_16x16x32_f16 v[30:33], v[186:189], v[130:133], v[14:17]
	v_mfma_f32_16x16x32_f16 v[14:17], v[6:9], v[226:229], v[150:153]
	v_mfma_f32_16x16x32_f16 v[18:21], v[26:29], v[242:245], v[14:17]
	v_mfma_f32_16x16x32_f16 v[2:5], v[26:29], v[250:253], v[2:5]
	v_mfma_f32_16x16x32_f16 v[6:9], v[6:9], v[246:249], v[2:5]
	v_mfma_f32_16x16x32_f16 v[2:5], v[186:189], v[246:249], v[10:13]
	v_mfma_f32_16x16x32_f16 v[2:5], v[190:193], v[250:253], v[2:5]
	v_mfma_f32_16x16x32_f16 v[14:17], v[190:193], v[242:245], v[154:157]
	v_mfma_f32_16x16x32_f16 v[14:17], v[186:189], v[226:229], v[14:17]
	v_mfma_f32_16x16x32_f16 v[10:13], v[206:209], v[38:41], v[158:161]
	v_mfma_f32_16x16x32_f16 v[82:85], v[210:213], v[42:45], v[10:13]
	v_mfma_f32_16x16x32_f16 v[10:13], v[218:221], v[42:45], v[162:165]
	v_mfma_f32_16x16x32_f16 v[70:73], v[214:217], v[38:41], v[10:13]
	v_mfma_f32_16x16x32_f16 v[10:13], v[206:209], v[130:133], v[166:169]
	v_mfma_f32_16x16x32_f16 v[62:65], v[210:213], v[222:225], v[10:13]
	v_mfma_f32_16x16x32_f16 v[10:13], v[218:221], v[222:225], v[170:173]
	v_mfma_f32_16x16x32_f16 v[42:45], v[214:217], v[130:133], v[10:13]
	v_mfma_f32_16x16x32_f16 v[10:13], v[206:209], v[226:229], v[174:177]
	v_mfma_f32_16x16x32_f16 v[38:41], v[210:213], v[242:245], v[10:13]
	s_barrier
	v_mfma_f32_16x16x32_f16 v[10:13], v[218:221], v[242:245], v[178:181]
	v_mfma_f32_16x16x32_f16 v[26:29], v[214:217], v[226:229], v[10:13]
	v_mfma_f32_16x16x32_f16 v[10:13], v[206:209], v[246:249], v[22:25]
	v_mfma_f32_16x16x32_f16 v[22:25], v[210:213], v[250:253], v[10:13]
	v_mfma_f32_16x16x32_f16 v[10:13], v[218:221], v[250:253], v[182:185]
	v_mfma_f32_16x16x32_f16 v[10:13], v[214:217], v[246:249], v[10:13]
	s_setprio 0
	s_add_u32 s53, s6, 0x200
	s_addc_u32 s61, s7, 0
	s_mov_b32 s64, 0
	s_branch .LBB0_231
; #define PG8_STAGE(bufoff, gbase, voff) do { if constexpr (ABL & 1) break; glds16s<(bufoff)>((voff)[0], (const void*)(gbase), ldsbw); glds16s<(bufoff) + 8192>((voff)[1], (const void*)(gbase), ldsbw); } while (0)
; #define PG8_LDA(dst, b, h) do { if constexpr (ABL & 4) break; _Pragma("unroll") for (int m = 0; m < 4; ++m) _Pragma("unroll") for (int k = 0; k < 2; ++k) dst[m][k] = *(const LAS f16x8*)(lds + PG8_SA(b, h) + aoff + m * 2048 + k * 1024); } while (0)
; #define PG8_LDB(dst, b, h) do { if constexpr (ABL & 4) break; _Pragma("unroll") for (int n = 0; n < 2; ++n) _Pragma("unroll") for (int k = 0; k < 2; ++k) dst[n][k] = *(const LAS f16x8*)(lds + PG8_SB(b, h) + boff + n * 2048 + k * 1024); } while (0)
; #define PG8_MMA(ai, bj, At, Bt) do { if constexpr (ABL & 2) break; __builtin_amdgcn_s_setprio(1); _Pragma("unroll") for (int m = 0; m < 4; ++m) _Pragma("unroll") for (int n = 0; n < 2; ++n) _Pragma("unroll") for (int k = 0; k < 2; ++k) \
;         acc[ai][bj][m][n] = __builtin_amdgcn_mfma_f32_16x16x32_f16(Bt[n][k], At[m][k], acc[ai][bj][m][n], 0, 0, 0); __builtin_amdgcn_s_setprio(0); } while (0)
; #define PG8_BAR __builtin_amdgcn_s_barrier()
;     ...
;             if constexpr (SP2) {
;             PG8_LDB(B0, 0, 0); PG8_LDB(B1, 0, 1); PG8_SCHED; PG8_LDA(At, 0, 0); PG8_STAGE(PG8_SA(1, 1), a1 + hstep, voffA);
;             PG8_WAIT_V(8); PG8_WAIT_L(0); PG8_BAR; PG8_MMAF(0, 0, At, B0); PG8_MMAF(0, 1, At, B1); PG8_BAR; PG8_SCHED;
;             const bool fin = last && !has_next;
;             PG8_LDA(At, 0, 1); if (!fin) { PG8_STAGE(PG8_SB(0, 0), b2, voffB); PG8_STAGE(PG8_SB(0, 1), b2 + hstep, voffB); PG8_STAGE(PG8_SA(0, 0), a2, voffA); }
;             if (!fin) PG8_WAIT_V(8); else PG8_WAIT_V(2); PG8_WAIT_L(0); PG8_BAR; PG8_MMAF(1, 0, At, B0); PG8_MMAF(1, 1, At, B1); PG8_BAR; PG8_SCHED;
;             PG8_LDB(B0, 1, 0); PG8_LDB(B1, 1, 1); PG8_SCHED; PG8_LDA(At, 1, 0); if (!fin) PG8_STAGE(PG8_SA(0, 1), a2 + hstep, voffA);
;             if (!fin) PG8_WAIT_V(8); else PG8_WAIT_V(0); PG8_WAIT_L(0); PG8_BAR; PG8_MMA(0, 0, At, B0); PG8_MMA(0, 1, At, B1); PG8_BAR; PG8_SCHED;
;             PG8_LDA(At, 1, 1); if (!fin) { PG8_STAGE(PG8_SB(1, 0), b3, voffB); PG8_STAGE(PG8_SB(1, 1), b3 + hstep, voffB); PG8_STAGE(PG8_SA(1, 0), a3, voffA); }
;             if (!fin) PG8_WAIT_V(8); PG8_WAIT_L(0); PG8_BAR; PG8_MMA(1, 0, At, B0); PG8_MMA(1, 1, At, B1); PG8_BAR; PG8_SCHED;
.LBB0_230:
	s_waitcnt lgkmcnt(0)
	s_barrier
	v_mfma_f32_16x16x32_f16 v[54:57], v[154:157], v[186:189], v[54:57]
	s_setprio 1
	v_mfma_f32_16x16x32_f16 v[54:57], v[158:161], v[190:193], v[54:57]
	v_mfma_f32_16x16x32_f16 v[46:49], v[150:153], v[190:193], v[46:49]
	v_mfma_f32_16x16x32_f16 v[46:49], v[146:149], v[186:189], v[46:49]
	v_mfma_f32_16x16x32_f16 v[30:33], v[146:149], v[178:181], v[30:33]
	v_mfma_f32_16x16x32_f16 v[30:33], v[150:153], v[182:185], v[30:33]
	v_mfma_f32_16x16x32_f16 v[34:37], v[158:161], v[182:185], v[34:37]
	v_mfma_f32_16x16x32_f16 v[34:37], v[154:157], v[178:181], v[34:37]
	v_mfma_f32_16x16x32_f16 v[18:21], v[154:157], v[170:173], v[18:21]
	v_mfma_f32_16x16x32_f16 v[18:21], v[158:161], v[174:177], v[18:21]
	v_mfma_f32_16x16x32_f16 v[14:17], v[150:153], v[174:177], v[14:17]
	v_mfma_f32_16x16x32_f16 v[14:17], v[146:149], v[170:173], v[14:17]
	v_mfma_f32_16x16x32_f16 v[2:5], v[146:149], v[162:165], v[2:5]
	v_mfma_f32_16x16x32_f16 v[2:5], v[150:153], v[166:169], v[2:5]
	v_mfma_f32_16x16x32_f16 v[6:9], v[158:161], v[166:169], v[6:9]
	v_mfma_f32_16x16x32_f16 v[6:9], v[154:157], v[162:165], v[6:9]
	v_mfma_f32_16x16x32_f16 v[22:25], v[138:141], v[162:165], v[22:25]
	v_mfma_f32_16x16x32_f16 v[22:25], v[142:145], v[166:169], v[22:25]
	v_mfma_f32_16x16x32_f16 v[82:85], v[142:145], v[190:193], v[82:85]
	v_mfma_f32_16x16x32_f16 v[82:85], v[138:141], v[186:189], v[82:85]
	v_mfma_f32_16x16x32_f16 v[70:73], v[130:133], v[186:189], v[70:73]
	v_mfma_f32_16x16x32_f16 v[70:73], v[134:137], v[190:193], v[70:73]
	v_mfma_f32_16x16x32_f16 v[42:45], v[134:137], v[182:185], v[42:45]
	v_mfma_f32_16x16x32_f16 v[42:45], v[130:133], v[178:181], v[42:45]
	v_mfma_f32_16x16x32_f16 v[62:65], v[138:141], v[178:181], v[62:65]
	v_mfma_f32_16x16x32_f16 v[62:65], v[142:145], v[182:185], v[62:65]
	s_barrier
	v_mfma_f32_16x16x32_f16 v[38:41], v[142:145], v[174:177], v[38:41]
	v_mfma_f32_16x16x32_f16 v[38:41], v[138:141], v[170:173], v[38:41]
	v_mfma_f32_16x16x32_f16 v[26:29], v[130:133], v[170:173], v[26:29]
	v_mfma_f32_16x16x32_f16 v[26:29], v[134:137], v[174:177], v[26:29]
	v_mfma_f32_16x16x32_f16 v[10:13], v[134:137], v[166:169], v[10:13]
	v_mfma_f32_16x16x32_f16 v[10:13], v[130:133], v[162:165], v[10:13]
	s_setprio 0
	s_add_i32 s64, s64, 2
	s_add_u32 s53, s53, 0x100
	s_addc_u32 s61, s61, 0
	s_cmp_gt_u32 s64, 13
	s_cbranch_scc1 .LBB0_241
.LBB0_231:
	ds_read_b128 v[146:149], v236
	ds_read_b128 v[150:153], v236 offset:1024
	ds_read_b128 v[154:157], v236 offset:2048
	ds_read_b128 v[158:161], v236 offset:3072
	ds_read_b128 v[130:133], v237
	ds_read_b128 v[134:137], v237 offset:1024
	ds_read_b128 v[138:141], v237 offset:2048
	ds_read_b128 v[142:145], v237 offset:3072
	s_mov_b64 s[6:7], s[8:9]
	s_add_u32 s8, s6, 0x100
	s_addc_u32 s9, s7, 0
	s_cmp_eq_u32 s64, 12
	s_cselect_b64 s[62:63], -1, 0
	s_and_b64 s[24:25], s[62:63], exec
	s_cselect_b32 s27, s11, s9
	s_cselect_b32 s26, s35, s8
	s_cselect_b32 s25, s1, s61
	s_cselect_b32 s24, s46, s53
	ds_read_b128 v[162:165], v238
	ds_read_b128 v[166:169], v238 offset:1024
	ds_read_b128 v[170:173], v238 offset:2048
	ds_read_b128 v[174:177], v238 offset:3072
	ds_read_b128 v[178:181], v238 offset:4096
	ds_read_b128 v[182:185], v238 offset:5120
	ds_read_b128 v[186:189], v238 offset:6144
	ds_read_b128 v[190:193], v238 offset:7168
	s_add_u32 s6, s6, 0x40080
	s_addc_u32 s7, s7, 0
	s_add_u32 m0, s28, 0xc000
	s_nop 0
	global_load_lds_dwordx4 v232, s[6:7]
	s_nop 0
	s_add_u32 m0, s28, 0xe000
	s_nop 0
	global_load_lds_dwordx4 v234, s[6:7]
	s_waitcnt vmcnt(8)
	s_waitcnt lgkmcnt(0)
	s_barrier
	v_mfma_f32_16x16x32_f16 v[118:121], v[146:149], v[162:165], v[118:121]
	s_setprio 1
	v_mfma_f32_16x16x32_f16 v[118:121], v[150:153], v[166:169], v[118:121]
	v_mfma_f32_16x16x32_f16 v[114:117], v[158:161], v[166:169], v[114:117]
	v_mfma_f32_16x16x32_f16 v[114:117], v[154:157], v[162:165], v[114:117]
	v_mfma_f32_16x16x32_f16 v[98:101], v[154:157], v[170:173], v[98:101]
	v_mfma_f32_16x16x32_f16 v[98:101], v[158:161], v[174:177], v[98:101]
	v_mfma_f32_16x16x32_f16 v[102:105], v[150:153], v[174:177], v[102:105]
	v_mfma_f32_16x16x32_f16 v[102:105], v[146:149], v[170:173], v[102:105]
	v_mfma_f32_16x16x32_f16 v[86:89], v[146:149], v[178:181], v[86:89]
	v_mfma_f32_16x16x32_f16 v[86:89], v[150:153], v[182:185], v[86:89]
	v_mfma_f32_16x16x32_f16 v[78:81], v[158:161], v[182:185], v[78:81]
	v_mfma_f32_16x16x32_f16 v[78:81], v[154:157], v[178:181], v[78:81]
	v_mfma_f32_16x16x32_f16 v[50:53], v[154:157], v[186:189], v[50:53]
	v_mfma_f32_16x16x32_f16 v[50:53], v[158:161], v[190:193], v[50:53]
	v_mfma_f32_16x16x32_f16 v[58:61], v[150:153], v[190:193], v[58:61]
	v_mfma_f32_16x16x32_f16 v[58:61], v[146:149], v[186:189], v[58:61]
	v_mfma_f32_16x16x32_f16 v[74:77], v[130:133], v[186:189], v[74:77]
	v_mfma_f32_16x16x32_f16 v[74:77], v[134:137], v[190:193], v[74:77]
	v_mfma_f32_16x16x32_f16 v[126:129], v[134:137], v[166:169], v[126:129]
	v_mfma_f32_16x16x32_f16 v[126:129], v[130:133], v[162:165], v[126:129]
	v_mfma_f32_16x16x32_f16 v[122:125], v[138:141], v[162:165], v[122:125]
	v_mfma_f32_16x16x32_f16 v[122:125], v[142:145], v[166:169], v[122:125]
	v_mfma_f32_16x16x32_f16 v[106:109], v[142:145], v[174:177], v[106:109]
	v_mfma_f32_16x16x32_f16 v[106:109], v[138:141], v[170:173], v[106:109]
	v_mfma_f32_16x16x32_f16 v[110:113], v[130:133], v[170:173], v[110:113]
	v_mfma_f32_16x16x32_f16 v[110:113], v[134:137], v[174:177], v[110:113]
	s_barrier
	v_mfma_f32_16x16x32_f16 v[94:97], v[134:137], v[182:185], v[94:97]
	v_mfma_f32_16x16x32_f16 v[94:97], v[130:133], v[178:181], v[94:97]
	v_mfma_f32_16x16x32_f16 v[90:93], v[138:141], v[178:181], v[90:93]
	v_mfma_f32_16x16x32_f16 v[90:93], v[142:145], v[182:185], v[90:93]
	v_mfma_f32_16x16x32_f16 v[66:69], v[142:145], v[190:193], v[66:69]
	v_mfma_f32_16x16x32_f16 v[66:69], v[138:141], v[186:189], v[66:69]
	s_setprio 0
	ds_read_b128 v[186:189], v238 offset:16384
	ds_read_b128 v[190:193], v238 offset:17408
	ds_read_b128 v[178:181], v238 offset:18432
	ds_read_b128 v[182:185], v238 offset:19456
	ds_read_b128 v[170:173], v238 offset:20480
	ds_read_b128 v[174:177], v238 offset:21504
	ds_read_b128 v[162:165], v238 offset:22528
	ds_read_b128 v[166:169], v238 offset:23552
	s_and_b64 s[6:7], s[4:5], s[62:63]
	s_mov_b64 s[62:63], -1
	s_and_b64 vcc, exec, s[6:7]
	s_cbranch_vccnz .LBB0_233
	s_add_u32 m0, s28, 0x10000
	s_nop 0
	global_load_lds_dwordx4 v233, s[24:25]
	s_nop 0
	s_add_u32 m0, s28, 0x12000
	s_nop 0
	global_load_lds_dwordx4 v235, s[24:25]
	s_add_u32 s62, s24, 0x40000
	s_addc_u32 s63, s25, 0
	s_add_u32 m0, s28, 0x14000
	s_nop 0
	global_load_lds_dwordx4 v233, s[62:63]
	s_nop 0
	s_add_u32 m0, s28, 0x16000
	s_nop 0
	global_load_lds_dwordx4 v235, s[62:63]
	s_mov_b64 s[62:63], 0
	s_add_u32 m0, s28, 0
	s_nop 0
	global_load_lds_dwordx4 v232, s[26:27]
	s_nop 0
	s_add_u32 m0, s28, 0x2000
	s_nop 0
	global_load_lds_dwordx4 v234, s[26:27]
	s_waitcnt vmcnt(8)

; #define PG8_STAGE(bufoff, gbase, voff) do { if constexpr (ABL & 1) break; glds16s<(bufoff)>((voff)[0], (const void*)(gbase), ldsbw); glds16s<(bufoff) + 8192>((voff)[1], (const void*)(gbase), ldsbw); } while (0)
; #define PG8_LDA(dst, b, h) do { if constexpr (ABL & 4) break; _Pragma("unroll") for (int m = 0; m < 4; ++m) _Pragma("unroll") for (int k = 0; k < 2; ++k) dst[m][k] = *(const LAS f16x8*)(lds + PG8_SA(b, h) + aoff + m * 2048 + k * 1024); } while (0)
; #define PG8_LDB(dst, b, h) do { if constexpr (ABL & 4) break; _Pragma("unroll") for (int n = 0; n < 2; ++n) _Pragma("unroll") for (int k = 0; k < 2; ++k) dst[n][k] = *(const LAS f16x8*)(lds + PG8_SB(b, h) + boff + n * 2048 + k * 1024); } while (0)
; #define PG8_MMA(ai, bj, At, Bt) do { if constexpr (ABL & 2) break; __builtin_amdgcn_s_setprio(1); _Pragma("unroll") for (int m = 0; m < 4; ++m) _Pragma("unroll") for (int n = 0; n < 2; ++n) _Pragma("unroll") for (int k = 0; k < 2; ++k) \
;         acc[ai][bj][m][n] = __builtin_amdgcn_mfma_f32_16x16x32_f16(Bt[n][k], At[m][k], acc[ai][bj][m][n], 0, 0, 0); __builtin_amdgcn_s_setprio(0); } while (0)
; #define PG8_BAR __builtin_amdgcn_s_barrier()
;     ...
;             if constexpr (SP2) {
;             PG8_LDB(B0, 0, 0); PG8_LDB(B1, 0, 1); PG8_SCHED; PG8_LDA(At, 0, 0); PG8_STAGE(PG8_SA(1, 1), a1 + hstep, voffA);
;             PG8_WAIT_V(8); PG8_WAIT_L(0); PG8_BAR; PG8_MMAF(0, 0, At, B0); PG8_MMAF(0, 1, At, B1); PG8_BAR; PG8_SCHED;
;             const bool fin = last && !has_next;
;             PG8_LDA(At, 0, 1); if (!fin) { PG8_STAGE(PG8_SB(0, 0), b2, voffB); PG8_STAGE(PG8_SB(0, 1), b2 + hstep, voffB); PG8_STAGE(PG8_SA(0, 0), a2, voffA); }
;             if (!fin) PG8_WAIT_V(8); else PG8_WAIT_V(2); PG8_WAIT_L(0); PG8_BAR; PG8_MMAF(1, 0, At, B0); PG8_MMAF(1, 1, At, B1); PG8_BAR; PG8_SCHED;
;             PG8_LDB(B0, 1, 0); PG8_LDB(B1, 1, 1); PG8_SCHED; PG8_LDA(At, 1, 0); if (!fin) PG8_STAGE(PG8_SA(0, 1), a2 + hstep, voffA);
;             if (!fin) PG8_WAIT_V(8); else PG8_WAIT_V(0); PG8_WAIT_L(0); PG8_BAR; PG8_MMA(0, 0, At, B0); PG8_MMA(0, 1, At, B1); PG8_BAR; PG8_SCHED;
;             PG8_LDA(At, 1, 1); if (!fin) { PG8_STAGE(PG8_SB(1, 0), b3, voffB); PG8_STAGE(PG8_SB(1, 1), b3 + hstep, voffB); PG8_STAGE(PG8_SA(1, 0), a3, voffA); }
;             if (!fin) PG8_WAIT_V(8); PG8_WAIT_L(0); PG8_BAR; PG8_MMA(1, 0, At, B0); PG8_MMA(1, 1, At, B1); PG8_BAR; PG8_SCHED;
.LBB0_235:
	s_waitcnt lgkmcnt(0)
	s_xor_b64 s[62:63], s[6:7], -1
	s_barrier
	v_mfma_f32_16x16x32_f16 v[54:57], v[146:149], v[186:189], v[54:57]
	s_setprio 1
	v_mfma_f32_16x16x32_f16 v[54:57], v[150:153], v[190:193], v[54:57]
	v_mfma_f32_16x16x32_f16 v[46:49], v[158:161], v[190:193], v[46:49]
	v_mfma_f32_16x16x32_f16 v[46:49], v[154:157], v[186:189], v[46:49]
	v_mfma_f32_16x16x32_f16 v[30:33], v[154:157], v[178:181], v[30:33]
	v_mfma_f32_16x16x32_f16 v[30:33], v[158:161], v[182:185], v[30:33]
	v_mfma_f32_16x16x32_f16 v[34:37], v[150:153], v[182:185], v[34:37]
	v_mfma_f32_16x16x32_f16 v[34:37], v[146:149], v[178:181], v[34:37]
	v_mfma_f32_16x16x32_f16 v[18:21], v[146:149], v[170:173], v[18:21]
	v_mfma_f32_16x16x32_f16 v[18:21], v[150:153], v[174:177], v[18:21]
	v_mfma_f32_16x16x32_f16 v[14:17], v[158:161], v[174:177], v[14:17]
	v_mfma_f32_16x16x32_f16 v[14:17], v[154:157], v[170:173], v[14:17]
	v_mfma_f32_16x16x32_f16 v[2:5], v[154:157], v[162:165], v[2:5]
	v_mfma_f32_16x16x32_f16 v[2:5], v[158:161], v[166:169], v[2:5]
	v_mfma_f32_16x16x32_f16 v[6:9], v[150:153], v[166:169], v[6:9]
	v_mfma_f32_16x16x32_f16 v[6:9], v[146:149], v[162:165], v[6:9]
	v_mfma_f32_16x16x32_f16 v[22:25], v[130:133], v[162:165], v[22:25]
	v_mfma_f32_16x16x32_f16 v[22:25], v[134:137], v[166:169], v[22:25]
	v_mfma_f32_16x16x32_f16 v[82:85], v[134:137], v[190:193], v[82:85]
	v_mfma_f32_16x16x32_f16 v[82:85], v[130:133], v[186:189], v[82:85]
	v_mfma_f32_16x16x32_f16 v[70:73], v[138:141], v[186:189], v[70:73]
	v_mfma_f32_16x16x32_f16 v[70:73], v[142:145], v[190:193], v[70:73]
	v_mfma_f32_16x16x32_f16 v[42:45], v[142:145], v[182:185], v[42:45]
	v_mfma_f32_16x16x32_f16 v[42:45], v[138:141], v[178:181], v[42:45]
	v_mfma_f32_16x16x32_f16 v[62:65], v[130:133], v[178:181], v[62:65]
	v_mfma_f32_16x16x32_f16 v[62:65], v[134:137], v[182:185], v[62:65]
	s_barrier
	v_mfma_f32_16x16x32_f16 v[38:41], v[134:137], v[174:177], v[38:41]
	v_mfma_f32_16x16x32_f16 v[38:41], v[130:133], v[170:173], v[38:41]
	v_mfma_f32_16x16x32_f16 v[26:29], v[138:141], v[170:173], v[26:29]
	v_mfma_f32_16x16x32_f16 v[26:29], v[142:145], v[174:177], v[26:29]
	v_mfma_f32_16x16x32_f16 v[10:13], v[142:145], v[166:169], v[10:13]
	v_mfma_f32_16x16x32_f16 v[10:13], v[138:141], v[162:165], v[10:13]
	s_setprio 0
	ds_read_b128 v[154:157], v239
	ds_read_b128 v[158:161], v239 offset:1024
	ds_read_b128 v[146:149], v239 offset:2048
	ds_read_b128 v[150:153], v239 offset:3072
	ds_read_b128 v[138:141], v240
	ds_read_b128 v[142:145], v240 offset:1024
	ds_read_b128 v[130:133], v240 offset:2048
	ds_read_b128 v[134:137], v240 offset:3072
	ds_read_b128 v[186:189], v238 offset:32768
	ds_read_b128 v[190:193], v238 offset:33792
	ds_read_b128 v[178:181], v238 offset:34816
	ds_read_b128 v[182:185], v238 offset:35840
	ds_read_b128 v[170:173], v238 offset:36864
	ds_read_b128 v[174:177], v238 offset:37888
	ds_read_b128 v[162:165], v238 offset:38912
	ds_read_b128 v[166:169], v238 offset:39936
	v_cndmask_b32_e64 v198, 0, 1, s[62:63]
	v_cmp_ne_u32_e64 s[6:7], 1, v198
	s_andn2_b64 vcc, exec, s[62:63]
	s_mov_b64 s[62:63], -1
	s_cbranch_vccnz .LBB0_237
	s_add_u32 s62, s26, 0x40000
	s_addc_u32 s63, s27, 0
	s_add_u32 m0, s28, 0x4000
	s_nop 0
	global_load_lds_dwordx4 v232, s[62:63]
	s_nop 0
	s_add_u32 m0, s28, 0x6000
	s_nop 0
	global_load_lds_dwordx4 v234, s[62:63]
	s_waitcnt vmcnt(8)
	s_mov_b64 s[62:63], 0

; #define PG8_STAGE(bufoff, gbase, voff) do { if constexpr (ABL & 1) break; glds16s<(bufoff)>((voff)[0], (const void*)(gbase), ldsbw); glds16s<(bufoff) + 8192>((voff)[1], (const void*)(gbase), ldsbw); } while (0)
; #define PG8_LDA(dst, b, h) do { if constexpr (ABL & 4) break; _Pragma("unroll") for (int m = 0; m < 4; ++m) _Pragma("unroll") for (int k = 0; k < 2; ++k) dst[m][k] = *(const LAS f16x8*)(lds + PG8_SA(b, h) + aoff + m * 2048 + k * 1024); } while (0)
; #define PG8_MMA(ai, bj, At, Bt) do { if constexpr (ABL & 2) break; __builtin_amdgcn_s_setprio(1); _Pragma("unroll") for (int m = 0; m < 4; ++m) _Pragma("unroll") for (int n = 0; n < 2; ++n) _Pragma("unroll") for (int k = 0; k < 2; ++k) \
;         acc[ai][bj][m][n] = __builtin_amdgcn_mfma_f32_16x16x32_f16(Bt[n][k], At[m][k], acc[ai][bj][m][n], 0, 0, 0); __builtin_amdgcn_s_setprio(0); } while (0)
; #define PG8_WAIT_V(n) asm volatile("s_waitcnt vmcnt(" #n ")" ::: "memory")
; #define PG8_WAIT_L(n) asm volatile("s_waitcnt lgkmcnt(" #n ")" ::: "memory")
; #define PG8_BAR __builtin_amdgcn_s_barrier()
; #define PG8_SCHED __builtin_amdgcn_sched_barrier(0)
;     ...
;             if (!fin) PG8_WAIT_V(8); else PG8_WAIT_V(0); PG8_WAIT_L(0); PG8_BAR; PG8_MMA(0, 0, At, B0); PG8_MMA(0, 1, At, B1); PG8_BAR; PG8_SCHED;
;             PG8_LDA(At, 1, 1); if (!fin) { PG8_STAGE(PG8_SB(1, 0), b3, voffB); PG8_STAGE(PG8_SB(1, 1), b3 + hstep, voffB); PG8_STAGE(PG8_SA(1, 0), a3, voffA); }
.LBB0_239:
	s_waitcnt lgkmcnt(0)
	s_barrier
	v_mfma_f32_16x16x32_f16 v[118:121], v[154:157], v[186:189], v[118:121]
	s_setprio 1
	v_mfma_f32_16x16x32_f16 v[118:121], v[158:161], v[190:193], v[118:121]
	v_mfma_f32_16x16x32_f16 v[114:117], v[150:153], v[190:193], v[114:117]
	v_mfma_f32_16x16x32_f16 v[114:117], v[146:149], v[186:189], v[114:117]
	v_mfma_f32_16x16x32_f16 v[98:101], v[146:149], v[178:181], v[98:101]
	v_mfma_f32_16x16x32_f16 v[98:101], v[150:153], v[182:185], v[98:101]
	v_mfma_f32_16x16x32_f16 v[102:105], v[158:161], v[182:185], v[102:105]
	v_mfma_f32_16x16x32_f16 v[102:105], v[154:157], v[178:181], v[102:105]
	v_mfma_f32_16x16x32_f16 v[86:89], v[154:157], v[170:173], v[86:89]
	v_mfma_f32_16x16x32_f16 v[86:89], v[158:161], v[174:177], v[86:89]
	v_mfma_f32_16x16x32_f16 v[78:81], v[150:153], v[174:177], v[78:81]
	v_mfma_f32_16x16x32_f16 v[78:81], v[146:149], v[170:173], v[78:81]
	v_mfma_f32_16x16x32_f16 v[50:53], v[146:149], v[162:165], v[50:53]
	v_mfma_f32_16x16x32_f16 v[50:53], v[150:153], v[166:169], v[50:53]
	v_mfma_f32_16x16x32_f16 v[58:61], v[158:161], v[166:169], v[58:61]
	v_mfma_f32_16x16x32_f16 v[58:61], v[154:157], v[162:165], v[58:61]
	v_mfma_f32_16x16x32_f16 v[74:77], v[138:141], v[162:165], v[74:77]
	v_mfma_f32_16x16x32_f16 v[74:77], v[142:145], v[166:169], v[74:77]
	v_mfma_f32_16x16x32_f16 v[126:129], v[142:145], v[190:193], v[126:129]
	v_mfma_f32_16x16x32_f16 v[126:129], v[138:141], v[186:189], v[126:129]
	v_mfma_f32_16x16x32_f16 v[122:125], v[130:133], v[186:189], v[122:125]
	v_mfma_f32_16x16x32_f16 v[122:125], v[134:137], v[190:193], v[122:125]
	v_mfma_f32_16x16x32_f16 v[106:109], v[134:137], v[182:185], v[106:109]
	v_mfma_f32_16x16x32_f16 v[106:109], v[130:133], v[178:181], v[106:109]
	v_mfma_f32_16x16x32_f16 v[110:113], v[138:141], v[178:181], v[110:113]
	v_mfma_f32_16x16x32_f16 v[110:113], v[142:145], v[182:185], v[110:113]
	s_barrier
	v_mfma_f32_16x16x32_f16 v[94:97], v[142:145], v[174:177], v[94:97]
	v_mfma_f32_16x16x32_f16 v[94:97], v[138:141], v[170:173], v[94:97]
	v_mfma_f32_16x16x32_f16 v[90:93], v[130:133], v[170:173], v[90:93]
	v_mfma_f32_16x16x32_f16 v[90:93], v[134:137], v[174:177], v[90:93]
	v_mfma_f32_16x16x32_f16 v[66:69], v[134:137], v[166:169], v[66:69]
	v_mfma_f32_16x16x32_f16 v[66:69], v[130:133], v[162:165], v[66:69]
	s_setprio 0
	ds_read_b128 v[186:189], v238 offset:49152
	ds_read_b128 v[190:193], v238 offset:50176
	ds_read_b128 v[178:181], v238 offset:51200
	ds_read_b128 v[182:185], v238 offset:52224
	ds_read_b128 v[170:173], v238 offset:53248
	ds_read_b128 v[174:177], v238 offset:54272
	ds_read_b128 v[162:165], v238 offset:55296
	ds_read_b128 v[166:169], v238 offset:56320
	s_and_b64 vcc, exec, s[6:7]
	s_cbranch_vccnz .LBB0_230
	s_add_u32 s6, s26, 0x80
	s_addc_u32 s7, s27, 0
	s_add_u32 s26, s24, 0x80
	s_addc_u32 s27, s25, 0
	s_add_u32 m0, s28, 0x18000
	s_nop 0
	global_load_lds_dwordx4 v233, s[26:27]
	s_nop 0
	s_add_u32 m0, s28, 0x1a000
	s_nop 0
	global_load_lds_dwordx4 v235, s[26:27]
	s_add_u32 s24, s24, 0x40080
	s_addc_u32 s25, s25, 0
	s_add_u32 m0, s28, 0x1c000
	s_nop 0
	global_load_lds_dwordx4 v233, s[24:25]
	s_nop 0
	s_add_u32 m0, s28, 0x1e000
	s_nop 0
	global_load_lds_dwordx4 v235, s[24:25]
	s_nop 0
	s_add_u32 m0, s28, 0x8000
	s_nop 0
	global_load_lds_dwordx4 v232, s[6:7]
	s_nop 0
	s_add_u32 m0, s28, 0xa000
	s_nop 0
	global_load_lds_dwordx4 v234, s[6:7]
	s_waitcnt vmcnt(8)
	s_branch .LBB0_230

; #define PG8_STAGE(bufoff, gbase, voff) do { if constexpr (ABL & 1) break; glds16s<(bufoff)>((voff)[0], (const void*)(gbase), ldsbw); glds16s<(bufoff) + 8192>((voff)[1], (const void*)(gbase), ldsbw); } while (0)
; #define PG8_LDA(dst, b, h) do { if constexpr (ABL & 4) break; _Pragma("unroll") for (int m = 0; m < 4; ++m) _Pragma("unroll") for (int k = 0; k < 2; ++k) dst[m][k] = *(const LAS f16x8*)(lds + PG8_SA(b, h) + aoff + m * 2048 + k * 1024); } while (0)
; #define PG8_LDB(dst, b, h) do { if constexpr (ABL & 4) break; _Pragma("unroll") for (int n = 0; n < 2; ++n) _Pragma("unroll") for (int k = 0; k < 2; ++k) dst[n][k] = *(const LAS f16x8*)(lds + PG8_SB(b, h) + boff + n * 2048 + k * 1024); } while (0)
; #define PG8_MMAF(ai, bj, At, Bt) do { if (t == 0) PG8_MMA0(ai, bj, At, Bt); else PG8_MMA(ai, bj, At, Bt); } while (0)
; #define PG8_WAIT_V(n) asm volatile("s_waitcnt vmcnt(" #n ")" ::: "memory")
; #define PG8_WAIT_L(n) asm volatile("s_waitcnt lgkmcnt(" #n ")" ::: "memory")
; #define PG8_BAR __builtin_amdgcn_s_barrier()
; #define PG8_SCHED __builtin_amdgcn_sched_barrier(0)
;     ...
;         const char* nA = has_next ? (const char*)g.A + (size_t)nxt.pm * tstep : cA; const char* nB = has_next ? (const char*)g.Bt + (size_t)nxt.pn * tstep : cB;
;         for (int t = 0; t < nt; t += 2) {
;             const bool last = (t == nt - 2);
;             const char* a1 = cA + (size_t)(t + 1) * kstep;
;             const char* a2 = last ? nA : cA + (size_t)(t + 2) * kstep; const char* b2 = last ? nB : cB + (size_t)(t + 2) * kstep;
;             const char* a3 = a2 + kstep; const char* b3 = b2 + kstep;
;             if (last && has_next) S.a_ready(nxt);
;             if constexpr (SP2) {
;             PG8_LDB(B0, 0, 0); PG8_LDB(B1, 0, 1); PG8_SCHED; PG8_LDA(At, 0, 0); PG8_STAGE(PG8_SA(1, 1), a1 + hstep, voffA);
;             PG8_WAIT_V(8); PG8_WAIT_L(0); PG8_BAR; PG8_MMAF(0, 0, At, B0); PG8_MMAF(0, 1, At, B1); PG8_BAR; PG8_SCHED;
;             const bool fin = last && !has_next;
;             PG8_LDA(At, 0, 1); if (!fin) { PG8_STAGE(PG8_SB(0, 0), b2, voffB); PG8_STAGE(PG8_SB(0, 1), b2 + hstep, voffB); PG8_STAGE(PG8_SA(0, 0), a2, voffA); }
;             if (!fin) PG8_WAIT_V(8); else PG8_WAIT_V(2); PG8_WAIT_L(0); PG8_BAR; PG8_MMAF(1, 0, At, B0); PG8_MMAF(1, 1, At, B1); PG8_BAR; PG8_SCHED;
.LBB0_748:
	s_ashr_i32 s47, s46, 31
	s_lshl_b64 s[8:9], s[46:47], 19
	s_add_u32 s48, s12, s8
	s_addc_u32 s49, s13, s9
	s_and_b64 s[8:9], exec, s[4:5]
	s_waitcnt lgkmcnt(0)
	ds_read_b128 v[2:5], v222
	ds_read_b128 v[6:9], v222 offset:1024
	ds_read_b128 v[10:13], v222 offset:2048
	ds_read_b128 v[14:17], v222 offset:3072
	ds_read_b128 v[18:21], v223
	ds_read_b128 v[22:25], v223 offset:1024
	ds_read_b128 v[26:29], v223 offset:2048
	ds_read_b128 v[30:33], v223 offset:3072
	s_cselect_b32 s47, s31, s49
	s_cselect_b32 s55, s30, s48
	s_ashr_i32 s45, s44, 31
	s_lshl_b64 s[8:9], s[44:45], 19
	s_add_u32 s50, s90, s8
	s_addc_u32 s51, s91, s9
	s_and_b64 s[8:9], exec, s[4:5]
	s_cselect_b32 s45, s7, s51
	s_cselect_b32 s58, s6, s50
	s_add_u32 s56, s30, 0x100
	s_addc_u32 s57, s31, 0
	s_add_u32 s26, s6, 0x100
	s_addc_u32 s27, s7, 0
	s_add_u32 s8, s30, 0x180
	s_addc_u32 s9, s31, 0
	ds_read_b128 v[34:37], v224
	ds_read_b128 v[38:41], v224 offset:1024
	ds_read_b128 v[42:45], v224 offset:2048
	ds_read_b128 v[46:49], v224 offset:3072
	ds_read_b128 v[50:53], v224 offset:4096
	ds_read_b128 v[54:57], v224 offset:5120
	ds_read_b128 v[58:61], v224 offset:6144
	ds_read_b128 v[62:65], v224 offset:7168
	s_add_u32 s24, s6, 0x180
	s_addc_u32 s25, s7, 0
	s_add_u32 s60, s30, 0x40080
	s_addc_u32 s61, s31, 0
	s_add_u32 m0, s14, 0xc000
	s_nop 0
	global_load_lds_dwordx4 v1, s[60:61]
	s_nop 0
	s_add_u32 m0, s14, 0xe000
	s_nop 0
	global_load_lds_dwordx4 v213, s[60:61]
	s_waitcnt vmcnt(8)
	s_waitcnt lgkmcnt(0)
	s_barrier
	v_mfma_f32_16x16x32_f16 v[66:69], v[2:5], v[34:37], 0
	s_setprio 1
	v_mfma_f32_16x16x32_f16 v[66:69], v[6:9], v[38:41], v[66:69]
	v_mfma_f32_16x16x32_f16 v[70:73], v[10:13], v[34:37], 0
	v_mfma_f32_16x16x32_f16 v[70:73], v[14:17], v[38:41], v[70:73]
	v_mfma_f32_16x16x32_f16 v[78:81], v[10:13], v[42:45], 0
	v_mfma_f32_16x16x32_f16 v[78:81], v[14:17], v[46:49], v[78:81]
	v_mfma_f32_16x16x32_f16 v[82:85], v[2:5], v[50:53], 0
	v_mfma_f32_16x16x32_f16 v[82:85], v[6:9], v[54:57], v[82:85]
	v_mfma_f32_16x16x32_f16 v[90:93], v[2:5], v[58:61], 0
	v_mfma_f32_16x16x32_f16 v[90:93], v[6:9], v[62:65], v[90:93]
	v_mfma_f32_16x16x32_f16 v[94:97], v[10:13], v[58:61], 0
	v_mfma_f32_16x16x32_f16 v[94:97], v[14:17], v[62:65], v[94:97]
	v_mfma_f32_16x16x32_f16 v[74:77], v[2:5], v[42:45], 0
	v_mfma_f32_16x16x32_f16 v[74:77], v[6:9], v[46:49], v[74:77]
	v_mfma_f32_16x16x32_f16 v[86:89], v[10:13], v[50:53], 0
	v_mfma_f32_16x16x32_f16 v[86:89], v[14:17], v[54:57], v[86:89]
	v_mfma_f32_16x16x32_f16 v[98:101], v[18:21], v[34:37], 0
	v_mfma_f32_16x16x32_f16 v[98:101], v[22:25], v[38:41], v[98:101]
	v_mfma_f32_16x16x32_f16 v[34:37], v[26:29], v[34:37], 0
	v_mfma_f32_16x16x32_f16 v[34:37], v[30:33], v[38:41], v[34:37]
	v_mfma_f32_16x16x32_f16 v[38:41], v[18:21], v[42:45], 0
	v_mfma_f32_16x16x32_f16 v[38:41], v[22:25], v[46:49], v[38:41]
	v_mfma_f32_16x16x32_f16 v[42:45], v[26:29], v[42:45], 0
	v_mfma_f32_16x16x32_f16 v[42:45], v[30:33], v[46:49], v[42:45]
	v_mfma_f32_16x16x32_f16 v[46:49], v[18:21], v[50:53], 0
	v_mfma_f32_16x16x32_f16 v[46:49], v[22:25], v[54:57], v[46:49]
	s_barrier
	v_mfma_f32_16x16x32_f16 v[50:53], v[26:29], v[50:53], 0
	v_mfma_f32_16x16x32_f16 v[50:53], v[30:33], v[54:57], v[50:53]
	v_mfma_f32_16x16x32_f16 v[54:57], v[18:21], v[58:61], 0
	v_mfma_f32_16x16x32_f16 v[54:57], v[22:25], v[62:65], v[54:57]
	v_mfma_f32_16x16x32_f16 v[58:61], v[26:29], v[58:61], 0
	v_mfma_f32_16x16x32_f16 v[58:61], v[30:33], v[62:65], v[58:61]
	s_setprio 0
	ds_read_b128 v[62:65], v224 offset:16384
	ds_read_b128 v[102:105], v224 offset:17408
	ds_read_b128 v[106:109], v224 offset:18432
	ds_read_b128 v[110:113], v224 offset:19456
	ds_read_b128 v[114:117], v224 offset:20480
	ds_read_b128 v[118:121], v224 offset:21504
	ds_read_b128 v[122:125], v224 offset:22528
	ds_read_b128 v[126:129], v224 offset:23552
	s_add_u32 m0, s14, 0x10000
	s_nop 0
	global_load_lds_dwordx4 v209, s[26:27]
	s_nop 0
	s_add_u32 m0, s14, 0x12000
	s_nop 0
	global_load_lds_dwordx4 v219, s[26:27]
	s_add_u32 s26, s6, 0x40100
	s_addc_u32 s27, s7, 0
	s_add_u32 m0, s14, 0x14000
	s_nop 0
	global_load_lds_dwordx4 v209, s[26:27]
	s_nop 0
	s_add_u32 m0, s14, 0x16000
	s_nop 0
	global_load_lds_dwordx4 v219, s[26:27]
	s_nop 0
	s_add_u32 m0, s14, 0
	s_nop 0
	global_load_lds_dwordx4 v1, s[56:57]
	s_nop 0
	s_add_u32 m0, s14, 0x2000
	s_nop 0
	global_load_lds_dwordx4 v213, s[56:57]
	s_waitcnt vmcnt(8)
	s_waitcnt lgkmcnt(0)
	s_barrier
	v_mfma_f32_16x16x32_f16 v[130:133], v[2:5], v[62:65], 0
	s_setprio 1
	v_mfma_f32_16x16x32_f16 v[134:137], v[6:9], v[102:105], v[130:133]
	v_mfma_f32_16x16x32_f16 v[130:133], v[10:13], v[62:65], 0
	v_mfma_f32_16x16x32_f16 v[146:149], v[14:17], v[102:105], v[130:133]
	v_mfma_f32_16x16x32_f16 v[130:133], v[2:5], v[106:109], 0
	v_mfma_f32_16x16x32_f16 v[158:161], v[6:9], v[110:113], v[130:133]
	v_mfma_f32_16x16x32_f16 v[130:133], v[10:13], v[106:109], 0
	v_mfma_f32_16x16x32_f16 v[162:165], v[14:17], v[110:113], v[130:133]
	v_mfma_f32_16x16x32_f16 v[130:133], v[2:5], v[114:117], 0
	v_mfma_f32_16x16x32_f16 v[166:169], v[6:9], v[118:121], v[130:133]
	v_mfma_f32_16x16x32_f16 v[2:5], v[2:5], v[122:125], 0
	v_mfma_f32_16x16x32_f16 v[2:5], v[6:9], v[126:129], v[2:5]
	v_mfma_f32_16x16x32_f16 v[6:9], v[10:13], v[122:125], 0
	v_mfma_f32_16x16x32_f16 v[6:9], v[14:17], v[126:129], v[6:9]
	v_mfma_f32_16x16x32_f16 v[130:133], v[10:13], v[114:117], 0
	v_mfma_f32_16x16x32_f16 v[170:173], v[14:17], v[118:121], v[130:133]
	v_mfma_f32_16x16x32_f16 v[10:13], v[18:21], v[62:65], 0
	v_mfma_f32_16x16x32_f16 v[174:177], v[22:25], v[102:105], v[10:13]
	v_mfma_f32_16x16x32_f16 v[10:13], v[26:29], v[62:65], 0
	v_mfma_f32_16x16x32_f16 v[178:181], v[30:33], v[102:105], v[10:13]
	v_mfma_f32_16x16x32_f16 v[10:13], v[18:21], v[106:109], 0
	v_mfma_f32_16x16x32_f16 v[182:185], v[22:25], v[110:113], v[10:13]
	v_mfma_f32_16x16x32_f16 v[10:13], v[26:29], v[106:109], 0
	v_mfma_f32_16x16x32_f16 v[110:113], v[30:33], v[110:113], v[10:13]
	v_mfma_f32_16x16x32_f16 v[10:13], v[18:21], v[114:117], 0
	v_mfma_f32_16x16x32_f16 v[186:189], v[22:25], v[118:121], v[10:13]
	s_barrier
; #define PG8_STAGE(bufoff, gbase, voff) do { if constexpr (ABL & 1) break; glds16s<(bufoff)>((voff)[0], (const void*)(gbase), ldsbw); glds16s<(bufoff) + 8192>((voff)[1], (const void*)(gbase), ldsbw); } while (0)
; #define PG8_LDA(dst, b, h) do { if constexpr (ABL & 4) break; _Pragma("unroll") for (int m = 0; m < 4; ++m) _Pragma("unroll") for (int k = 0; k < 2; ++k) dst[m][k] = *(const LAS f16x8*)(lds + PG8_SA(b, h) + aoff + m * 2048 + k * 1024); } while (0)
; #define PG8_LDB(dst, b, h) do { if constexpr (ABL & 4) break; _Pragma("unroll") for (int n = 0; n < 2; ++n) _Pragma("unroll") for (int k = 0; k < 2; ++k) dst[n][k] = *(const LAS f16x8*)(lds + PG8_SB(b, h) + boff + n * 2048 + k * 1024); } while (0)
; #define PG8_MMA(ai, bj, At, Bt) do { if constexpr (ABL & 2) break; __builtin_amdgcn_s_setprio(1); _Pragma("unroll") for (int m = 0; m < 4; ++m) _Pragma("unroll") for (int n = 0; n < 2; ++n) _Pragma("unroll") for (int k = 0; k < 2; ++k) \
;         acc[ai][bj][m][n] = __builtin_amdgcn_mfma_f32_16x16x32_f16(Bt[n][k], At[m][k], acc[ai][bj][m][n], 0, 0, 0); __builtin_amdgcn_s_setprio(0); } while (0)
; #define PG8_MMAF(ai, bj, At, Bt) do { if (t == 0) PG8_MMA0(ai, bj, At, Bt); else PG8_MMA(ai, bj, At, Bt); } while (0)
; #define PG8_WAIT_V(n) asm volatile("s_waitcnt vmcnt(" #n ")" ::: "memory")
; #define PG8_WAIT_L(n) asm volatile("s_waitcnt lgkmcnt(" #n ")" ::: "memory")
; #define PG8_BAR __builtin_amdgcn_s_barrier()
; #define PG8_SCHED __builtin_amdgcn_sched_barrier(0)
;     ...
;             if (!fin) PG8_WAIT_V(8); else PG8_WAIT_V(2); PG8_WAIT_L(0); PG8_BAR; PG8_MMAF(1, 0, At, B0); PG8_MMAF(1, 1, At, B1); PG8_BAR; PG8_SCHED;
;             PG8_LDB(B0, 1, 0); PG8_LDB(B1, 1, 1); PG8_SCHED; PG8_LDA(At, 1, 0); if (!fin) PG8_STAGE(PG8_SA(0, 1), a2 + hstep, voffA);
;             if (!fin) PG8_WAIT_V(8); else PG8_WAIT_V(0); PG8_WAIT_L(0); PG8_BAR; PG8_MMA(0, 0, At, B0); PG8_MMA(0, 1, At, B1); PG8_BAR; PG8_SCHED;
;             PG8_LDA(At, 1, 1); if (!fin) { PG8_STAGE(PG8_SB(1, 0), b3, voffB); PG8_STAGE(PG8_SB(1, 1), b3 + hstep, voffB); PG8_STAGE(PG8_SA(1, 0), a3, voffA); }
;             if (!fin) PG8_WAIT_V(8); PG8_WAIT_L(0); PG8_BAR; PG8_MMA(1, 0, At, B0); PG8_MMA(1, 1, At, B1); PG8_BAR; PG8_SCHED;
	v_mfma_f32_16x16x32_f16 v[10:13], v[26:29], v[114:117], 0
	v_mfma_f32_16x16x32_f16 v[190:193], v[30:33], v[118:121], v[10:13]
	v_mfma_f32_16x16x32_f16 v[10:13], v[18:21], v[122:125], 0
	v_mfma_f32_16x16x32_f16 v[194:197], v[22:25], v[126:129], v[10:13]
	v_mfma_f32_16x16x32_f16 v[10:13], v[26:29], v[122:125], 0
	v_mfma_f32_16x16x32_f16 v[122:125], v[30:33], v[126:129], v[10:13]
	s_setprio 0
	s_nop 4
	ds_read_b128 v[10:13], v225
	ds_read_b128 v[14:17], v225 offset:1024
	ds_read_b128 v[18:21], v225 offset:2048
	ds_read_b128 v[22:25], v225 offset:3072
	ds_read_b128 v[198:201], v226
	ds_read_b128 v[214:217], v226 offset:1024
	ds_read_b128 v[228:231], v226 offset:2048
	ds_read_b128 v[232:235], v226 offset:3072
	ds_read_b128 v[26:29], v224 offset:32768
	ds_read_b128 v[30:33], v224 offset:33792
	ds_read_b128 v[62:65], v224 offset:34816
	ds_read_b128 v[114:117], v224 offset:35840
	ds_read_b128 v[236:239], v224 offset:36864
	ds_read_b128 v[240:243], v224 offset:37888
	ds_read_b128 v[244:247], v224 offset:38912
	ds_read_b128 v[248:251], v224 offset:39936
	s_add_u32 s26, s30, 0x40100
	s_addc_u32 s27, s31, 0
	s_add_u32 m0, s14, 0x4000
	s_nop 0
	global_load_lds_dwordx4 v1, s[26:27]
	s_nop 0
	s_add_u32 m0, s14, 0x6000
	s_nop 0
	global_load_lds_dwordx4 v213, s[26:27]
	s_waitcnt vmcnt(8)
	s_waitcnt lgkmcnt(0)
	s_barrier
	v_mfma_f32_16x16x32_f16 v[66:69], v[10:13], v[26:29], v[66:69]
	s_setprio 1
	v_mfma_f32_16x16x32_f16 v[154:157], v[14:17], v[30:33], v[66:69]
	v_mfma_f32_16x16x32_f16 v[66:69], v[18:21], v[26:29], v[70:73]
	v_mfma_f32_16x16x32_f16 v[150:153], v[22:25], v[30:33], v[66:69]
	v_mfma_f32_16x16x32_f16 v[66:69], v[10:13], v[62:65], v[74:77]
	v_mfma_f32_16x16x32_f16 v[130:133], v[14:17], v[114:117], v[66:69]
	v_mfma_f32_16x16x32_f16 v[66:69], v[18:21], v[62:65], v[78:81]
	v_mfma_f32_16x16x32_f16 v[126:129], v[22:25], v[114:117], v[66:69]
	v_mfma_f32_16x16x32_f16 v[66:69], v[10:13], v[236:239], v[82:85]
	v_mfma_f32_16x16x32_f16 v[106:109], v[14:17], v[240:243], v[66:69]
	v_mfma_f32_16x16x32_f16 v[66:69], v[18:21], v[236:239], v[86:89]
	v_mfma_f32_16x16x32_f16 v[102:105], v[22:25], v[240:243], v[66:69]
	v_mfma_f32_16x16x32_f16 v[66:69], v[10:13], v[244:247], v[90:93]
	v_mfma_f32_16x16x32_f16 v[82:85], v[14:17], v[248:251], v[66:69]
	v_mfma_f32_16x16x32_f16 v[66:69], v[18:21], v[244:247], v[94:97]
	v_mfma_f32_16x16x32_f16 v[78:81], v[22:25], v[248:251], v[66:69]
	v_mfma_f32_16x16x32_f16 v[66:69], v[198:201], v[26:29], v[98:101]
	v_mfma_f32_16x16x32_f16 v[142:145], v[214:217], v[30:33], v[66:69]
	v_mfma_f32_16x16x32_f16 v[26:29], v[228:231], v[26:29], v[34:37]
	v_mfma_f32_16x16x32_f16 v[138:141], v[232:235], v[30:33], v[26:29]
	v_mfma_f32_16x16x32_f16 v[26:29], v[198:201], v[62:65], v[38:41]
	v_mfma_f32_16x16x32_f16 v[118:121], v[214:217], v[114:117], v[26:29]
	v_mfma_f32_16x16x32_f16 v[26:29], v[228:231], v[62:65], v[42:45]
	v_mfma_f32_16x16x32_f16 v[114:117], v[232:235], v[114:117], v[26:29]
	v_mfma_f32_16x16x32_f16 v[26:29], v[198:201], v[236:239], v[46:49]
	v_mfma_f32_16x16x32_f16 v[94:97], v[214:217], v[240:243], v[26:29]
	s_barrier
	v_mfma_f32_16x16x32_f16 v[26:29], v[228:231], v[236:239], v[50:53]
	v_mfma_f32_16x16x32_f16 v[90:93], v[232:235], v[240:243], v[26:29]
	v_mfma_f32_16x16x32_f16 v[26:29], v[198:201], v[244:247], v[54:57]
	v_mfma_f32_16x16x32_f16 v[70:73], v[214:217], v[248:251], v[26:29]
	v_mfma_f32_16x16x32_f16 v[26:29], v[228:231], v[244:247], v[58:61]
	v_mfma_f32_16x16x32_f16 v[66:69], v[232:235], v[248:251], v[26:29]
	s_setprio 0
	ds_read_b128 v[34:37], v224 offset:49152
	ds_read_b128 v[38:41], v224 offset:50176
	ds_read_b128 v[74:77], v224 offset:51200
	ds_read_b128 v[86:89], v224 offset:52224
	ds_read_b128 v[98:101], v224 offset:53248
	ds_read_b128 v[236:239], v224 offset:54272
	ds_read_b128 v[240:243], v224 offset:55296
	ds_read_b128 v[244:247], v224 offset:56320
	s_add_u32 m0, s14, 0x18000
	s_nop 0
	global_load_lds_dwordx4 v209, s[24:25]
	s_nop 0
	s_add_u32 m0, s14, 0x1a000
	s_nop 0
	global_load_lds_dwordx4 v219, s[24:25]
	s_add_u32 s24, s6, 0x40180
	s_addc_u32 s25, s7, 0
	s_add_u32 m0, s14, 0x1c000
	s_nop 0
	global_load_lds_dwordx4 v209, s[24:25]
	s_nop 0
	s_add_u32 m0, s14, 0x1e000
	s_nop 0
	global_load_lds_dwordx4 v219, s[24:25]
	s_nop 0
	s_add_u32 m0, s14, 0x8000
	s_nop 0
	global_load_lds_dwordx4 v1, s[8:9]
	s_nop 0
	s_add_u32 m0, s14, 0xa000
	s_nop 0
	global_load_lds_dwordx4 v213, s[8:9]
	s_waitcnt vmcnt(8)
	s_waitcnt lgkmcnt(0)
	s_barrier
	v_mfma_f32_16x16x32_f16 v[26:29], v[10:13], v[34:37], v[134:137]
	s_setprio 1
	v_mfma_f32_16x16x32_f16 v[62:65], v[14:17], v[38:41], v[26:29]
	v_mfma_f32_16x16x32_f16 v[26:29], v[22:25], v[38:41], v[146:149]
	v_mfma_f32_16x16x32_f16 v[58:61], v[18:21], v[34:37], v[26:29]
	v_mfma_f32_16x16x32_f16 v[26:29], v[10:13], v[74:77], v[158:161]
	v_mfma_f32_16x16x32_f16 v[46:49], v[14:17], v[86:89], v[26:29]
	v_mfma_f32_16x16x32_f16 v[26:29], v[22:25], v[86:89], v[162:165]
	v_mfma_f32_16x16x32_f16 v[42:45], v[18:21], v[74:77], v[26:29]
	v_mfma_f32_16x16x32_f16 v[26:29], v[10:13], v[98:101], v[166:169]
	v_mfma_f32_16x16x32_f16 v[30:33], v[14:17], v[236:239], v[26:29]
	v_mfma_f32_16x16x32_f16 v[2:5], v[14:17], v[244:247], v[2:5]
	v_mfma_f32_16x16x32_f16 v[14:17], v[10:13], v[240:243], v[2:5]
	v_mfma_f32_16x16x32_f16 v[2:5], v[18:21], v[240:243], v[6:9]
	v_mfma_f32_16x16x32_f16 v[10:13], v[22:25], v[244:247], v[2:5]
	v_mfma_f32_16x16x32_f16 v[26:29], v[22:25], v[236:239], v[170:173]
	v_mfma_f32_16x16x32_f16 v[26:29], v[18:21], v[98:101], v[26:29]
	v_mfma_f32_16x16x32_f16 v[2:5], v[198:201], v[34:37], v[174:177]
	v_mfma_f32_16x16x32_f16 v[54:57], v[214:217], v[38:41], v[2:5]
	v_mfma_f32_16x16x32_f16 v[2:5], v[232:235], v[38:41], v[178:181]
	v_mfma_f32_16x16x32_f16 v[50:53], v[228:231], v[34:37], v[2:5]
	v_mfma_f32_16x16x32_f16 v[2:5], v[198:201], v[74:77], v[182:185]
	v_mfma_f32_16x16x32_f16 v[38:41], v[214:217], v[86:89], v[2:5]
	v_mfma_f32_16x16x32_f16 v[2:5], v[232:235], v[86:89], v[110:113]
	v_mfma_f32_16x16x32_f16 v[34:37], v[228:231], v[74:77], v[2:5]
	v_mfma_f32_16x16x32_f16 v[2:5], v[198:201], v[98:101], v[186:189]
	v_mfma_f32_16x16x32_f16 v[22:25], v[214:217], v[236:239], v[2:5]
	s_barrier
	v_mfma_f32_16x16x32_f16 v[2:5], v[232:235], v[236:239], v[190:193]
	v_mfma_f32_16x16x32_f16 v[18:21], v[228:231], v[98:101], v[2:5]
	v_mfma_f32_16x16x32_f16 v[2:5], v[198:201], v[240:243], v[194:197]
	v_mfma_f32_16x16x32_f16 v[6:9], v[214:217], v[244:247], v[2:5]
	v_mfma_f32_16x16x32_f16 v[2:5], v[232:235], v[244:247], v[122:125]
	v_mfma_f32_16x16x32_f16 v[2:5], v[228:231], v[240:243], v[2:5]
	s_setprio 0
	s_add_u32 s30, s6, 0x200
	s_addc_u32 s31, s7, 0
	s_mov_b32 s59, 0
	s_branch .LBB0_750
; #define PG8_STAGE(bufoff, gbase, voff) do { if constexpr (ABL & 1) break; glds16s<(bufoff)>((voff)[0], (const void*)(gbase), ldsbw); glds16s<(bufoff) + 8192>((voff)[1], (const void*)(gbase), ldsbw); } while (0)
; #define PG8_LDA(dst, b, h) do { if constexpr (ABL & 4) break; _Pragma("unroll") for (int m = 0; m < 4; ++m) _Pragma("unroll") for (int k = 0; k < 2; ++k) dst[m][k] = *(const LAS f16x8*)(lds + PG8_SA(b, h) + aoff + m * 2048 + k * 1024); } while (0)
; #define PG8_LDB(dst, b, h) do { if constexpr (ABL & 4) break; _Pragma("unroll") for (int n = 0; n < 2; ++n) _Pragma("unroll") for (int k = 0; k < 2; ++k) dst[n][k] = *(const LAS f16x8*)(lds + PG8_SB(b, h) + boff + n * 2048 + k * 1024); } while (0)
; #define PG8_MMA(ai, bj, At, Bt) do { if constexpr (ABL & 2) break; __builtin_amdgcn_s_setprio(1); _Pragma("unroll") for (int m = 0; m < 4; ++m) _Pragma("unroll") for (int n = 0; n < 2; ++n) _Pragma("unroll") for (int k = 0; k < 2; ++k) \
;         acc[ai][bj][m][n] = __builtin_amdgcn_mfma_f32_16x16x32_f16(Bt[n][k], At[m][k], acc[ai][bj][m][n], 0, 0, 0); __builtin_amdgcn_s_setprio(0); } while (0)
; #define PG8_WAIT_V(n) asm volatile("s_waitcnt vmcnt(" #n ")" ::: "memory")
;     ...
;             PG8_LDB(B0, 0, 0); PG8_LDB(B1, 0, 1); PG8_SCHED; PG8_LDA(At, 0, 0); PG8_STAGE(PG8_SA(1, 1), a1 + hstep, voffA);
;             PG8_WAIT_V(8); PG8_WAIT_L(0); PG8_BAR; PG8_MMAF(0, 0, At, B0); PG8_MMAF(0, 1, At, B1); PG8_BAR; PG8_SCHED;
;             const bool fin = last && !has_next;
;             PG8_LDA(At, 0, 1); if (!fin) { PG8_STAGE(PG8_SB(0, 0), b2, voffB); PG8_STAGE(PG8_SB(0, 1), b2 + hstep, voffB); PG8_STAGE(PG8_SA(0, 0), a2, voffA); }
;             if (!fin) PG8_WAIT_V(8); else PG8_WAIT_V(2); PG8_WAIT_L(0); PG8_BAR; PG8_MMAF(1, 0, At, B0); PG8_MMAF(1, 1, At, B1); PG8_BAR; PG8_SCHED;
;             PG8_LDB(B0, 1, 0); PG8_LDB(B1, 1, 1); PG8_SCHED; PG8_LDA(At, 1, 0); if (!fin) PG8_STAGE(PG8_SA(0, 1), a2 + hstep, voffA);
;             if (!fin) PG8_WAIT_V(8); else PG8_WAIT_V(0); PG8_WAIT_L(0); PG8_BAR; PG8_MMA(0, 0, At, B0); PG8_MMA(0, 1, At, B1); PG8_BAR; PG8_SCHED;
;             PG8_LDA(At, 1, 1); if (!fin) { PG8_STAGE(PG8_SB(1, 0), b3, voffB); PG8_STAGE(PG8_SB(1, 1), b3 + hstep, voffB); PG8_STAGE(PG8_SA(1, 0), a3, voffA); }
;             if (!fin) PG8_WAIT_V(8); PG8_WAIT_L(0); PG8_BAR; PG8_MMA(1, 0, At, B0); PG8_MMA(1, 1, At, B1); PG8_BAR; PG8_SCHED;
.LBB0_749:
	s_waitcnt lgkmcnt(0)
	s_barrier
	v_mfma_f32_16x16x32_f16 v[62:65], v[162:165], v[186:189], v[62:65]
	s_setprio 1
	v_mfma_f32_16x16x32_f16 v[62:65], v[166:169], v[190:193], v[62:65]
	v_mfma_f32_16x16x32_f16 v[58:61], v[158:161], v[190:193], v[58:61]
	v_mfma_f32_16x16x32_f16 v[58:61], v[146:149], v[186:189], v[58:61]
	v_mfma_f32_16x16x32_f16 v[42:45], v[146:149], v[178:181], v[42:45]
	v_mfma_f32_16x16x32_f16 v[42:45], v[158:161], v[182:185], v[42:45]
	v_mfma_f32_16x16x32_f16 v[46:49], v[166:169], v[182:185], v[46:49]
	v_mfma_f32_16x16x32_f16 v[46:49], v[162:165], v[178:181], v[46:49]
	v_mfma_f32_16x16x32_f16 v[30:33], v[162:165], v[170:173], v[30:33]
	v_mfma_f32_16x16x32_f16 v[30:33], v[166:169], v[174:177], v[30:33]
	v_mfma_f32_16x16x32_f16 v[26:29], v[158:161], v[174:177], v[26:29]
	v_mfma_f32_16x16x32_f16 v[26:29], v[146:149], v[170:173], v[26:29]
	v_mfma_f32_16x16x32_f16 v[10:13], v[146:149], v[122:125], v[10:13]
	v_mfma_f32_16x16x32_f16 v[10:13], v[158:161], v[134:137], v[10:13]
	v_mfma_f32_16x16x32_f16 v[14:17], v[166:169], v[134:137], v[14:17]
	v_mfma_f32_16x16x32_f16 v[14:17], v[162:165], v[122:125], v[14:17]
	v_mfma_f32_16x16x32_f16 v[6:9], v[98:101], v[122:125], v[6:9]
	v_mfma_f32_16x16x32_f16 v[6:9], v[110:113], v[134:137], v[6:9]
	v_mfma_f32_16x16x32_f16 v[54:57], v[110:113], v[190:193], v[54:57]
	v_mfma_f32_16x16x32_f16 v[54:57], v[98:101], v[186:189], v[54:57]
	v_mfma_f32_16x16x32_f16 v[50:53], v[74:77], v[186:189], v[50:53]
	v_mfma_f32_16x16x32_f16 v[50:53], v[86:89], v[190:193], v[50:53]
	v_mfma_f32_16x16x32_f16 v[34:37], v[86:89], v[182:185], v[34:37]
	v_mfma_f32_16x16x32_f16 v[34:37], v[74:77], v[178:181], v[34:37]
	v_mfma_f32_16x16x32_f16 v[38:41], v[98:101], v[178:181], v[38:41]
	v_mfma_f32_16x16x32_f16 v[38:41], v[110:113], v[182:185], v[38:41]
	s_barrier
	v_mfma_f32_16x16x32_f16 v[22:25], v[110:113], v[174:177], v[22:25]
	v_mfma_f32_16x16x32_f16 v[22:25], v[98:101], v[170:173], v[22:25]
	v_mfma_f32_16x16x32_f16 v[18:21], v[74:77], v[170:173], v[18:21]
	v_mfma_f32_16x16x32_f16 v[18:21], v[86:89], v[174:177], v[18:21]
	v_mfma_f32_16x16x32_f16 v[2:5], v[86:89], v[134:137], v[2:5]
	v_mfma_f32_16x16x32_f16 v[2:5], v[74:77], v[122:125], v[2:5]
	s_setprio 0
	s_add_i32 s59, s59, 2
	s_add_u32 s30, s30, 0x100
	s_addc_u32 s31, s31, 0
	s_cmp_gt_u32 s59, 13
	s_cbranch_scc1 .LBB0_760
.LBB0_750:
	ds_read_b128 v[146:149], v222
	ds_read_b128 v[158:161], v222 offset:1024
	ds_read_b128 v[162:165], v222 offset:2048
	ds_read_b128 v[166:169], v222 offset:3072
	ds_read_b128 v[74:77], v223
	ds_read_b128 v[86:89], v223 offset:1024
	ds_read_b128 v[98:101], v223 offset:2048
	ds_read_b128 v[110:113], v223 offset:3072
	s_mov_b64 s[6:7], s[56:57]
	s_add_u32 s56, s6, 0x100
	s_addc_u32 s57, s7, 0
	s_cmp_eq_u32 s59, 12
	s_cselect_b64 s[26:27], -1, 0
	s_and_b64 s[8:9], s[26:27], exec
	s_cselect_b32 s25, s47, s57
	s_cselect_b32 s24, s55, s56
	s_cselect_b32 s9, s45, s31
	s_cselect_b32 s8, s58, s30
	ds_read_b128 v[170:173], v224
	ds_read_b128 v[174:177], v224 offset:1024
	ds_read_b128 v[178:181], v224 offset:2048
	ds_read_b128 v[182:185], v224 offset:3072
	ds_read_b128 v[186:189], v224 offset:4096
	ds_read_b128 v[190:193], v224 offset:5120
	ds_read_b128 v[194:197], v224 offset:6144
	ds_read_b128 v[198:201], v224 offset:7168
	s_add_u32 s6, s6, 0x40080
	s_addc_u32 s7, s7, 0
	s_add_u32 m0, s14, 0xc000
	s_nop 0
	global_load_lds_dwordx4 v1, s[6:7]
	s_nop 0
	s_add_u32 m0, s14, 0xe000
	s_nop 0
	global_load_lds_dwordx4 v213, s[6:7]
	s_waitcnt vmcnt(8)
	s_waitcnt lgkmcnt(0)
	s_barrier
	v_mfma_f32_16x16x32_f16 v[122:125], v[146:149], v[170:173], v[154:157]
	s_setprio 1
	v_mfma_f32_16x16x32_f16 v[122:125], v[158:161], v[174:177], v[122:125]
	v_mfma_f32_16x16x32_f16 v[134:137], v[166:169], v[174:177], v[150:153]
	v_mfma_f32_16x16x32_f16 v[134:137], v[162:165], v[170:173], v[134:137]
	v_mfma_f32_16x16x32_f16 v[126:129], v[162:165], v[178:181], v[126:129]
	v_mfma_f32_16x16x32_f16 v[126:129], v[166:169], v[182:185], v[126:129]
	v_mfma_f32_16x16x32_f16 v[130:133], v[158:161], v[182:185], v[130:133]
	v_mfma_f32_16x16x32_f16 v[130:133], v[146:149], v[178:181], v[130:133]
	v_mfma_f32_16x16x32_f16 v[106:109], v[146:149], v[186:189], v[106:109]
	v_mfma_f32_16x16x32_f16 v[106:109], v[158:161], v[190:193], v[106:109]
	v_mfma_f32_16x16x32_f16 v[102:105], v[166:169], v[190:193], v[102:105]
	v_mfma_f32_16x16x32_f16 v[102:105], v[162:165], v[186:189], v[102:105]
	v_mfma_f32_16x16x32_f16 v[78:81], v[162:165], v[194:197], v[78:81]
	v_mfma_f32_16x16x32_f16 v[78:81], v[166:169], v[198:201], v[78:81]
	v_mfma_f32_16x16x32_f16 v[82:85], v[158:161], v[198:201], v[82:85]
	v_mfma_f32_16x16x32_f16 v[82:85], v[146:149], v[194:197], v[82:85]
	v_mfma_f32_16x16x32_f16 v[70:73], v[74:77], v[194:197], v[70:73]
	v_mfma_f32_16x16x32_f16 v[70:73], v[86:89], v[198:201], v[70:73]
	v_mfma_f32_16x16x32_f16 v[142:145], v[86:89], v[174:177], v[142:145]
	v_mfma_f32_16x16x32_f16 v[142:145], v[74:77], v[170:173], v[142:145]
	v_mfma_f32_16x16x32_f16 v[138:141], v[98:101], v[170:173], v[138:141]
	v_mfma_f32_16x16x32_f16 v[138:141], v[110:113], v[174:177], v[138:141]
	v_mfma_f32_16x16x32_f16 v[114:117], v[110:113], v[182:185], v[114:117]
	v_mfma_f32_16x16x32_f16 v[114:117], v[98:101], v[178:181], v[114:117]
	v_mfma_f32_16x16x32_f16 v[118:121], v[74:77], v[178:181], v[118:121]
	v_mfma_f32_16x16x32_f16 v[118:121], v[86:89], v[182:185], v[118:121]
	s_barrier
	v_mfma_f32_16x16x32_f16 v[94:97], v[86:89], v[190:193], v[94:97]
	v_mfma_f32_16x16x32_f16 v[94:97], v[74:77], v[186:189], v[94:97]
	v_mfma_f32_16x16x32_f16 v[90:93], v[98:101], v[186:189], v[90:93]
	v_mfma_f32_16x16x32_f16 v[90:93], v[110:113], v[190:193], v[90:93]
	v_mfma_f32_16x16x32_f16 v[66:69], v[110:113], v[198:201], v[66:69]
	v_mfma_f32_16x16x32_f16 v[66:69], v[98:101], v[194:197], v[66:69]
	s_setprio 0
	ds_read_b128 v[186:189], v224 offset:16384
	ds_read_b128 v[190:193], v224 offset:17408
	ds_read_b128 v[178:181], v224 offset:18432
	ds_read_b128 v[182:185], v224 offset:19456
	ds_read_b128 v[170:173], v224 offset:20480
	ds_read_b128 v[174:177], v224 offset:21504
	ds_read_b128 v[150:153], v224 offset:22528
	ds_read_b128 v[154:157], v224 offset:23552
	s_and_b64 s[6:7], s[4:5], s[26:27]
	s_mov_b64 s[26:27], -1
	s_and_b64 vcc, exec, s[6:7]
	s_cbranch_vccnz .LBB0_752
	s_add_u32 m0, s14, 0x10000
	s_nop 0
	global_load_lds_dwordx4 v209, s[8:9]
	s_nop 0
	s_add_u32 m0, s14, 0x12000
	s_nop 0
	global_load_lds_dwordx4 v219, s[8:9]
	s_add_u32 s26, s8, 0x40000
	s_addc_u32 s27, s9, 0
	s_add_u32 m0, s14, 0x14000
	s_nop 0
	global_load_lds_dwordx4 v209, s[26:27]
	s_nop 0
	s_add_u32 m0, s14, 0x16000
	s_nop 0
	global_load_lds_dwordx4 v219, s[26:27]
	s_mov_b64 s[26:27], 0
	s_add_u32 m0, s14, 0
	s_nop 0
	global_load_lds_dwordx4 v1, s[24:25]
	s_nop 0
	s_add_u32 m0, s14, 0x2000
	s_nop 0
	global_load_lds_dwordx4 v213, s[24:25]
	s_waitcnt vmcnt(8)

; #define PG8_STAGE(bufoff, gbase, voff) do { if constexpr (ABL & 1) break; glds16s<(bufoff)>((voff)[0], (const void*)(gbase), ldsbw); glds16s<(bufoff) + 8192>((voff)[1], (const void*)(gbase), ldsbw); } while (0)
; #define PG8_LDA(dst, b, h) do { if constexpr (ABL & 4) break; _Pragma("unroll") for (int m = 0; m < 4; ++m) _Pragma("unroll") for (int k = 0; k < 2; ++k) dst[m][k] = *(const LAS f16x8*)(lds + PG8_SA(b, h) + aoff + m * 2048 + k * 1024); } while (0)
; #define PG8_LDB(dst, b, h) do { if constexpr (ABL & 4) break; _Pragma("unroll") for (int n = 0; n < 2; ++n) _Pragma("unroll") for (int k = 0; k < 2; ++k) dst[n][k] = *(const LAS f16x8*)(lds + PG8_SB(b, h) + boff + n * 2048 + k * 1024); } while (0)
; #define PG8_MMAF(ai, bj, At, Bt) do { if (t == 0) PG8_MMA0(ai, bj, At, Bt); else PG8_MMA(ai, bj, At, Bt); } while (0)
; #define PG8_WAIT_V(n) asm volatile("s_waitcnt vmcnt(" #n ")" ::: "memory")
; #define PG8_WAIT_L(n) asm volatile("s_waitcnt lgkmcnt(" #n ")" ::: "memory")
; #define PG8_BAR __builtin_amdgcn_s_barrier()
; #define PG8_SCHED __builtin_amdgcn_sched_barrier(0)
;     ...
;             if (!fin) PG8_WAIT_V(8); else PG8_WAIT_V(2); PG8_WAIT_L(0); PG8_BAR; PG8_MMAF(1, 0, At, B0); PG8_MMAF(1, 1, At, B1); PG8_BAR; PG8_SCHED;
;             PG8_LDB(B0, 1, 0); PG8_LDB(B1, 1, 1); PG8_SCHED; PG8_LDA(At, 1, 0); if (!fin) PG8_STAGE(PG8_SA(0, 1), a2 + hstep, voffA);
.LBB0_754:
	s_waitcnt lgkmcnt(0)
	s_xor_b64 s[26:27], s[6:7], -1
	s_barrier
	v_mfma_f32_16x16x32_f16 v[62:65], v[146:149], v[186:189], v[62:65]
	s_setprio 1
	v_mfma_f32_16x16x32_f16 v[62:65], v[158:161], v[190:193], v[62:65]
	v_mfma_f32_16x16x32_f16 v[58:61], v[166:169], v[190:193], v[58:61]
	v_mfma_f32_16x16x32_f16 v[58:61], v[162:165], v[186:189], v[58:61]
	v_mfma_f32_16x16x32_f16 v[42:45], v[162:165], v[178:181], v[42:45]
	v_mfma_f32_16x16x32_f16 v[42:45], v[166:169], v[182:185], v[42:45]
	v_mfma_f32_16x16x32_f16 v[46:49], v[158:161], v[182:185], v[46:49]
	v_mfma_f32_16x16x32_f16 v[46:49], v[146:149], v[178:181], v[46:49]
	v_mfma_f32_16x16x32_f16 v[30:33], v[146:149], v[170:173], v[30:33]
	v_mfma_f32_16x16x32_f16 v[30:33], v[158:161], v[174:177], v[30:33]
	v_mfma_f32_16x16x32_f16 v[26:29], v[166:169], v[174:177], v[26:29]
	v_mfma_f32_16x16x32_f16 v[26:29], v[162:165], v[170:173], v[26:29]
	v_mfma_f32_16x16x32_f16 v[10:13], v[162:165], v[150:153], v[10:13]
	v_mfma_f32_16x16x32_f16 v[10:13], v[166:169], v[154:157], v[10:13]
	v_mfma_f32_16x16x32_f16 v[14:17], v[158:161], v[154:157], v[14:17]
	v_mfma_f32_16x16x32_f16 v[14:17], v[146:149], v[150:153], v[14:17]
	v_mfma_f32_16x16x32_f16 v[6:9], v[74:77], v[150:153], v[6:9]
	v_mfma_f32_16x16x32_f16 v[6:9], v[86:89], v[154:157], v[6:9]
	v_mfma_f32_16x16x32_f16 v[54:57], v[86:89], v[190:193], v[54:57]
	v_mfma_f32_16x16x32_f16 v[54:57], v[74:77], v[186:189], v[54:57]
	v_mfma_f32_16x16x32_f16 v[50:53], v[98:101], v[186:189], v[50:53]
	v_mfma_f32_16x16x32_f16 v[50:53], v[110:113], v[190:193], v[50:53]
	v_mfma_f32_16x16x32_f16 v[34:37], v[110:113], v[182:185], v[34:37]
	v_mfma_f32_16x16x32_f16 v[34:37], v[98:101], v[178:181], v[34:37]
	v_mfma_f32_16x16x32_f16 v[38:41], v[74:77], v[178:181], v[38:41]
	v_mfma_f32_16x16x32_f16 v[38:41], v[86:89], v[182:185], v[38:41]
	s_barrier
	v_mfma_f32_16x16x32_f16 v[22:25], v[86:89], v[174:177], v[22:25]
	v_mfma_f32_16x16x32_f16 v[22:25], v[74:77], v[170:173], v[22:25]
	v_mfma_f32_16x16x32_f16 v[18:21], v[98:101], v[170:173], v[18:21]
	v_mfma_f32_16x16x32_f16 v[18:21], v[110:113], v[174:177], v[18:21]
	v_mfma_f32_16x16x32_f16 v[2:5], v[110:113], v[154:157], v[2:5]
	v_mfma_f32_16x16x32_f16 v[2:5], v[98:101], v[150:153], v[2:5]
	s_setprio 0
	ds_read_b128 v[162:165], v225
	ds_read_b128 v[166:169], v225 offset:1024
	ds_read_b128 v[146:149], v225 offset:2048
	ds_read_b128 v[158:161], v225 offset:3072
	ds_read_b128 v[98:101], v226
	ds_read_b128 v[110:113], v226 offset:1024
	ds_read_b128 v[74:77], v226 offset:2048
	ds_read_b128 v[86:89], v226 offset:3072
	ds_read_b128 v[194:197], v224 offset:32768
	ds_read_b128 v[198:201], v224 offset:33792
	ds_read_b128 v[186:189], v224 offset:34816
	ds_read_b128 v[190:193], v224 offset:35840
	ds_read_b128 v[178:181], v224 offset:36864
	ds_read_b128 v[182:185], v224 offset:37888
	ds_read_b128 v[170:173], v224 offset:38912
	ds_read_b128 v[174:177], v224 offset:39936
	v_cndmask_b32_e64 v150, 0, 1, s[26:27]
	v_cmp_ne_u32_e64 s[6:7], 1, v150
	s_andn2_b64 vcc, exec, s[26:27]
	s_mov_b64 s[26:27], -1
	s_cbranch_vccnz .LBB0_756
	s_add_u32 s26, s24, 0x40000
	s_addc_u32 s27, s25, 0
	s_add_u32 m0, s14, 0x4000
	s_nop 0
	global_load_lds_dwordx4 v1, s[26:27]
	s_nop 0
	s_add_u32 m0, s14, 0x6000
	s_nop 0
	global_load_lds_dwordx4 v213, s[26:27]
	s_waitcnt vmcnt(8)
	s_mov_b64 s[26:27], 0

; #define PG8_STAGE(bufoff, gbase, voff) do { if constexpr (ABL & 1) break; glds16s<(bufoff)>((voff)[0], (const void*)(gbase), ldsbw); glds16s<(bufoff) + 8192>((voff)[1], (const void*)(gbase), ldsbw); } while (0)
; #define PG8_LDA(dst, b, h) do { if constexpr (ABL & 4) break; _Pragma("unroll") for (int m = 0; m < 4; ++m) _Pragma("unroll") for (int k = 0; k < 2; ++k) dst[m][k] = *(const LAS f16x8*)(lds + PG8_SA(b, h) + aoff + m * 2048 + k * 1024); } while (0)
; #define PG8_MMA(ai, bj, At, Bt) do { if constexpr (ABL & 2) break; __builtin_amdgcn_s_setprio(1); _Pragma("unroll") for (int m = 0; m < 4; ++m) _Pragma("unroll") for (int n = 0; n < 2; ++n) _Pragma("unroll") for (int k = 0; k < 2; ++k) \
;         acc[ai][bj][m][n] = __builtin_amdgcn_mfma_f32_16x16x32_f16(Bt[n][k], At[m][k], acc[ai][bj][m][n], 0, 0, 0); __builtin_amdgcn_s_setprio(0); } while (0)
; #define PG8_WAIT_V(n) asm volatile("s_waitcnt vmcnt(" #n ")" ::: "memory")
; #define PG8_WAIT_L(n) asm volatile("s_waitcnt lgkmcnt(" #n ")" ::: "memory")
; #define PG8_BAR __builtin_amdgcn_s_barrier()
; #define PG8_SCHED __builtin_amdgcn_sched_barrier(0)
;     ...
;             if (!fin) PG8_WAIT_V(8); else PG8_WAIT_V(0); PG8_WAIT_L(0); PG8_BAR; PG8_MMA(0, 0, At, B0); PG8_MMA(0, 1, At, B1); PG8_BAR; PG8_SCHED;
;             PG8_LDA(At, 1, 1); if (!fin) { PG8_STAGE(PG8_SB(1, 0), b3, voffB); PG8_STAGE(PG8_SB(1, 1), b3 + hstep, voffB); PG8_STAGE(PG8_SA(1, 0), a3, voffA); }
.LBB0_758:
	s_waitcnt lgkmcnt(0)
	s_barrier
	v_mfma_f32_16x16x32_f16 v[122:125], v[162:165], v[194:197], v[122:125]
	s_setprio 1
	v_mfma_f32_16x16x32_f16 v[154:157], v[166:169], v[198:201], v[122:125]
	v_mfma_f32_16x16x32_f16 v[122:125], v[158:161], v[198:201], v[134:137]
	v_mfma_f32_16x16x32_f16 v[150:153], v[146:149], v[194:197], v[122:125]
	v_mfma_f32_16x16x32_f16 v[102:105], v[146:149], v[178:181], v[102:105]
	v_mfma_f32_16x16x32_f16 v[102:105], v[158:161], v[182:185], v[102:105]
	v_mfma_f32_16x16x32_f16 v[106:109], v[166:169], v[182:185], v[106:109]
	v_mfma_f32_16x16x32_f16 v[106:109], v[162:165], v[178:181], v[106:109]
	v_mfma_f32_16x16x32_f16 v[122:125], v[162:165], v[186:189], v[130:133]
	v_mfma_f32_16x16x32_f16 v[130:133], v[166:169], v[190:193], v[122:125]
	v_mfma_f32_16x16x32_f16 v[122:125], v[158:161], v[190:193], v[126:129]
	v_mfma_f32_16x16x32_f16 v[126:129], v[146:149], v[186:189], v[122:125]
	v_mfma_f32_16x16x32_f16 v[78:81], v[146:149], v[170:173], v[78:81]
	v_mfma_f32_16x16x32_f16 v[78:81], v[158:161], v[174:177], v[78:81]
	v_mfma_f32_16x16x32_f16 v[82:85], v[166:169], v[174:177], v[82:85]
	v_mfma_f32_16x16x32_f16 v[82:85], v[162:165], v[170:173], v[82:85]
	v_mfma_f32_16x16x32_f16 v[70:73], v[98:101], v[170:173], v[70:73]
	v_mfma_f32_16x16x32_f16 v[70:73], v[110:113], v[174:177], v[70:73]
	v_mfma_f32_16x16x32_f16 v[122:125], v[110:113], v[198:201], v[142:145]
	v_mfma_f32_16x16x32_f16 v[142:145], v[98:101], v[194:197], v[122:125]
	v_mfma_f32_16x16x32_f16 v[122:125], v[74:77], v[194:197], v[138:141]
	v_mfma_f32_16x16x32_f16 v[138:141], v[86:89], v[198:201], v[122:125]
	v_mfma_f32_16x16x32_f16 v[114:117], v[86:89], v[190:193], v[114:117]
	v_mfma_f32_16x16x32_f16 v[114:117], v[74:77], v[186:189], v[114:117]
	v_mfma_f32_16x16x32_f16 v[118:121], v[98:101], v[186:189], v[118:121]
	v_mfma_f32_16x16x32_f16 v[118:121], v[110:113], v[190:193], v[118:121]
	s_barrier
	v_mfma_f32_16x16x32_f16 v[94:97], v[110:113], v[182:185], v[94:97]
	v_mfma_f32_16x16x32_f16 v[94:97], v[98:101], v[178:181], v[94:97]
	v_mfma_f32_16x16x32_f16 v[90:93], v[74:77], v[178:181], v[90:93]
	v_mfma_f32_16x16x32_f16 v[90:93], v[86:89], v[182:185], v[90:93]
	v_mfma_f32_16x16x32_f16 v[66:69], v[86:89], v[174:177], v[66:69]
	v_mfma_f32_16x16x32_f16 v[66:69], v[74:77], v[170:173], v[66:69]
	s_setprio 0
	ds_read_b128 v[186:189], v224 offset:49152
	ds_read_b128 v[190:193], v224 offset:50176
	ds_read_b128 v[178:181], v224 offset:51200
	ds_read_b128 v[182:185], v224 offset:52224
	ds_read_b128 v[170:173], v224 offset:53248
	ds_read_b128 v[174:177], v224 offset:54272
	ds_read_b128 v[122:125], v224 offset:55296
	ds_read_b128 v[134:137], v224 offset:56320
	s_and_b64 vcc, exec, s[6:7]
	s_cbranch_vccnz .LBB0_749
	s_add_u32 s6, s24, 0x80
	s_addc_u32 s7, s25, 0
	s_add_u32 s24, s8, 0x80
	s_addc_u32 s25, s9, 0
	s_add_u32 m0, s14, 0x18000
	s_nop 0
	global_load_lds_dwordx4 v209, s[24:25]
	s_nop 0
	s_add_u32 m0, s14, 0x1a000
	s_nop 0
	global_load_lds_dwordx4 v219, s[24:25]
	s_add_u32 s8, s8, 0x40080
	s_addc_u32 s9, s9, 0
	s_add_u32 m0, s14, 0x1c000
	s_nop 0
	global_load_lds_dwordx4 v209, s[8:9]
	s_nop 0
	s_add_u32 m0, s14, 0x1e000
	s_nop 0
	global_load_lds_dwordx4 v219, s[8:9]
	s_nop 0
	s_add_u32 m0, s14, 0x8000
	s_nop 0
	global_load_lds_dwordx4 v1, s[6:7]
	s_nop 0
	s_add_u32 m0, s14, 0xa000
	s_nop 0
	global_load_lds_dwordx4 v213, s[6:7]
	s_waitcnt vmcnt(8)
	s_branch .LBB0_749

; #define PG8_STAGE(bufoff, gbase, voff) do { if constexpr (ABL & 1) break; glds16s<(bufoff)>((voff)[0], (const void*)(gbase), ldsbw); glds16s<(bufoff) + 8192>((voff)[1], (const void*)(gbase), ldsbw); } while (0)
; #define PG8_LDA(dst, b, h) do { if constexpr (ABL & 4) break; _Pragma("unroll") for (int m = 0; m < 4; ++m) _Pragma("unroll") for (int k = 0; k < 2; ++k) dst[m][k] = *(const LAS f16x8*)(lds + PG8_SA(b, h) + aoff + m * 2048 + k * 1024); } while (0)
; #define PG8_LDB(dst, b, h) do { if constexpr (ABL & 4) break; _Pragma("unroll") for (int n = 0; n < 2; ++n) _Pragma("unroll") for (int k = 0; k < 2; ++k) dst[n][k] = *(const LAS f16x8*)(lds + PG8_SB(b, h) + boff + n * 2048 + k * 1024); } while (0)
; #define PG8_MMAF(ai, bj, At, Bt) do { if (t == 0) PG8_MMA0(ai, bj, At, Bt); else PG8_MMA(ai, bj, At, Bt); } while (0)
; #define PG8_WAIT_V(n) asm volatile("s_waitcnt vmcnt(" #n ")" ::: "memory")
; #define PG8_WAIT_L(n) asm volatile("s_waitcnt lgkmcnt(" #n ")" ::: "memory")
; #define PG8_BAR __builtin_amdgcn_s_barrier()
; #define PG8_SCHED __builtin_amdgcn_sched_barrier(0)
;     ...
;         const char* nA = has_next ? (const char*)g.A + (size_t)nxt.pm * tstep : cA; const char* nB = has_next ? (const char*)g.Bt + (size_t)nxt.pn * tstep : cB;
;         for (int t = 0; t < nt; t += 2) {
;             const bool last = (t == nt - 2);
;             const char* a1 = cA + (size_t)(t + 1) * kstep;
;             const char* a2 = last ? nA : cA + (size_t)(t + 2) * kstep; const char* b2 = last ? nB : cB + (size_t)(t + 2) * kstep;
;             const char* a3 = a2 + kstep; const char* b3 = b2 + kstep;
;             if (last && has_next) S.a_ready(nxt);
;             if constexpr (SP2) {
;             PG8_LDB(B0, 0, 0); PG8_LDB(B1, 0, 1); PG8_SCHED; PG8_LDA(At, 0, 0); PG8_STAGE(PG8_SA(1, 1), a1 + hstep, voffA);
;             PG8_WAIT_V(8); PG8_WAIT_L(0); PG8_BAR; PG8_MMAF(0, 0, At, B0); PG8_MMAF(0, 1, At, B1); PG8_BAR; PG8_SCHED;
;             const bool fin = last && !has_next;
;             PG8_LDA(At, 0, 1); if (!fin) { PG8_STAGE(PG8_SB(0, 0), b2, voffB); PG8_STAGE(PG8_SB(0, 1), b2 + hstep, voffB); PG8_STAGE(PG8_SA(0, 0), a2, voffA); }
;             if (!fin) PG8_WAIT_V(8); else PG8_WAIT_V(2); PG8_WAIT_L(0); PG8_BAR; PG8_MMAF(1, 0, At, B0); PG8_MMAF(1, 1, At, B1); PG8_BAR; PG8_SCHED;
.LBB0_841:
	s_ashr_i32 s41, s40, 31
	s_lshl_b64 s[24:25], s[40:41], 19
	s_add_u32 s42, s74, s24
	s_addc_u32 s43, s75, s25
	s_and_b64 s[24:25], exec, s[4:5]
	ds_read_b128 v[2:5], v210
	ds_read_b128 v[6:9], v210 offset:1024
	ds_read_b128 v[10:13], v210 offset:2048
	ds_read_b128 v[14:17], v210 offset:3072
	ds_read_b128 v[18:21], v211
	ds_read_b128 v[22:25], v211 offset:1024
	ds_read_b128 v[26:29], v211 offset:2048
	ds_read_b128 v[30:33], v211 offset:3072
	s_cselect_b32 s41, s9, s43
	s_cselect_b32 s51, s8, s42
	s_ashr_i32 s39, s38, 31
	s_lshl_b64 s[24:25], s[38:39], 19
	s_add_u32 s44, s58, s24
	s_addc_u32 s45, s59, s25
	s_and_b64 s[24:25], exec, s[4:5]
	s_cselect_b32 s39, s7, s45
	s_cselect_b32 s52, s6, s44
	s_add_u32 s48, s8, 0x100
	s_addc_u32 s49, s9, 0
	s_add_u32 s54, s6, 0x100
	s_addc_u32 s55, s7, 0
	s_add_u32 s24, s8, 0x180
	s_addc_u32 s25, s9, 0
	ds_read_b128 v[34:37], v212
	ds_read_b128 v[38:41], v212 offset:1024
	ds_read_b128 v[42:45], v212 offset:2048
	ds_read_b128 v[46:49], v212 offset:3072
	ds_read_b128 v[50:53], v212 offset:4096
	ds_read_b128 v[54:57], v212 offset:5120
	ds_read_b128 v[58:61], v212 offset:6144
	ds_read_b128 v[62:65], v212 offset:7168
	s_add_u32 s26, s6, 0x180
	s_addc_u32 s27, s7, 0
	s_add_u32 s56, s8, 0x40080
	s_addc_u32 s57, s9, 0
	s_add_u32 m0, s14, 0xc000
	s_nop 0
	global_load_lds_dwordx4 v206, s[56:57]
	s_nop 0
	s_add_u32 m0, s14, 0xe000
	s_nop 0
	global_load_lds_dwordx4 v208, s[56:57]
	s_waitcnt vmcnt(8)
	s_waitcnt lgkmcnt(0)
	s_barrier
	v_mfma_f32_16x16x32_f16 v[90:93], v[2:5], v[58:61], 0
	s_setprio 1
	v_mfma_f32_16x16x32_f16 v[94:97], v[6:9], v[62:65], v[90:93]
	v_mfma_f32_16x16x32_f16 v[66:69], v[2:5], v[34:37], 0
	v_mfma_f32_16x16x32_f16 v[66:69], v[6:9], v[38:41], v[66:69]
	v_mfma_f32_16x16x32_f16 v[70:73], v[10:13], v[34:37], 0
	v_mfma_f32_16x16x32_f16 v[70:73], v[14:17], v[38:41], v[70:73]
	v_mfma_f32_16x16x32_f16 v[74:77], v[2:5], v[42:45], 0
	v_mfma_f32_16x16x32_f16 v[74:77], v[6:9], v[46:49], v[74:77]
	v_mfma_f32_16x16x32_f16 v[78:81], v[10:13], v[42:45], 0
	v_mfma_f32_16x16x32_f16 v[78:81], v[14:17], v[46:49], v[78:81]
	v_mfma_f32_16x16x32_f16 v[82:85], v[2:5], v[50:53], 0
	v_mfma_f32_16x16x32_f16 v[82:85], v[6:9], v[54:57], v[82:85]
	v_mfma_f32_16x16x32_f16 v[86:89], v[10:13], v[50:53], 0
	v_mfma_f32_16x16x32_f16 v[86:89], v[14:17], v[54:57], v[86:89]
	v_mfma_f32_16x16x32_f16 v[90:93], v[10:13], v[58:61], 0
	v_mfma_f32_16x16x32_f16 v[102:105], v[14:17], v[62:65], v[90:93]
	v_mfma_f32_16x16x32_f16 v[90:93], v[18:21], v[34:37], 0
	v_mfma_f32_16x16x32_f16 v[118:121], v[22:25], v[38:41], v[90:93]
	v_mfma_f32_16x16x32_f16 v[34:37], v[26:29], v[34:37], 0
	v_mfma_f32_16x16x32_f16 v[34:37], v[30:33], v[38:41], v[34:37]
	v_mfma_f32_16x16x32_f16 v[38:41], v[18:21], v[42:45], 0
	v_mfma_f32_16x16x32_f16 v[38:41], v[22:25], v[46:49], v[38:41]
	v_mfma_f32_16x16x32_f16 v[42:45], v[26:29], v[42:45], 0
	v_mfma_f32_16x16x32_f16 v[42:45], v[30:33], v[46:49], v[42:45]
	v_mfma_f32_16x16x32_f16 v[46:49], v[18:21], v[50:53], 0
	v_mfma_f32_16x16x32_f16 v[46:49], v[22:25], v[54:57], v[46:49]
	s_barrier
	v_mfma_f32_16x16x32_f16 v[50:53], v[26:29], v[50:53], 0
	v_mfma_f32_16x16x32_f16 v[50:53], v[30:33], v[54:57], v[50:53]
	v_mfma_f32_16x16x32_f16 v[54:57], v[18:21], v[58:61], 0
	v_mfma_f32_16x16x32_f16 v[54:57], v[22:25], v[62:65], v[54:57]
	v_mfma_f32_16x16x32_f16 v[58:61], v[26:29], v[58:61], 0
	v_mfma_f32_16x16x32_f16 v[58:61], v[30:33], v[62:65], v[58:61]
	s_setprio 0
	ds_read_b128 v[62:65], v212 offset:16384
	ds_read_b128 v[90:93], v212 offset:17408
	ds_read_b128 v[98:101], v212 offset:18432
	ds_read_b128 v[106:109], v212 offset:19456
	ds_read_b128 v[110:113], v212 offset:20480
	ds_read_b128 v[114:117], v212 offset:21504
	ds_read_b128 v[122:125], v212 offset:22528
	ds_read_b128 v[126:129], v212 offset:23552
	s_add_u32 m0, s14, 0x10000
	s_nop 0
	global_load_lds_dwordx4 v207, s[54:55]
	s_nop 0
	s_add_u32 m0, s14, 0x12000
	s_nop 0
	global_load_lds_dwordx4 v209, s[54:55]
	s_add_u32 s54, s6, 0x40100
	s_addc_u32 s55, s7, 0
	s_add_u32 m0, s14, 0x14000
	s_nop 0
	global_load_lds_dwordx4 v207, s[54:55]
	s_nop 0
	s_add_u32 m0, s14, 0x16000
	s_nop 0
	global_load_lds_dwordx4 v209, s[54:55]
	s_nop 0
	s_add_u32 m0, s14, 0
	s_nop 0
	global_load_lds_dwordx4 v206, s[48:49]
	s_nop 0
	s_add_u32 m0, s14, 0x2000
	s_nop 0
	global_load_lds_dwordx4 v208, s[48:49]
	s_waitcnt vmcnt(8)
	s_waitcnt lgkmcnt(0)
	s_barrier
	v_mfma_f32_16x16x32_f16 v[130:133], v[2:5], v[62:65], 0
	s_setprio 1
	v_mfma_f32_16x16x32_f16 v[130:133], v[6:9], v[90:93], v[130:133]
	v_mfma_f32_16x16x32_f16 v[138:141], v[2:5], v[98:101], 0
	v_mfma_f32_16x16x32_f16 v[138:141], v[6:9], v[106:109], v[138:141]
	v_mfma_f32_16x16x32_f16 v[146:149], v[2:5], v[110:113], 0
	v_mfma_f32_16x16x32_f16 v[146:149], v[6:9], v[114:117], v[146:149]
	v_mfma_f32_16x16x32_f16 v[2:5], v[2:5], v[122:125], 0
	v_mfma_f32_16x16x32_f16 v[2:5], v[6:9], v[126:129], v[2:5]
	v_mfma_f32_16x16x32_f16 v[6:9], v[10:13], v[122:125], 0
	v_mfma_f32_16x16x32_f16 v[6:9], v[14:17], v[126:129], v[6:9]
	v_mfma_f32_16x16x32_f16 v[134:137], v[10:13], v[62:65], 0
	v_mfma_f32_16x16x32_f16 v[134:137], v[14:17], v[90:93], v[134:137]
	v_mfma_f32_16x16x32_f16 v[142:145], v[10:13], v[98:101], 0
	v_mfma_f32_16x16x32_f16 v[142:145], v[14:17], v[106:109], v[142:145]
	v_mfma_f32_16x16x32_f16 v[150:153], v[10:13], v[110:113], 0
	v_mfma_f32_16x16x32_f16 v[150:153], v[14:17], v[114:117], v[150:153]
	v_mfma_f32_16x16x32_f16 v[10:13], v[18:21], v[62:65], 0
	v_mfma_f32_16x16x32_f16 v[14:17], v[22:25], v[90:93], v[10:13]
	v_mfma_f32_16x16x32_f16 v[10:13], v[26:29], v[62:65], 0
	v_mfma_f32_16x16x32_f16 v[154:157], v[30:33], v[90:93], v[10:13]
	v_mfma_f32_16x16x32_f16 v[10:13], v[18:21], v[98:101], 0
	v_mfma_f32_16x16x32_f16 v[158:161], v[22:25], v[106:109], v[10:13]
	v_mfma_f32_16x16x32_f16 v[10:13], v[26:29], v[98:101], 0
	v_mfma_f32_16x16x32_f16 v[162:165], v[30:33], v[106:109], v[10:13]
	v_mfma_f32_16x16x32_f16 v[10:13], v[18:21], v[110:113], 0
	v_mfma_f32_16x16x32_f16 v[166:169], v[22:25], v[114:117], v[10:13]
	s_barrier
; #define PG8_STAGE(bufoff, gbase, voff) do { if constexpr (ABL & 1) break; glds16s<(bufoff)>((voff)[0], (const void*)(gbase), ldsbw); glds16s<(bufoff) + 8192>((voff)[1], (const void*)(gbase), ldsbw); } while (0)
; #define PG8_LDA(dst, b, h) do { if constexpr (ABL & 4) break; _Pragma("unroll") for (int m = 0; m < 4; ++m) _Pragma("unroll") for (int k = 0; k < 2; ++k) dst[m][k] = *(const LAS f16x8*)(lds + PG8_SA(b, h) + aoff + m * 2048 + k * 1024); } while (0)
; #define PG8_LDB(dst, b, h) do { if constexpr (ABL & 4) break; _Pragma("unroll") for (int n = 0; n < 2; ++n) _Pragma("unroll") for (int k = 0; k < 2; ++k) dst[n][k] = *(const LAS f16x8*)(lds + PG8_SB(b, h) + boff + n * 2048 + k * 1024); } while (0)
; #define PG8_MMA(ai, bj, At, Bt) do { if constexpr (ABL & 2) break; __builtin_amdgcn_s_setprio(1); _Pragma("unroll") for (int m = 0; m < 4; ++m) _Pragma("unroll") for (int n = 0; n < 2; ++n) _Pragma("unroll") for (int k = 0; k < 2; ++k) \
;         acc[ai][bj][m][n] = __builtin_amdgcn_mfma_f32_16x16x32_f16(Bt[n][k], At[m][k], acc[ai][bj][m][n], 0, 0, 0); __builtin_amdgcn_s_setprio(0); } while (0)
; #define PG8_MMAF(ai, bj, At, Bt) do { if (t == 0) PG8_MMA0(ai, bj, At, Bt); else PG8_MMA(ai, bj, At, Bt); } while (0)
; #define PG8_WAIT_V(n) asm volatile("s_waitcnt vmcnt(" #n ")" ::: "memory")
; #define PG8_WAIT_L(n) asm volatile("s_waitcnt lgkmcnt(" #n ")" ::: "memory")
; #define PG8_BAR __builtin_amdgcn_s_barrier()
; #define PG8_SCHED __builtin_amdgcn_sched_barrier(0)
;     ...
;             if (!fin) PG8_WAIT_V(8); else PG8_WAIT_V(2); PG8_WAIT_L(0); PG8_BAR; PG8_MMAF(1, 0, At, B0); PG8_MMAF(1, 1, At, B1); PG8_BAR; PG8_SCHED;
;             PG8_LDB(B0, 1, 0); PG8_LDB(B1, 1, 1); PG8_SCHED; PG8_LDA(At, 1, 0); if (!fin) PG8_STAGE(PG8_SA(0, 1), a2 + hstep, voffA);
;             if (!fin) PG8_WAIT_V(8); else PG8_WAIT_V(0); PG8_WAIT_L(0); PG8_BAR; PG8_MMA(0, 0, At, B0); PG8_MMA(0, 1, At, B1); PG8_BAR; PG8_SCHED;
;             PG8_LDA(At, 1, 1); if (!fin) { PG8_STAGE(PG8_SB(1, 0), b3, voffB); PG8_STAGE(PG8_SB(1, 1), b3 + hstep, voffB); PG8_STAGE(PG8_SA(1, 0), a3, voffA); }
;             if (!fin) PG8_WAIT_V(8); PG8_WAIT_L(0); PG8_BAR; PG8_MMA(1, 0, At, B0); PG8_MMA(1, 1, At, B1); PG8_BAR; PG8_SCHED;
	v_mfma_f32_16x16x32_f16 v[10:13], v[26:29], v[110:113], 0
	v_mfma_f32_16x16x32_f16 v[170:173], v[30:33], v[114:117], v[10:13]
	v_mfma_f32_16x16x32_f16 v[10:13], v[18:21], v[122:125], 0
	v_mfma_f32_16x16x32_f16 v[174:177], v[22:25], v[126:129], v[10:13]
	v_mfma_f32_16x16x32_f16 v[10:13], v[26:29], v[122:125], 0
	v_mfma_f32_16x16x32_f16 v[178:181], v[30:33], v[126:129], v[10:13]
	s_setprio 0
	s_nop 4
	ds_read_b128 v[10:13], v213
	ds_read_b128 v[22:25], v213 offset:1024
	ds_read_b128 v[30:33], v213 offset:2048
	ds_read_b128 v[182:185], v213 offset:3072
	ds_read_b128 v[186:189], v214
	ds_read_b128 v[190:193], v214 offset:1024
	ds_read_b128 v[216:219], v214 offset:2048
	ds_read_b128 v[220:223], v214 offset:3072
	ds_read_b128 v[18:21], v212 offset:32768
	ds_read_b128 v[26:29], v212 offset:33792
	ds_read_b128 v[224:227], v212 offset:34816
	ds_read_b128 v[228:231], v212 offset:35840
	ds_read_b128 v[232:235], v212 offset:36864
	ds_read_b128 v[236:239], v212 offset:37888
	ds_read_b128 v[240:243], v212 offset:38912
	ds_read_b128 v[244:247], v212 offset:39936
	s_add_u32 s8, s8, 0x40100
	s_addc_u32 s9, s9, 0
	s_add_u32 m0, s14, 0x4000
	s_nop 0
	global_load_lds_dwordx4 v206, s[8:9]
	s_nop 0
	s_add_u32 m0, s14, 0x6000
	s_nop 0
	global_load_lds_dwordx4 v208, s[8:9]
	s_waitcnt vmcnt(8)
	s_waitcnt lgkmcnt(0)
	s_barrier
	v_mfma_f32_16x16x32_f16 v[62:65], v[10:13], v[18:21], v[66:69]
	s_setprio 1
	v_mfma_f32_16x16x32_f16 v[114:117], v[22:25], v[26:29], v[62:65]
	v_mfma_f32_16x16x32_f16 v[62:65], v[30:33], v[18:21], v[70:73]
	v_mfma_f32_16x16x32_f16 v[110:113], v[182:185], v[26:29], v[62:65]
	v_mfma_f32_16x16x32_f16 v[62:65], v[10:13], v[224:227], v[74:77]
	v_mfma_f32_16x16x32_f16 v[106:109], v[22:25], v[228:231], v[62:65]
	v_mfma_f32_16x16x32_f16 v[62:65], v[30:33], v[224:227], v[78:81]
	v_mfma_f32_16x16x32_f16 v[98:101], v[182:185], v[228:231], v[62:65]
	v_mfma_f32_16x16x32_f16 v[62:65], v[10:13], v[232:235], v[82:85]
	v_mfma_f32_16x16x32_f16 v[90:93], v[22:25], v[236:239], v[62:65]
	v_mfma_f32_16x16x32_f16 v[62:65], v[30:33], v[232:235], v[86:89]
	v_mfma_f32_16x16x32_f16 v[82:85], v[182:185], v[236:239], v[62:65]
	v_mfma_f32_16x16x32_f16 v[62:65], v[10:13], v[240:243], v[94:97]
	v_mfma_f32_16x16x32_f16 v[74:77], v[22:25], v[244:247], v[62:65]
	v_mfma_f32_16x16x32_f16 v[62:65], v[30:33], v[240:243], v[102:105]
	v_mfma_f32_16x16x32_f16 v[62:65], v[182:185], v[244:247], v[62:65]
	v_mfma_f32_16x16x32_f16 v[66:69], v[186:189], v[18:21], v[118:121]
	v_mfma_f32_16x16x32_f16 v[126:129], v[190:193], v[26:29], v[66:69]
	v_mfma_f32_16x16x32_f16 v[18:21], v[216:219], v[18:21], v[34:37]
	v_mfma_f32_16x16x32_f16 v[122:125], v[220:223], v[26:29], v[18:21]
	v_mfma_f32_16x16x32_f16 v[18:21], v[186:189], v[224:227], v[38:41]
	v_mfma_f32_16x16x32_f16 v[118:121], v[190:193], v[228:231], v[18:21]
	v_mfma_f32_16x16x32_f16 v[18:21], v[216:219], v[224:227], v[42:45]
	v_mfma_f32_16x16x32_f16 v[102:105], v[220:223], v[228:231], v[18:21]
	v_mfma_f32_16x16x32_f16 v[18:21], v[186:189], v[232:235], v[46:49]
	v_mfma_f32_16x16x32_f16 v[94:97], v[190:193], v[236:239], v[18:21]
	s_barrier
	v_mfma_f32_16x16x32_f16 v[18:21], v[216:219], v[232:235], v[50:53]
	v_mfma_f32_16x16x32_f16 v[86:89], v[220:223], v[236:239], v[18:21]
	v_mfma_f32_16x16x32_f16 v[18:21], v[186:189], v[240:243], v[54:57]
	v_mfma_f32_16x16x32_f16 v[78:81], v[190:193], v[244:247], v[18:21]
	v_mfma_f32_16x16x32_f16 v[18:21], v[216:219], v[240:243], v[58:61]
	v_mfma_f32_16x16x32_f16 v[70:73], v[220:223], v[244:247], v[18:21]
	s_setprio 0
	ds_read_b128 v[38:41], v212 offset:49152
	ds_read_b128 v[46:49], v212 offset:50176
	ds_read_b128 v[224:227], v212 offset:51200
	ds_read_b128 v[228:231], v212 offset:52224
	ds_read_b128 v[232:235], v212 offset:53248
	ds_read_b128 v[236:239], v212 offset:54272
	ds_read_b128 v[240:243], v212 offset:55296
	ds_read_b128 v[244:247], v212 offset:56320
	s_add_u32 m0, s14, 0x18000
	s_nop 0
	global_load_lds_dwordx4 v207, s[26:27]
	s_nop 0
	s_add_u32 m0, s14, 0x1a000
	s_nop 0
	global_load_lds_dwordx4 v209, s[26:27]
	s_add_u32 s8, s6, 0x40180
	s_addc_u32 s9, s7, 0
	s_add_u32 m0, s14, 0x1c000
	s_nop 0
	global_load_lds_dwordx4 v207, s[8:9]
	s_nop 0
	s_add_u32 m0, s14, 0x1e000
	s_nop 0
	global_load_lds_dwordx4 v209, s[8:9]
	s_nop 0
	s_add_u32 m0, s14, 0x8000
	s_nop 0
	global_load_lds_dwordx4 v206, s[24:25]
	s_nop 0
	s_add_u32 m0, s14, 0xa000
	s_nop 0
	global_load_lds_dwordx4 v208, s[24:25]
	s_waitcnt vmcnt(8)
	s_waitcnt lgkmcnt(0)
	s_barrier
	v_mfma_f32_16x16x32_f16 v[18:21], v[10:13], v[38:41], v[130:133]
	s_setprio 1
	v_mfma_f32_16x16x32_f16 v[58:61], v[22:25], v[46:49], v[18:21]
	v_mfma_f32_16x16x32_f16 v[18:21], v[182:185], v[46:49], v[134:137]
	v_mfma_f32_16x16x32_f16 v[50:53], v[30:33], v[38:41], v[18:21]
	v_mfma_f32_16x16x32_f16 v[18:21], v[10:13], v[224:227], v[138:141]
	v_mfma_f32_16x16x32_f16 v[42:45], v[22:25], v[228:231], v[18:21]
	v_mfma_f32_16x16x32_f16 v[18:21], v[182:185], v[228:231], v[142:145]
	v_mfma_f32_16x16x32_f16 v[34:37], v[30:33], v[224:227], v[18:21]
	v_mfma_f32_16x16x32_f16 v[18:21], v[10:13], v[232:235], v[146:149]
	v_mfma_f32_16x16x32_f16 v[26:29], v[22:25], v[236:239], v[18:21]
	v_mfma_f32_16x16x32_f16 v[2:5], v[22:25], v[244:247], v[2:5]
	v_mfma_f32_16x16x32_f16 v[10:13], v[10:13], v[240:243], v[2:5]
	v_mfma_f32_16x16x32_f16 v[2:5], v[30:33], v[240:243], v[6:9]
	v_mfma_f32_16x16x32_f16 v[2:5], v[182:185], v[244:247], v[2:5]
	v_mfma_f32_16x16x32_f16 v[18:21], v[182:185], v[236:239], v[150:153]
	v_mfma_f32_16x16x32_f16 v[18:21], v[30:33], v[232:235], v[18:21]
	v_mfma_f32_16x16x32_f16 v[6:9], v[186:189], v[38:41], v[14:17]
	v_mfma_f32_16x16x32_f16 v[66:69], v[190:193], v[46:49], v[6:9]
	v_mfma_f32_16x16x32_f16 v[6:9], v[220:223], v[46:49], v[154:157]
	v_mfma_f32_16x16x32_f16 v[54:57], v[216:219], v[38:41], v[6:9]
	v_mfma_f32_16x16x32_f16 v[6:9], v[186:189], v[224:227], v[158:161]
	v_mfma_f32_16x16x32_f16 v[46:49], v[190:193], v[228:231], v[6:9]
	v_mfma_f32_16x16x32_f16 v[6:9], v[220:223], v[228:231], v[162:165]
	v_mfma_f32_16x16x32_f16 v[38:41], v[216:219], v[224:227], v[6:9]
	v_mfma_f32_16x16x32_f16 v[6:9], v[186:189], v[232:235], v[166:169]
	v_mfma_f32_16x16x32_f16 v[30:33], v[190:193], v[236:239], v[6:9]
	s_barrier
	v_mfma_f32_16x16x32_f16 v[6:9], v[220:223], v[236:239], v[170:173]
	v_mfma_f32_16x16x32_f16 v[22:25], v[216:219], v[232:235], v[6:9]
	v_mfma_f32_16x16x32_f16 v[6:9], v[186:189], v[240:243], v[174:177]
	v_mfma_f32_16x16x32_f16 v[14:17], v[190:193], v[244:247], v[6:9]
	v_mfma_f32_16x16x32_f16 v[6:9], v[220:223], v[244:247], v[178:181]
	v_mfma_f32_16x16x32_f16 v[6:9], v[216:219], v[240:243], v[6:9]
	s_setprio 0
	s_add_u32 s53, s6, 0x200
	s_addc_u32 s54, s7, 0
	s_mov_b32 s55, 0
	s_branch .LBB0_843
; #define PG8_STAGE(bufoff, gbase, voff) do { if constexpr (ABL & 1) break; glds16s<(bufoff)>((voff)[0], (const void*)(gbase), ldsbw); glds16s<(bufoff) + 8192>((voff)[1], (const void*)(gbase), ldsbw); } while (0)
; #define PG8_LDA(dst, b, h) do { if constexpr (ABL & 4) break; _Pragma("unroll") for (int m = 0; m < 4; ++m) _Pragma("unroll") for (int k = 0; k < 2; ++k) dst[m][k] = *(const LAS f16x8*)(lds + PG8_SA(b, h) + aoff + m * 2048 + k * 1024); } while (0)
; #define PG8_LDB(dst, b, h) do { if constexpr (ABL & 4) break; _Pragma("unroll") for (int n = 0; n < 2; ++n) _Pragma("unroll") for (int k = 0; k < 2; ++k) dst[n][k] = *(const LAS f16x8*)(lds + PG8_SB(b, h) + boff + n * 2048 + k * 1024); } while (0)
; #define PG8_MMA(ai, bj, At, Bt) do { if constexpr (ABL & 2) break; __builtin_amdgcn_s_setprio(1); _Pragma("unroll") for (int m = 0; m < 4; ++m) _Pragma("unroll") for (int n = 0; n < 2; ++n) _Pragma("unroll") for (int k = 0; k < 2; ++k) \
;         acc[ai][bj][m][n] = __builtin_amdgcn_mfma_f32_16x16x32_f16(Bt[n][k], At[m][k], acc[ai][bj][m][n], 0, 0, 0); __builtin_amdgcn_s_setprio(0); } while (0)
; #define PG8_WAIT_V(n) asm volatile("s_waitcnt vmcnt(" #n ")" ::: "memory")
;     ...
;             PG8_LDB(B0, 0, 0); PG8_LDB(B1, 0, 1); PG8_SCHED; PG8_LDA(At, 0, 0); PG8_STAGE(PG8_SA(1, 1), a1 + hstep, voffA);
;             PG8_WAIT_V(8); PG8_WAIT_L(0); PG8_BAR; PG8_MMAF(0, 0, At, B0); PG8_MMAF(0, 1, At, B1); PG8_BAR; PG8_SCHED;
;             const bool fin = last && !has_next;
;             PG8_LDA(At, 0, 1); if (!fin) { PG8_STAGE(PG8_SB(0, 0), b2, voffB); PG8_STAGE(PG8_SB(0, 1), b2 + hstep, voffB); PG8_STAGE(PG8_SA(0, 0), a2, voffA); }
;             if (!fin) PG8_WAIT_V(8); else PG8_WAIT_V(2); PG8_WAIT_L(0); PG8_BAR; PG8_MMAF(1, 0, At, B0); PG8_MMAF(1, 1, At, B1); PG8_BAR; PG8_SCHED;
;             PG8_LDB(B0, 1, 0); PG8_LDB(B1, 1, 1); PG8_SCHED; PG8_LDA(At, 1, 0); if (!fin) PG8_STAGE(PG8_SA(0, 1), a2 + hstep, voffA);
;             if (!fin) PG8_WAIT_V(8); else PG8_WAIT_V(0); PG8_WAIT_L(0); PG8_BAR; PG8_MMA(0, 0, At, B0); PG8_MMA(0, 1, At, B1); PG8_BAR; PG8_SCHED;
;             PG8_LDA(At, 1, 1); if (!fin) { PG8_STAGE(PG8_SB(1, 0), b3, voffB); PG8_STAGE(PG8_SB(1, 1), b3 + hstep, voffB); PG8_STAGE(PG8_SA(1, 0), a3, voffA); }
;             if (!fin) PG8_WAIT_V(8); PG8_WAIT_L(0); PG8_BAR; PG8_MMA(1, 0, At, B0); PG8_MMA(1, 1, At, B1); PG8_BAR; PG8_SCHED;
.LBB0_842:
	s_waitcnt lgkmcnt(0)
	s_barrier
	v_mfma_f32_16x16x32_f16 v[58:61], v[146:149], v[186:189], v[58:61]
	s_setprio 1
	v_mfma_f32_16x16x32_f16 v[58:61], v[150:153], v[190:193], v[58:61]
	v_mfma_f32_16x16x32_f16 v[50:53], v[158:161], v[190:193], v[50:53]
	v_mfma_f32_16x16x32_f16 v[50:53], v[154:157], v[186:189], v[50:53]
	v_mfma_f32_16x16x32_f16 v[34:37], v[154:157], v[178:181], v[34:37]
	v_mfma_f32_16x16x32_f16 v[34:37], v[158:161], v[182:185], v[34:37]
	v_mfma_f32_16x16x32_f16 v[42:45], v[150:153], v[182:185], v[42:45]
	v_mfma_f32_16x16x32_f16 v[42:45], v[146:149], v[178:181], v[42:45]
	v_mfma_f32_16x16x32_f16 v[26:29], v[146:149], v[170:173], v[26:29]
	v_mfma_f32_16x16x32_f16 v[26:29], v[150:153], v[174:177], v[26:29]
	v_mfma_f32_16x16x32_f16 v[18:21], v[158:161], v[174:177], v[18:21]
	v_mfma_f32_16x16x32_f16 v[18:21], v[154:157], v[170:173], v[18:21]
	v_mfma_f32_16x16x32_f16 v[2:5], v[154:157], v[162:165], v[2:5]
	v_mfma_f32_16x16x32_f16 v[2:5], v[158:161], v[166:169], v[2:5]
	v_mfma_f32_16x16x32_f16 v[10:13], v[150:153], v[166:169], v[10:13]
	v_mfma_f32_16x16x32_f16 v[10:13], v[146:149], v[162:165], v[10:13]
	v_mfma_f32_16x16x32_f16 v[14:17], v[130:133], v[162:165], v[14:17]
	v_mfma_f32_16x16x32_f16 v[14:17], v[134:137], v[166:169], v[14:17]
	v_mfma_f32_16x16x32_f16 v[66:69], v[134:137], v[190:193], v[66:69]
	v_mfma_f32_16x16x32_f16 v[66:69], v[130:133], v[186:189], v[66:69]
	v_mfma_f32_16x16x32_f16 v[54:57], v[138:141], v[186:189], v[54:57]
	v_mfma_f32_16x16x32_f16 v[54:57], v[142:145], v[190:193], v[54:57]
	v_mfma_f32_16x16x32_f16 v[38:41], v[142:145], v[182:185], v[38:41]
	v_mfma_f32_16x16x32_f16 v[38:41], v[138:141], v[178:181], v[38:41]
	v_mfma_f32_16x16x32_f16 v[46:49], v[130:133], v[178:181], v[46:49]
	v_mfma_f32_16x16x32_f16 v[46:49], v[134:137], v[182:185], v[46:49]
	s_barrier
	v_mfma_f32_16x16x32_f16 v[30:33], v[134:137], v[174:177], v[30:33]
	v_mfma_f32_16x16x32_f16 v[30:33], v[130:133], v[170:173], v[30:33]
	v_mfma_f32_16x16x32_f16 v[22:25], v[138:141], v[170:173], v[22:25]
	v_mfma_f32_16x16x32_f16 v[22:25], v[142:145], v[174:177], v[22:25]
	v_mfma_f32_16x16x32_f16 v[6:9], v[142:145], v[166:169], v[6:9]
	v_mfma_f32_16x16x32_f16 v[6:9], v[138:141], v[162:165], v[6:9]
	s_setprio 0
	s_add_i32 s55, s55, 2
	s_add_u32 s53, s53, 0x100
	s_addc_u32 s54, s54, 0
	s_cmp_gt_u32 s55, 13
	s_cbranch_scc1 .LBB0_853
.LBB0_843:
	ds_read_b128 v[146:149], v210
	ds_read_b128 v[150:153], v210 offset:1024
	ds_read_b128 v[154:157], v210 offset:2048
	ds_read_b128 v[158:161], v210 offset:3072
	ds_read_b128 v[130:133], v211
	ds_read_b128 v[134:137], v211 offset:1024
	ds_read_b128 v[138:141], v211 offset:2048
	ds_read_b128 v[142:145], v211 offset:3072
	s_mov_b64 s[6:7], s[48:49]
	s_add_u32 s48, s6, 0x100
	s_addc_u32 s49, s7, 0
	s_cmp_eq_u32 s55, 12
	s_cselect_b64 s[26:27], -1, 0
	s_and_b64 s[8:9], s[26:27], exec
	s_cselect_b32 s25, s41, s49
	s_cselect_b32 s24, s51, s48
	s_cselect_b32 s9, s39, s54
	s_cselect_b32 s8, s52, s53
	ds_read_b128 v[162:165], v212
	ds_read_b128 v[166:169], v212 offset:1024
	ds_read_b128 v[170:173], v212 offset:2048
	ds_read_b128 v[174:177], v212 offset:3072
	ds_read_b128 v[178:181], v212 offset:4096
	ds_read_b128 v[182:185], v212 offset:5120
	ds_read_b128 v[186:189], v212 offset:6144
	ds_read_b128 v[190:193], v212 offset:7168
	s_add_u32 s6, s6, 0x40080
	s_addc_u32 s7, s7, 0
	s_add_u32 m0, s14, 0xc000
	s_nop 0
	global_load_lds_dwordx4 v206, s[6:7]
	s_nop 0
	s_add_u32 m0, s14, 0xe000
	s_nop 0
	global_load_lds_dwordx4 v208, s[6:7]
	s_waitcnt vmcnt(8)
	s_waitcnt lgkmcnt(0)
	s_barrier
	v_mfma_f32_16x16x32_f16 v[114:117], v[146:149], v[162:165], v[114:117]
	s_setprio 1
	v_mfma_f32_16x16x32_f16 v[114:117], v[150:153], v[166:169], v[114:117]
	v_mfma_f32_16x16x32_f16 v[110:113], v[158:161], v[166:169], v[110:113]
	v_mfma_f32_16x16x32_f16 v[110:113], v[154:157], v[162:165], v[110:113]
	v_mfma_f32_16x16x32_f16 v[98:101], v[154:157], v[170:173], v[98:101]
	v_mfma_f32_16x16x32_f16 v[98:101], v[158:161], v[174:177], v[98:101]
	v_mfma_f32_16x16x32_f16 v[106:109], v[150:153], v[174:177], v[106:109]
	v_mfma_f32_16x16x32_f16 v[106:109], v[146:149], v[170:173], v[106:109]
	v_mfma_f32_16x16x32_f16 v[90:93], v[146:149], v[178:181], v[90:93]
	v_mfma_f32_16x16x32_f16 v[90:93], v[150:153], v[182:185], v[90:93]
	v_mfma_f32_16x16x32_f16 v[82:85], v[158:161], v[182:185], v[82:85]
	v_mfma_f32_16x16x32_f16 v[82:85], v[154:157], v[178:181], v[82:85]
	v_mfma_f32_16x16x32_f16 v[62:65], v[154:157], v[186:189], v[62:65]
	v_mfma_f32_16x16x32_f16 v[62:65], v[158:161], v[190:193], v[62:65]
	v_mfma_f32_16x16x32_f16 v[74:77], v[150:153], v[190:193], v[74:77]
	v_mfma_f32_16x16x32_f16 v[74:77], v[146:149], v[186:189], v[74:77]
	v_mfma_f32_16x16x32_f16 v[78:81], v[130:133], v[186:189], v[78:81]
	v_mfma_f32_16x16x32_f16 v[78:81], v[134:137], v[190:193], v[78:81]
	v_mfma_f32_16x16x32_f16 v[126:129], v[134:137], v[166:169], v[126:129]
	v_mfma_f32_16x16x32_f16 v[126:129], v[130:133], v[162:165], v[126:129]
	v_mfma_f32_16x16x32_f16 v[122:125], v[138:141], v[162:165], v[122:125]
	v_mfma_f32_16x16x32_f16 v[122:125], v[142:145], v[166:169], v[122:125]
	v_mfma_f32_16x16x32_f16 v[102:105], v[142:145], v[174:177], v[102:105]
	v_mfma_f32_16x16x32_f16 v[102:105], v[138:141], v[170:173], v[102:105]
	v_mfma_f32_16x16x32_f16 v[118:121], v[130:133], v[170:173], v[118:121]
	v_mfma_f32_16x16x32_f16 v[118:121], v[134:137], v[174:177], v[118:121]
	s_barrier
	v_mfma_f32_16x16x32_f16 v[94:97], v[134:137], v[182:185], v[94:97]
	v_mfma_f32_16x16x32_f16 v[94:97], v[130:133], v[178:181], v[94:97]
	v_mfma_f32_16x16x32_f16 v[86:89], v[138:141], v[178:181], v[86:89]
	v_mfma_f32_16x16x32_f16 v[86:89], v[142:145], v[182:185], v[86:89]
	v_mfma_f32_16x16x32_f16 v[70:73], v[142:145], v[190:193], v[70:73]
	v_mfma_f32_16x16x32_f16 v[70:73], v[138:141], v[186:189], v[70:73]
	s_setprio 0
	ds_read_b128 v[186:189], v212 offset:16384
	ds_read_b128 v[190:193], v212 offset:17408
	ds_read_b128 v[178:181], v212 offset:18432
	ds_read_b128 v[182:185], v212 offset:19456
	ds_read_b128 v[170:173], v212 offset:20480
	ds_read_b128 v[174:177], v212 offset:21504
	ds_read_b128 v[162:165], v212 offset:22528
	ds_read_b128 v[166:169], v212 offset:23552
	s_and_b64 s[6:7], s[4:5], s[26:27]
	s_mov_b64 s[26:27], -1
	s_and_b64 vcc, exec, s[6:7]
	s_cbranch_vccnz .LBB0_845
	s_add_u32 m0, s14, 0x10000
	s_nop 0
	global_load_lds_dwordx4 v207, s[8:9]
	s_nop 0
	s_add_u32 m0, s14, 0x12000
	s_nop 0
	global_load_lds_dwordx4 v209, s[8:9]
	s_add_u32 s26, s8, 0x40000
	s_addc_u32 s27, s9, 0
	s_add_u32 m0, s14, 0x14000
	s_nop 0
	global_load_lds_dwordx4 v207, s[26:27]
	s_nop 0
	s_add_u32 m0, s14, 0x16000
	s_nop 0
	global_load_lds_dwordx4 v209, s[26:27]
	s_mov_b64 s[26:27], 0
	s_add_u32 m0, s14, 0
	s_nop 0
	global_load_lds_dwordx4 v206, s[24:25]
	s_nop 0
	s_add_u32 m0, s14, 0x2000
	s_nop 0
	global_load_lds_dwordx4 v208, s[24:25]
	s_waitcnt vmcnt(8)

; #define PG8_STAGE(bufoff, gbase, voff) do { if constexpr (ABL & 1) break; glds16s<(bufoff)>((voff)[0], (const void*)(gbase), ldsbw); glds16s<(bufoff) + 8192>((voff)[1], (const void*)(gbase), ldsbw); } while (0)
; #define PG8_LDA(dst, b, h) do { if constexpr (ABL & 4) break; _Pragma("unroll") for (int m = 0; m < 4; ++m) _Pragma("unroll") for (int k = 0; k < 2; ++k) dst[m][k] = *(const LAS f16x8*)(lds + PG8_SA(b, h) + aoff + m * 2048 + k * 1024); } while (0)
; #define PG8_LDB(dst, b, h) do { if constexpr (ABL & 4) break; _Pragma("unroll") for (int n = 0; n < 2; ++n) _Pragma("unroll") for (int k = 0; k < 2; ++k) dst[n][k] = *(const LAS f16x8*)(lds + PG8_SB(b, h) + boff + n * 2048 + k * 1024); } while (0)
; #define PG8_MMAF(ai, bj, At, Bt) do { if (t == 0) PG8_MMA0(ai, bj, At, Bt); else PG8_MMA(ai, bj, At, Bt); } while (0)
; #define PG8_WAIT_V(n) asm volatile("s_waitcnt vmcnt(" #n ")" ::: "memory")
; #define PG8_WAIT_L(n) asm volatile("s_waitcnt lgkmcnt(" #n ")" ::: "memory")
; #define PG8_BAR __builtin_amdgcn_s_barrier()
; #define PG8_SCHED __builtin_amdgcn_sched_barrier(0)
;     ...
;             if (!fin) PG8_WAIT_V(8); else PG8_WAIT_V(2); PG8_WAIT_L(0); PG8_BAR; PG8_MMAF(1, 0, At, B0); PG8_MMAF(1, 1, At, B1); PG8_BAR; PG8_SCHED;
;             PG8_LDB(B0, 1, 0); PG8_LDB(B1, 1, 1); PG8_SCHED; PG8_LDA(At, 1, 0); if (!fin) PG8_STAGE(PG8_SA(0, 1), a2 + hstep, voffA);
.LBB0_847:
	s_waitcnt lgkmcnt(0)
	s_xor_b64 s[26:27], s[6:7], -1
	s_barrier
	v_mfma_f32_16x16x32_f16 v[58:61], v[146:149], v[186:189], v[58:61]
	s_setprio 1
	v_mfma_f32_16x16x32_f16 v[58:61], v[150:153], v[190:193], v[58:61]
	v_mfma_f32_16x16x32_f16 v[50:53], v[158:161], v[190:193], v[50:53]
	v_mfma_f32_16x16x32_f16 v[50:53], v[154:157], v[186:189], v[50:53]
	v_mfma_f32_16x16x32_f16 v[34:37], v[154:157], v[178:181], v[34:37]
	v_mfma_f32_16x16x32_f16 v[34:37], v[158:161], v[182:185], v[34:37]
	v_mfma_f32_16x16x32_f16 v[42:45], v[150:153], v[182:185], v[42:45]
	v_mfma_f32_16x16x32_f16 v[42:45], v[146:149], v[178:181], v[42:45]
	v_mfma_f32_16x16x32_f16 v[26:29], v[146:149], v[170:173], v[26:29]
	v_mfma_f32_16x16x32_f16 v[26:29], v[150:153], v[174:177], v[26:29]
	v_mfma_f32_16x16x32_f16 v[18:21], v[158:161], v[174:177], v[18:21]
	v_mfma_f32_16x16x32_f16 v[18:21], v[154:157], v[170:173], v[18:21]
	v_mfma_f32_16x16x32_f16 v[2:5], v[154:157], v[162:165], v[2:5]
	v_mfma_f32_16x16x32_f16 v[2:5], v[158:161], v[166:169], v[2:5]
	v_mfma_f32_16x16x32_f16 v[10:13], v[150:153], v[166:169], v[10:13]
	v_mfma_f32_16x16x32_f16 v[10:13], v[146:149], v[162:165], v[10:13]
	v_mfma_f32_16x16x32_f16 v[14:17], v[130:133], v[162:165], v[14:17]
	v_mfma_f32_16x16x32_f16 v[14:17], v[134:137], v[166:169], v[14:17]
	v_mfma_f32_16x16x32_f16 v[66:69], v[134:137], v[190:193], v[66:69]
	v_mfma_f32_16x16x32_f16 v[66:69], v[130:133], v[186:189], v[66:69]
	v_mfma_f32_16x16x32_f16 v[54:57], v[138:141], v[186:189], v[54:57]
	v_mfma_f32_16x16x32_f16 v[54:57], v[142:145], v[190:193], v[54:57]
	v_mfma_f32_16x16x32_f16 v[38:41], v[142:145], v[182:185], v[38:41]
	v_mfma_f32_16x16x32_f16 v[38:41], v[138:141], v[178:181], v[38:41]
	v_mfma_f32_16x16x32_f16 v[46:49], v[130:133], v[178:181], v[46:49]
	v_mfma_f32_16x16x32_f16 v[46:49], v[134:137], v[182:185], v[46:49]
	s_barrier
	v_mfma_f32_16x16x32_f16 v[30:33], v[134:137], v[174:177], v[30:33]
	v_mfma_f32_16x16x32_f16 v[30:33], v[130:133], v[170:173], v[30:33]
	v_mfma_f32_16x16x32_f16 v[22:25], v[138:141], v[170:173], v[22:25]
	v_mfma_f32_16x16x32_f16 v[22:25], v[142:145], v[174:177], v[22:25]
	v_mfma_f32_16x16x32_f16 v[6:9], v[142:145], v[166:169], v[6:9]
	v_mfma_f32_16x16x32_f16 v[6:9], v[138:141], v[162:165], v[6:9]
	s_setprio 0
	ds_read_b128 v[146:149], v213
	ds_read_b128 v[150:153], v213 offset:1024
	ds_read_b128 v[154:157], v213 offset:2048
	ds_read_b128 v[158:161], v213 offset:3072
	ds_read_b128 v[130:133], v214
	ds_read_b128 v[134:137], v214 offset:1024
	ds_read_b128 v[138:141], v214 offset:2048
	ds_read_b128 v[142:145], v214 offset:3072
	ds_read_b128 v[186:189], v212 offset:32768
	ds_read_b128 v[190:193], v212 offset:33792
	ds_read_b128 v[178:181], v212 offset:34816
	ds_read_b128 v[182:185], v212 offset:35840
	ds_read_b128 v[170:173], v212 offset:36864
	ds_read_b128 v[174:177], v212 offset:37888
	ds_read_b128 v[162:165], v212 offset:38912
	ds_read_b128 v[166:169], v212 offset:39936
	v_cndmask_b32_e64 v216, 0, 1, s[26:27]
	v_cmp_ne_u32_e64 s[6:7], 1, v216
	s_andn2_b64 vcc, exec, s[26:27]
	s_mov_b64 s[26:27], -1
	s_cbranch_vccnz .LBB0_849
	s_add_u32 s26, s24, 0x40000
	s_addc_u32 s27, s25, 0
	s_add_u32 m0, s14, 0x4000
	s_nop 0
	global_load_lds_dwordx4 v206, s[26:27]
	s_nop 0
	s_add_u32 m0, s14, 0x6000
	s_nop 0
	global_load_lds_dwordx4 v208, s[26:27]
	s_waitcnt vmcnt(8)
	s_mov_b64 s[26:27], 0

; #define PG8_STAGE(bufoff, gbase, voff) do { if constexpr (ABL & 1) break; glds16s<(bufoff)>((voff)[0], (const void*)(gbase), ldsbw); glds16s<(bufoff) + 8192>((voff)[1], (const void*)(gbase), ldsbw); } while (0)
; #define PG8_LDA(dst, b, h) do { if constexpr (ABL & 4) break; _Pragma("unroll") for (int m = 0; m < 4; ++m) _Pragma("unroll") for (int k = 0; k < 2; ++k) dst[m][k] = *(const LAS f16x8*)(lds + PG8_SA(b, h) + aoff + m * 2048 + k * 1024); } while (0)
; #define PG8_MMA(ai, bj, At, Bt) do { if constexpr (ABL & 2) break; __builtin_amdgcn_s_setprio(1); _Pragma("unroll") for (int m = 0; m < 4; ++m) _Pragma("unroll") for (int n = 0; n < 2; ++n) _Pragma("unroll") for (int k = 0; k < 2; ++k) \
;         acc[ai][bj][m][n] = __builtin_amdgcn_mfma_f32_16x16x32_f16(Bt[n][k], At[m][k], acc[ai][bj][m][n], 0, 0, 0); __builtin_amdgcn_s_setprio(0); } while (0)
; #define PG8_WAIT_V(n) asm volatile("s_waitcnt vmcnt(" #n ")" ::: "memory")
; #define PG8_WAIT_L(n) asm volatile("s_waitcnt lgkmcnt(" #n ")" ::: "memory")
; #define PG8_BAR __builtin_amdgcn_s_barrier()
; #define PG8_SCHED __builtin_amdgcn_sched_barrier(0)
;     ...
;             if (!fin) PG8_WAIT_V(8); else PG8_WAIT_V(0); PG8_WAIT_L(0); PG8_BAR; PG8_MMA(0, 0, At, B0); PG8_MMA(0, 1, At, B1); PG8_BAR; PG8_SCHED;
;             PG8_LDA(At, 1, 1); if (!fin) { PG8_STAGE(PG8_SB(1, 0), b3, voffB); PG8_STAGE(PG8_SB(1, 1), b3 + hstep, voffB); PG8_STAGE(PG8_SA(1, 0), a3, voffA); }
.LBB0_851:
	s_waitcnt lgkmcnt(0)
	s_barrier
	v_mfma_f32_16x16x32_f16 v[114:117], v[146:149], v[186:189], v[114:117]
	s_setprio 1
	v_mfma_f32_16x16x32_f16 v[114:117], v[150:153], v[190:193], v[114:117]
	v_mfma_f32_16x16x32_f16 v[110:113], v[158:161], v[190:193], v[110:113]
	v_mfma_f32_16x16x32_f16 v[110:113], v[154:157], v[186:189], v[110:113]
	v_mfma_f32_16x16x32_f16 v[98:101], v[154:157], v[178:181], v[98:101]
	v_mfma_f32_16x16x32_f16 v[98:101], v[158:161], v[182:185], v[98:101]
	v_mfma_f32_16x16x32_f16 v[106:109], v[150:153], v[182:185], v[106:109]
	v_mfma_f32_16x16x32_f16 v[106:109], v[146:149], v[178:181], v[106:109]
	v_mfma_f32_16x16x32_f16 v[90:93], v[146:149], v[170:173], v[90:93]
	v_mfma_f32_16x16x32_f16 v[90:93], v[150:153], v[174:177], v[90:93]
	v_mfma_f32_16x16x32_f16 v[82:85], v[158:161], v[174:177], v[82:85]
	v_mfma_f32_16x16x32_f16 v[82:85], v[154:157], v[170:173], v[82:85]
	v_mfma_f32_16x16x32_f16 v[62:65], v[154:157], v[162:165], v[62:65]
	v_mfma_f32_16x16x32_f16 v[62:65], v[158:161], v[166:169], v[62:65]
	v_mfma_f32_16x16x32_f16 v[74:77], v[150:153], v[166:169], v[74:77]
	v_mfma_f32_16x16x32_f16 v[74:77], v[146:149], v[162:165], v[74:77]
	v_mfma_f32_16x16x32_f16 v[78:81], v[130:133], v[162:165], v[78:81]
	v_mfma_f32_16x16x32_f16 v[78:81], v[134:137], v[166:169], v[78:81]
	v_mfma_f32_16x16x32_f16 v[126:129], v[134:137], v[190:193], v[126:129]
	v_mfma_f32_16x16x32_f16 v[126:129], v[130:133], v[186:189], v[126:129]
	v_mfma_f32_16x16x32_f16 v[122:125], v[138:141], v[186:189], v[122:125]
	v_mfma_f32_16x16x32_f16 v[122:125], v[142:145], v[190:193], v[122:125]
	v_mfma_f32_16x16x32_f16 v[102:105], v[142:145], v[182:185], v[102:105]
	v_mfma_f32_16x16x32_f16 v[102:105], v[138:141], v[178:181], v[102:105]
	v_mfma_f32_16x16x32_f16 v[118:121], v[130:133], v[178:181], v[118:121]
	v_mfma_f32_16x16x32_f16 v[118:121], v[134:137], v[182:185], v[118:121]
	s_barrier
	v_mfma_f32_16x16x32_f16 v[94:97], v[134:137], v[174:177], v[94:97]
	v_mfma_f32_16x16x32_f16 v[94:97], v[130:133], v[170:173], v[94:97]
	v_mfma_f32_16x16x32_f16 v[86:89], v[138:141], v[170:173], v[86:89]
	v_mfma_f32_16x16x32_f16 v[86:89], v[142:145], v[174:177], v[86:89]
	v_mfma_f32_16x16x32_f16 v[70:73], v[142:145], v[166:169], v[70:73]
	v_mfma_f32_16x16x32_f16 v[70:73], v[138:141], v[162:165], v[70:73]
	s_setprio 0
	ds_read_b128 v[186:189], v212 offset:49152
	ds_read_b128 v[190:193], v212 offset:50176
	ds_read_b128 v[178:181], v212 offset:51200
	ds_read_b128 v[182:185], v212 offset:52224
	ds_read_b128 v[170:173], v212 offset:53248
	ds_read_b128 v[174:177], v212 offset:54272
	ds_read_b128 v[162:165], v212 offset:55296
	ds_read_b128 v[166:169], v212 offset:56320
	s_and_b64 vcc, exec, s[6:7]
	s_cbranch_vccnz .LBB0_842
	s_add_u32 s6, s24, 0x80
	s_addc_u32 s7, s25, 0
	s_add_u32 s24, s8, 0x80
	s_addc_u32 s25, s9, 0
	s_add_u32 m0, s14, 0x18000
	s_nop 0
	global_load_lds_dwordx4 v207, s[24:25]
	s_nop 0
	s_add_u32 m0, s14, 0x1a000
	s_nop 0
	global_load_lds_dwordx4 v209, s[24:25]
	s_add_u32 s8, s8, 0x40080
	s_addc_u32 s9, s9, 0
	s_add_u32 m0, s14, 0x1c000
	s_nop 0
	global_load_lds_dwordx4 v207, s[8:9]
	s_nop 0
	s_add_u32 m0, s14, 0x1e000
	s_nop 0
	global_load_lds_dwordx4 v209, s[8:9]
	s_nop 0
	s_add_u32 m0, s14, 0x8000
	s_nop 0
	global_load_lds_dwordx4 v206, s[6:7]
	s_nop 0
	s_add_u32 m0, s14, 0xa000
	s_nop 0
	global_load_lds_dwordx4 v208, s[6:7]
	s_waitcnt vmcnt(8)
	s_branch .LBB0_842

; #define PG8_STAGE(bufoff, gbase, voff) do { if constexpr (ABL & 1) break; glds16s<(bufoff)>((voff)[0], (const void*)(gbase), ldsbw); glds16s<(bufoff) + 8192>((voff)[1], (const void*)(gbase), ldsbw); } while (0)
; #define PG8_LDA(dst, b, h) do { if constexpr (ABL & 4) break; _Pragma("unroll") for (int m = 0; m < 4; ++m) _Pragma("unroll") for (int k = 0; k < 2; ++k) dst[m][k] = *(const LAS f16x8*)(lds + PG8_SA(b, h) + aoff + m * 2048 + k * 1024); } while (0)
; #define PG8_LDB(dst, b, h) do { if constexpr (ABL & 4) break; _Pragma("unroll") for (int n = 0; n < 2; ++n) _Pragma("unroll") for (int k = 0; k < 2; ++k) dst[n][k] = *(const LAS f16x8*)(lds + PG8_SB(b, h) + boff + n * 2048 + k * 1024); } while (0)
; #define PG8_MMAF(ai, bj, At, Bt) do { if (t == 0) PG8_MMA0(ai, bj, At, Bt); else PG8_MMA(ai, bj, At, Bt); } while (0)
; #define PG8_WAIT_V(n) asm volatile("s_waitcnt vmcnt(" #n ")" ::: "memory")
; #define PG8_WAIT_L(n) asm volatile("s_waitcnt lgkmcnt(" #n ")" ::: "memory")
; #define PG8_BAR __builtin_amdgcn_s_barrier()
; #define PG8_SCHED __builtin_amdgcn_sched_barrier(0)
;     ...
;         const char* nA = has_next ? (const char*)g.A + (size_t)nxt.pm * tstep : cA; const char* nB = has_next ? (const char*)g.Bt + (size_t)nxt.pn * tstep : cB;
;         for (int t = 0; t < nt; t += 2) {
;             const bool last = (t == nt - 2);
;             const char* a1 = cA + (size_t)(t + 1) * kstep;
;             const char* a2 = last ? nA : cA + (size_t)(t + 2) * kstep; const char* b2 = last ? nB : cB + (size_t)(t + 2) * kstep;
;             const char* a3 = a2 + kstep; const char* b3 = b2 + kstep;
;             if (last && has_next) S.a_ready(nxt);
;             if constexpr (SP2) {
;             PG8_LDB(B0, 0, 0); PG8_LDB(B1, 0, 1); PG8_SCHED; PG8_LDA(At, 0, 0); PG8_STAGE(PG8_SA(1, 1), a1 + hstep, voffA);
;             PG8_WAIT_V(8); PG8_WAIT_L(0); PG8_BAR; PG8_MMAF(0, 0, At, B0); PG8_MMAF(0, 1, At, B1); PG8_BAR; PG8_SCHED;
;             const bool fin = last && !has_next;
;             PG8_LDA(At, 0, 1); if (!fin) { PG8_STAGE(PG8_SB(0, 0), b2, voffB); PG8_STAGE(PG8_SB(0, 1), b2 + hstep, voffB); PG8_STAGE(PG8_SA(0, 0), a2, voffA); }
;             if (!fin) PG8_WAIT_V(8); else PG8_WAIT_V(2); PG8_WAIT_L(0); PG8_BAR; PG8_MMAF(1, 0, At, B0); PG8_MMAF(1, 1, At, B1); PG8_BAR; PG8_SCHED;
.LBB0_878:
	s_ashr_i32 s45, s44, 31
	s_lshl_b64 s[8:9], s[44:45], 17
	s_add_u32 s48, s86, s8
	ds_read_b128 v[2:5], v1
	ds_read_b128 v[6:9], v1 offset:1024
	ds_read_b128 v[10:13], v1 offset:2048
	ds_read_b128 v[14:17], v1 offset:3072
	ds_read_b128 v[18:21], v234
	ds_read_b128 v[22:25], v234 offset:1024
	ds_read_b128 v[26:29], v234 offset:2048
	ds_read_b128 v[30:33], v234 offset:3072
	s_addc_u32 s49, s87, s9
	s_ashr_i32 s43, s42, 31
	s_lshl_b64 s[8:9], s[42:43], 17
	s_add_u32 s50, s70, s8
	s_addc_u32 s51, s71, s9
	s_add_u32 s26, s52, 0x100
	s_addc_u32 s27, s53, 0
	s_add_u32 s60, s54, 0x100
	s_addc_u32 s61, s55, 0
	s_add_u32 s8, s52, 0x180
	s_addc_u32 s9, s53, 0
	ds_read_b128 v[34:37], v235
	ds_read_b128 v[38:41], v235 offset:1024
	ds_read_b128 v[42:45], v235 offset:2048
	ds_read_b128 v[46:49], v235 offset:3072
	ds_read_b128 v[50:53], v235 offset:4096
	ds_read_b128 v[54:57], v235 offset:5120
	ds_read_b128 v[58:61], v235 offset:6144
	ds_read_b128 v[62:65], v235 offset:7168
	s_add_u32 s24, s54, 0x180
	s_addc_u32 s25, s55, 0
	s_add_u32 s62, s52, 0x10080
	s_addc_u32 s63, s53, 0
	s_add_u32 m0, s14, 0xc000
	s_nop 0
	global_load_lds_dwordx4 v230, s[62:63]
	s_nop 0
	s_add_u32 m0, s14, 0xe000
	s_nop 0
	global_load_lds_dwordx4 v232, s[62:63]
	s_waitcnt vmcnt(8)
	s_waitcnt lgkmcnt(0)
	s_barrier
	v_mfma_f32_16x16x32_f16 v[66:69], v[2:5], v[34:37], 0
	s_setprio 1
	v_mfma_f32_16x16x32_f16 v[66:69], v[6:9], v[38:41], v[66:69]
	v_mfma_f32_16x16x32_f16 v[70:73], v[10:13], v[34:37], 0
	v_mfma_f32_16x16x32_f16 v[70:73], v[14:17], v[38:41], v[70:73]
	v_mfma_f32_16x16x32_f16 v[82:85], v[2:5], v[50:53], 0
	v_mfma_f32_16x16x32_f16 v[82:85], v[6:9], v[54:57], v[82:85]
	v_mfma_f32_16x16x32_f16 v[86:89], v[10:13], v[50:53], 0
	v_mfma_f32_16x16x32_f16 v[86:89], v[14:17], v[54:57], v[86:89]
	v_mfma_f32_16x16x32_f16 v[90:93], v[2:5], v[58:61], 0
	v_mfma_f32_16x16x32_f16 v[90:93], v[6:9], v[62:65], v[90:93]
	v_mfma_f32_16x16x32_f16 v[94:97], v[10:13], v[58:61], 0
	v_mfma_f32_16x16x32_f16 v[94:97], v[14:17], v[62:65], v[94:97]
	v_mfma_f32_16x16x32_f16 v[74:77], v[2:5], v[42:45], 0
	v_mfma_f32_16x16x32_f16 v[74:77], v[6:9], v[46:49], v[74:77]
	v_mfma_f32_16x16x32_f16 v[78:81], v[10:13], v[42:45], 0
	v_mfma_f32_16x16x32_f16 v[78:81], v[14:17], v[46:49], v[78:81]
	v_mfma_f32_16x16x32_f16 v[98:101], v[18:21], v[34:37], 0
	v_mfma_f32_16x16x32_f16 v[98:101], v[22:25], v[38:41], v[98:101]
	v_mfma_f32_16x16x32_f16 v[34:37], v[26:29], v[34:37], 0
	v_mfma_f32_16x16x32_f16 v[34:37], v[30:33], v[38:41], v[34:37]
	v_mfma_f32_16x16x32_f16 v[38:41], v[18:21], v[42:45], 0
	v_mfma_f32_16x16x32_f16 v[38:41], v[22:25], v[46:49], v[38:41]
	v_mfma_f32_16x16x32_f16 v[42:45], v[26:29], v[42:45], 0
	v_mfma_f32_16x16x32_f16 v[42:45], v[30:33], v[46:49], v[42:45]
	v_mfma_f32_16x16x32_f16 v[46:49], v[18:21], v[50:53], 0
	v_mfma_f32_16x16x32_f16 v[46:49], v[22:25], v[54:57], v[46:49]
	s_barrier
	v_mfma_f32_16x16x32_f16 v[50:53], v[26:29], v[50:53], 0
	v_mfma_f32_16x16x32_f16 v[50:53], v[30:33], v[54:57], v[50:53]
	v_mfma_f32_16x16x32_f16 v[54:57], v[18:21], v[58:61], 0
	v_mfma_f32_16x16x32_f16 v[54:57], v[22:25], v[62:65], v[54:57]
	v_mfma_f32_16x16x32_f16 v[58:61], v[26:29], v[58:61], 0
	v_mfma_f32_16x16x32_f16 v[58:61], v[30:33], v[62:65], v[58:61]
	s_setprio 0
	ds_read_b128 v[62:65], v235 offset:16384
	ds_read_b128 v[102:105], v235 offset:17408
	ds_read_b128 v[106:109], v235 offset:18432
	ds_read_b128 v[110:113], v235 offset:19456
	ds_read_b128 v[114:117], v235 offset:20480
	ds_read_b128 v[118:121], v235 offset:21504
	ds_read_b128 v[122:125], v235 offset:22528
	ds_read_b128 v[126:129], v235 offset:23552
	s_add_u32 m0, s14, 0x10000
	s_nop 0
	global_load_lds_dwordx4 v231, s[60:61]
	s_nop 0
	s_add_u32 m0, s14, 0x12000
	s_nop 0
	global_load_lds_dwordx4 v233, s[60:61]
	s_add_u32 s60, s54, 0x10100
	s_addc_u32 s61, s55, 0
	s_add_u32 m0, s14, 0x14000
	s_nop 0
	global_load_lds_dwordx4 v231, s[60:61]
	s_nop 0
	s_add_u32 m0, s14, 0x16000
	s_nop 0
	global_load_lds_dwordx4 v233, s[60:61]
	s_nop 0
	s_add_u32 m0, s14, 0
	s_nop 0
	global_load_lds_dwordx4 v230, s[26:27]
	s_nop 0
	s_add_u32 m0, s14, 0x2000
	s_nop 0
	global_load_lds_dwordx4 v232, s[26:27]
	s_waitcnt vmcnt(8)
	s_waitcnt lgkmcnt(0)
	s_barrier
	v_mfma_f32_16x16x32_f16 v[130:133], v[2:5], v[62:65], 0
	s_setprio 1
	v_mfma_f32_16x16x32_f16 v[130:133], v[6:9], v[102:105], v[130:133]
	v_mfma_f32_16x16x32_f16 v[138:141], v[2:5], v[106:109], 0
	v_mfma_f32_16x16x32_f16 v[138:141], v[6:9], v[110:113], v[138:141]
	v_mfma_f32_16x16x32_f16 v[146:149], v[2:5], v[114:117], 0
	v_mfma_f32_16x16x32_f16 v[146:149], v[6:9], v[118:121], v[146:149]
	v_mfma_f32_16x16x32_f16 v[2:5], v[2:5], v[122:125], 0
	v_mfma_f32_16x16x32_f16 v[2:5], v[6:9], v[126:129], v[2:5]
	v_mfma_f32_16x16x32_f16 v[134:137], v[10:13], v[62:65], 0
	v_mfma_f32_16x16x32_f16 v[134:137], v[14:17], v[102:105], v[134:137]
	v_mfma_f32_16x16x32_f16 v[142:145], v[10:13], v[106:109], 0
	v_mfma_f32_16x16x32_f16 v[142:145], v[14:17], v[110:113], v[142:145]
	v_mfma_f32_16x16x32_f16 v[150:153], v[10:13], v[114:117], 0
	v_mfma_f32_16x16x32_f16 v[150:153], v[14:17], v[118:121], v[150:153]
	v_mfma_f32_16x16x32_f16 v[6:9], v[10:13], v[122:125], 0
	v_mfma_f32_16x16x32_f16 v[6:9], v[14:17], v[126:129], v[6:9]
	v_mfma_f32_16x16x32_f16 v[10:13], v[18:21], v[62:65], 0
	v_mfma_f32_16x16x32_f16 v[14:17], v[26:29], v[62:65], 0
	v_mfma_f32_16x16x32_f16 v[10:13], v[22:25], v[102:105], v[10:13]
	v_mfma_f32_16x16x32_f16 v[14:17], v[30:33], v[102:105], v[14:17]
	v_mfma_f32_16x16x32_f16 v[102:105], v[26:29], v[106:109], 0
	v_mfma_f32_16x16x32_f16 v[62:65], v[18:21], v[106:109], 0
	v_mfma_f32_16x16x32_f16 v[154:157], v[30:33], v[110:113], v[102:105]
	v_mfma_f32_16x16x32_f16 v[102:105], v[18:21], v[114:117], 0
	v_mfma_f32_16x16x32_f16 v[18:21], v[18:21], v[122:125], 0
	v_mfma_f32_16x16x32_f16 v[62:65], v[22:25], v[110:113], v[62:65]
	s_barrier
; #define PG8_STAGE(bufoff, gbase, voff) do { if constexpr (ABL & 1) break; glds16s<(bufoff)>((voff)[0], (const void*)(gbase), ldsbw); glds16s<(bufoff) + 8192>((voff)[1], (const void*)(gbase), ldsbw); } while (0)
; #define PG8_LDA(dst, b, h) do { if constexpr (ABL & 4) break; _Pragma("unroll") for (int m = 0; m < 4; ++m) _Pragma("unroll") for (int k = 0; k < 2; ++k) dst[m][k] = *(const LAS f16x8*)(lds + PG8_SA(b, h) + aoff + m * 2048 + k * 1024); } while (0)
; #define PG8_LDB(dst, b, h) do { if constexpr (ABL & 4) break; _Pragma("unroll") for (int n = 0; n < 2; ++n) _Pragma("unroll") for (int k = 0; k < 2; ++k) dst[n][k] = *(const LAS f16x8*)(lds + PG8_SB(b, h) + boff + n * 2048 + k * 1024); } while (0)
; #define PG8_MMA(ai, bj, At, Bt) do { if constexpr (ABL & 2) break; __builtin_amdgcn_s_setprio(1); _Pragma("unroll") for (int m = 0; m < 4; ++m) _Pragma("unroll") for (int n = 0; n < 2; ++n) _Pragma("unroll") for (int k = 0; k < 2; ++k) \
;         acc[ai][bj][m][n] = __builtin_amdgcn_mfma_f32_16x16x32_f16(Bt[n][k], At[m][k], acc[ai][bj][m][n], 0, 0, 0); __builtin_amdgcn_s_setprio(0); } while (0)
; #define PG8_MMAF(ai, bj, At, Bt) do { if (t == 0) PG8_MMA0(ai, bj, At, Bt); else PG8_MMA(ai, bj, At, Bt); } while (0)
; #define PG8_WAIT_V(n) asm volatile("s_waitcnt vmcnt(" #n ")" ::: "memory")
; #define PG8_WAIT_L(n) asm volatile("s_waitcnt lgkmcnt(" #n ")" ::: "memory")
; #define PG8_BAR __builtin_amdgcn_s_barrier()
; #define PG8_SCHED __builtin_amdgcn_sched_barrier(0)
;     ...
;             if (!fin) PG8_WAIT_V(8); else PG8_WAIT_V(2); PG8_WAIT_L(0); PG8_BAR; PG8_MMAF(1, 0, At, B0); PG8_MMAF(1, 1, At, B1); PG8_BAR; PG8_SCHED;
;             PG8_LDB(B0, 1, 0); PG8_LDB(B1, 1, 1); PG8_SCHED; PG8_LDA(At, 1, 0); if (!fin) PG8_STAGE(PG8_SA(0, 1), a2 + hstep, voffA);
;             if (!fin) PG8_WAIT_V(8); else PG8_WAIT_V(0); PG8_WAIT_L(0); PG8_BAR; PG8_MMA(0, 0, At, B0); PG8_MMA(0, 1, At, B1); PG8_BAR; PG8_SCHED;
;             PG8_LDA(At, 1, 1); if (!fin) { PG8_STAGE(PG8_SB(1, 0), b3, voffB); PG8_STAGE(PG8_SB(1, 1), b3 + hstep, voffB); PG8_STAGE(PG8_SA(1, 0), a3, voffA); }
	v_mfma_f32_16x16x32_f16 v[158:161], v[22:25], v[118:121], v[102:105]
	v_mfma_f32_16x16x32_f16 v[102:105], v[26:29], v[114:117], 0
	v_mfma_f32_16x16x32_f16 v[18:21], v[22:25], v[126:129], v[18:21]
	v_mfma_f32_16x16x32_f16 v[22:25], v[26:29], v[122:125], 0
	v_mfma_f32_16x16x32_f16 v[162:165], v[30:33], v[118:121], v[102:105]
	v_mfma_f32_16x16x32_f16 v[22:25], v[30:33], v[126:129], v[22:25]
	s_setprio 0
	ds_read_b128 v[26:29], v236
	ds_read_b128 v[30:33], v236 offset:1024
	ds_read_b128 v[102:105], v236 offset:2048
	ds_read_b128 v[106:109], v236 offset:3072
	ds_read_b128 v[166:169], v237
	ds_read_b128 v[170:173], v237 offset:1024
	ds_read_b128 v[174:177], v237 offset:2048
	ds_read_b128 v[178:181], v237 offset:3072
	ds_read_b128 v[110:113], v235 offset:32768
	ds_read_b128 v[114:117], v235 offset:33792
	ds_read_b128 v[118:121], v235 offset:34816
	ds_read_b128 v[122:125], v235 offset:35840
	ds_read_b128 v[126:129], v235 offset:36864
	ds_read_b128 v[182:185], v235 offset:37888
	ds_read_b128 v[186:189], v235 offset:38912
	ds_read_b128 v[190:193], v235 offset:39936
	s_add_u32 s26, s52, 0x10100
	s_addc_u32 s27, s53, 0
	s_add_u32 m0, s14, 0x4000
	s_nop 0
	global_load_lds_dwordx4 v230, s[26:27]
	s_nop 0
	s_add_u32 m0, s14, 0x6000
	s_nop 0
	global_load_lds_dwordx4 v232, s[26:27]
	s_waitcnt vmcnt(8)
	s_waitcnt lgkmcnt(0)
	s_barrier
	v_mfma_f32_16x16x32_f16 v[82:85], v[26:29], v[126:129], v[82:85]
	s_setprio 1
	v_mfma_f32_16x16x32_f16 v[194:197], v[30:33], v[182:185], v[82:85]
	v_mfma_f32_16x16x32_f16 v[82:85], v[102:105], v[126:129], v[86:89]
	v_mfma_f32_16x16x32_f16 v[198:201], v[106:109], v[182:185], v[82:85]
	v_mfma_f32_16x16x32_f16 v[66:69], v[26:29], v[110:113], v[66:69]
	v_mfma_f32_16x16x32_f16 v[66:69], v[30:33], v[114:117], v[66:69]
	v_mfma_f32_16x16x32_f16 v[70:73], v[102:105], v[110:113], v[70:73]
	v_mfma_f32_16x16x32_f16 v[70:73], v[106:109], v[114:117], v[70:73]
	v_mfma_f32_16x16x32_f16 v[82:85], v[26:29], v[186:189], v[90:93]
	v_mfma_f32_16x16x32_f16 v[202:205], v[30:33], v[190:193], v[82:85]
	v_mfma_f32_16x16x32_f16 v[74:77], v[26:29], v[118:121], v[74:77]
	v_mfma_f32_16x16x32_f16 v[74:77], v[30:33], v[122:125], v[74:77]
	v_mfma_f32_16x16x32_f16 v[78:81], v[102:105], v[118:121], v[78:81]
	v_mfma_f32_16x16x32_f16 v[78:81], v[106:109], v[122:125], v[78:81]
	v_mfma_f32_16x16x32_f16 v[82:85], v[102:105], v[186:189], v[94:97]
	v_mfma_f32_16x16x32_f16 v[206:209], v[106:109], v[190:193], v[82:85]
	v_mfma_f32_16x16x32_f16 v[34:37], v[174:177], v[110:113], v[34:37]
	v_mfma_f32_16x16x32_f16 v[214:217], v[178:181], v[114:117], v[34:37]
	v_mfma_f32_16x16x32_f16 v[34:37], v[166:169], v[118:121], v[38:41]
	v_mfma_f32_16x16x32_f16 v[218:221], v[170:173], v[122:125], v[34:37]
	v_mfma_f32_16x16x32_f16 v[34:37], v[174:177], v[118:121], v[42:45]
	v_mfma_f32_16x16x32_f16 v[222:225], v[178:181], v[122:125], v[34:37]
	v_mfma_f32_16x16x32_f16 v[34:37], v[166:169], v[126:129], v[46:49]
	v_mfma_f32_16x16x32_f16 v[238:241], v[170:173], v[182:185], v[34:37]
	v_mfma_f32_16x16x32_f16 v[34:37], v[174:177], v[126:129], v[50:53]
	v_mfma_f32_16x16x32_f16 v[182:185], v[178:181], v[182:185], v[34:37]
	s_barrier
	v_mfma_f32_16x16x32_f16 v[34:37], v[166:169], v[186:189], v[54:57]
	v_mfma_f32_16x16x32_f16 v[242:245], v[170:173], v[190:193], v[34:37]
	v_mfma_f32_16x16x32_f16 v[34:37], v[174:177], v[186:189], v[58:61]
	v_mfma_f32_16x16x32_f16 v[186:189], v[178:181], v[190:193], v[34:37]
	v_mfma_f32_16x16x32_f16 v[82:85], v[166:169], v[110:113], v[98:101]
	v_mfma_f32_16x16x32_f16 v[210:213], v[170:173], v[114:117], v[82:85]
	s_setprio 0
	ds_read_b128 v[42:45], v235 offset:49152
	ds_read_b128 v[46:49], v235 offset:50176
	ds_read_b128 v[50:53], v235 offset:51200
	ds_read_b128 v[54:57], v235 offset:52224
	ds_read_b128 v[58:61], v235 offset:53248
	ds_read_b128 v[126:129], v235 offset:54272
	ds_read_b128 v[190:193], v235 offset:55296
	ds_read_b128 v[246:249], v235 offset:56320
	s_add_u32 m0, s14, 0x18000
	s_nop 0
	global_load_lds_dwordx4 v231, s[24:25]
	s_nop 0
	s_add_u32 m0, s14, 0x1a000
	s_nop 0
	global_load_lds_dwordx4 v233, s[24:25]
	s_add_u32 s24, s54, 0x10180
	s_addc_u32 s25, s55, 0
	s_add_u32 m0, s14, 0x1c000
	s_nop 0
	global_load_lds_dwordx4 v231, s[24:25]
	s_nop 0
	s_add_u32 m0, s14, 0x1e000
	s_nop 0
	global_load_lds_dwordx4 v233, s[24:25]
	s_nop 0
	s_add_u32 m0, s14, 0x8000
	s_nop 0
	global_load_lds_dwordx4 v230, s[8:9]
	s_nop 0
	s_add_u32 m0, s14, 0xa000
	s_nop 0
	global_load_lds_dwordx4 v232, s[8:9]
	s_waitcnt vmcnt(8)
	s_waitcnt lgkmcnt(0)
	s_barrier
; #define PG8_STAGE(bufoff, gbase, voff) do { if constexpr (ABL & 1) break; glds16s<(bufoff)>((voff)[0], (const void*)(gbase), ldsbw); glds16s<(bufoff) + 8192>((voff)[1], (const void*)(gbase), ldsbw); } while (0)
; #define PG8_LDA(dst, b, h) do { if constexpr (ABL & 4) break; _Pragma("unroll") for (int m = 0; m < 4; ++m) _Pragma("unroll") for (int k = 0; k < 2; ++k) dst[m][k] = *(const LAS f16x8*)(lds + PG8_SA(b, h) + aoff + m * 2048 + k * 1024); } while (0)
; #define PG8_LDB(dst, b, h) do { if constexpr (ABL & 4) break; _Pragma("unroll") for (int n = 0; n < 2; ++n) _Pragma("unroll") for (int k = 0; k < 2; ++k) dst[n][k] = *(const LAS f16x8*)(lds + PG8_SB(b, h) + boff + n * 2048 + k * 1024); } while (0)
; #define PG8_MMA(ai, bj, At, Bt) do { if constexpr (ABL & 2) break; __builtin_amdgcn_s_setprio(1); _Pragma("unroll") for (int m = 0; m < 4; ++m) _Pragma("unroll") for (int n = 0; n < 2; ++n) _Pragma("unroll") for (int k = 0; k < 2; ++k) \
;         acc[ai][bj][m][n] = __builtin_amdgcn_mfma_f32_16x16x32_f16(Bt[n][k], At[m][k], acc[ai][bj][m][n], 0, 0, 0); __builtin_amdgcn_s_setprio(0); } while (0)
; #define PG8_WAIT_V(n) asm volatile("s_waitcnt vmcnt(" #n ")" ::: "memory")
;     ...
;             PG8_LDB(B0, 0, 0); PG8_LDB(B1, 0, 1); PG8_SCHED; PG8_LDA(At, 0, 0); PG8_STAGE(PG8_SA(1, 1), a1 + hstep, voffA);
;             PG8_WAIT_V(8); PG8_WAIT_L(0); PG8_BAR; PG8_MMAF(0, 0, At, B0); PG8_MMAF(0, 1, At, B1); PG8_BAR; PG8_SCHED;
;             const bool fin = last && !has_next;
;             PG8_LDA(At, 0, 1); if (!fin) { PG8_STAGE(PG8_SB(0, 0), b2, voffB); PG8_STAGE(PG8_SB(0, 1), b2 + hstep, voffB); PG8_STAGE(PG8_SA(0, 0), a2, voffA); }
;             if (!fin) PG8_WAIT_V(8); else PG8_WAIT_V(2); PG8_WAIT_L(0); PG8_BAR; PG8_MMAF(1, 0, At, B0); PG8_MMAF(1, 1, At, B1); PG8_BAR; PG8_SCHED;
;             PG8_LDB(B0, 1, 0); PG8_LDB(B1, 1, 1); PG8_SCHED; PG8_LDA(At, 1, 0); if (!fin) PG8_STAGE(PG8_SA(0, 1), a2 + hstep, voffA);
;             if (!fin) PG8_WAIT_V(8); else PG8_WAIT_V(0); PG8_WAIT_L(0); PG8_BAR; PG8_MMA(0, 0, At, B0); PG8_MMA(0, 1, At, B1); PG8_BAR; PG8_SCHED;
;             PG8_LDA(At, 1, 1); if (!fin) { PG8_STAGE(PG8_SB(1, 0), b3, voffB); PG8_STAGE(PG8_SB(1, 1), b3 + hstep, voffB); PG8_STAGE(PG8_SA(1, 0), a3, voffA); }
;             if (!fin) PG8_WAIT_V(8); PG8_WAIT_L(0); PG8_BAR; PG8_MMA(1, 0, At, B0); PG8_MMA(1, 1, At, B1); PG8_BAR; PG8_SCHED;
	v_mfma_f32_16x16x32_f16 v[2:5], v[26:29], v[190:193], v[2:5]
	s_setprio 1
	v_mfma_f32_16x16x32_f16 v[98:101], v[30:33], v[246:249], v[2:5]
	v_mfma_f32_16x16x32_f16 v[34:37], v[26:29], v[42:45], v[130:133]
	v_mfma_f32_16x16x32_f16 v[34:37], v[30:33], v[46:49], v[34:37]
	v_mfma_f32_16x16x32_f16 v[38:41], v[102:105], v[42:45], v[134:137]
	v_mfma_f32_16x16x32_f16 v[38:41], v[106:109], v[46:49], v[38:41]
	v_mfma_f32_16x16x32_f16 v[82:85], v[26:29], v[50:53], v[138:141]
	v_mfma_f32_16x16x32_f16 v[82:85], v[30:33], v[54:57], v[82:85]
	v_mfma_f32_16x16x32_f16 v[86:89], v[102:105], v[50:53], v[142:145]
	v_mfma_f32_16x16x32_f16 v[86:89], v[106:109], v[54:57], v[86:89]
	v_mfma_f32_16x16x32_f16 v[90:93], v[26:29], v[58:61], v[146:149]
	v_mfma_f32_16x16x32_f16 v[90:93], v[30:33], v[126:129], v[90:93]
	v_mfma_f32_16x16x32_f16 v[94:97], v[102:105], v[58:61], v[150:153]
	v_mfma_f32_16x16x32_f16 v[94:97], v[106:109], v[126:129], v[94:97]
	v_mfma_f32_16x16x32_f16 v[2:5], v[102:105], v[190:193], v[6:9]
	v_mfma_f32_16x16x32_f16 v[102:105], v[106:109], v[246:249], v[2:5]
	v_mfma_f32_16x16x32_f16 v[2:5], v[166:169], v[42:45], v[10:13]
	v_mfma_f32_16x16x32_f16 v[106:109], v[170:173], v[46:49], v[2:5]
	v_mfma_f32_16x16x32_f16 v[2:5], v[174:177], v[42:45], v[14:17]
	v_mfma_f32_16x16x32_f16 v[110:113], v[178:181], v[46:49], v[2:5]
	v_mfma_f32_16x16x32_f16 v[2:5], v[166:169], v[50:53], v[62:65]
	v_mfma_f32_16x16x32_f16 v[114:117], v[170:173], v[54:57], v[2:5]
	v_mfma_f32_16x16x32_f16 v[2:5], v[174:177], v[50:53], v[154:157]
	v_mfma_f32_16x16x32_f16 v[118:121], v[178:181], v[54:57], v[2:5]
	v_mfma_f32_16x16x32_f16 v[2:5], v[166:169], v[58:61], v[158:161]
	v_mfma_f32_16x16x32_f16 v[122:125], v[170:173], v[126:129], v[2:5]
	s_barrier
	v_mfma_f32_16x16x32_f16 v[2:5], v[174:177], v[58:61], v[162:165]
	v_mfma_f32_16x16x32_f16 v[126:129], v[178:181], v[126:129], v[2:5]
	v_mfma_f32_16x16x32_f16 v[2:5], v[166:169], v[190:193], v[18:21]
	v_mfma_f32_16x16x32_f16 v[130:133], v[170:173], v[246:249], v[2:5]
	v_mfma_f32_16x16x32_f16 v[2:5], v[174:177], v[190:193], v[22:25]
	v_mfma_f32_16x16x32_f16 v[134:137], v[178:181], v[246:249], v[2:5]
	s_setprio 0
	ds_read_b128 v[154:157], v1
	ds_read_b128 v[158:161], v1 offset:1024
	ds_read_b128 v[162:165], v1 offset:2048
	ds_read_b128 v[166:169], v1 offset:3072
	ds_read_b128 v[138:141], v234
	ds_read_b128 v[142:145], v234 offset:1024
	ds_read_b128 v[146:149], v234 offset:2048
	ds_read_b128 v[150:153], v234 offset:3072
	ds_read_b128 v[46:49], v235
	ds_read_b128 v[50:53], v235 offset:1024
	ds_read_b128 v[54:57], v235 offset:2048
	ds_read_b128 v[58:61], v235 offset:3072
	ds_read_b128 v[62:65], v235 offset:4096
	ds_read_b128 v[170:173], v235 offset:5120
	ds_read_b128 v[174:177], v235 offset:6144
	ds_read_b128 v[178:181], v235 offset:7168
	s_add_u32 s8, s52, 0x10180
	s_addc_u32 s9, s53, 0
	s_add_u32 m0, s14, 0xc000
	s_nop 0
	global_load_lds_dwordx4 v230, s[8:9]
	s_nop 0
	s_add_u32 m0, s14, 0xe000
	s_nop 0
	global_load_lds_dwordx4 v232, s[8:9]
	s_waitcnt vmcnt(8)
	s_waitcnt lgkmcnt(0)
	s_barrier
	v_mfma_f32_16x16x32_f16 v[2:5], v[154:157], v[46:49], v[66:69]
	s_setprio 1
	v_mfma_f32_16x16x32_f16 v[2:5], v[158:161], v[50:53], v[2:5]
	v_mfma_f32_16x16x32_f16 v[6:9], v[162:165], v[46:49], v[70:73]
	v_mfma_f32_16x16x32_f16 v[6:9], v[166:169], v[50:53], v[6:9]
	v_mfma_f32_16x16x32_f16 v[10:13], v[154:157], v[54:57], v[74:77]
	v_mfma_f32_16x16x32_f16 v[10:13], v[158:161], v[58:61], v[10:13]
	v_mfma_f32_16x16x32_f16 v[14:17], v[162:165], v[54:57], v[78:81]
	v_mfma_f32_16x16x32_f16 v[14:17], v[166:169], v[58:61], v[14:17]
	v_mfma_f32_16x16x32_f16 v[18:21], v[154:157], v[62:65], v[194:197]
	v_mfma_f32_16x16x32_f16 v[18:21], v[158:161], v[170:173], v[18:21]
	v_mfma_f32_16x16x32_f16 v[22:25], v[162:165], v[62:65], v[198:201]
	v_mfma_f32_16x16x32_f16 v[22:25], v[166:169], v[170:173], v[22:25]
	v_mfma_f32_16x16x32_f16 v[26:29], v[154:157], v[174:177], v[202:205]
	v_mfma_f32_16x16x32_f16 v[26:29], v[158:161], v[178:181], v[26:29]
	v_mfma_f32_16x16x32_f16 v[30:33], v[162:165], v[174:177], v[206:209]
	v_mfma_f32_16x16x32_f16 v[30:33], v[166:169], v[178:181], v[30:33]
	v_mfma_f32_16x16x32_f16 v[42:45], v[138:141], v[46:49], v[210:213]
	v_mfma_f32_16x16x32_f16 v[42:45], v[142:145], v[50:53], v[42:45]
	v_mfma_f32_16x16x32_f16 v[46:49], v[146:149], v[46:49], v[214:217]
	v_mfma_f32_16x16x32_f16 v[46:49], v[150:153], v[50:53], v[46:49]
	v_mfma_f32_16x16x32_f16 v[50:53], v[138:141], v[54:57], v[218:221]
	v_mfma_f32_16x16x32_f16 v[50:53], v[142:145], v[58:61], v[50:53]
	v_mfma_f32_16x16x32_f16 v[54:57], v[146:149], v[54:57], v[222:225]
	v_mfma_f32_16x16x32_f16 v[54:57], v[150:153], v[58:61], v[54:57]
	v_mfma_f32_16x16x32_f16 v[58:61], v[138:141], v[62:65], v[238:241]
	v_mfma_f32_16x16x32_f16 v[58:61], v[142:145], v[170:173], v[58:61]
	s_barrier
	v_mfma_f32_16x16x32_f16 v[62:65], v[146:149], v[62:65], v[182:185]
	v_mfma_f32_16x16x32_f16 v[62:65], v[150:153], v[170:173], v[62:65]
	v_mfma_f32_16x16x32_f16 v[66:69], v[138:141], v[174:177], v[242:245]
	v_mfma_f32_16x16x32_f16 v[66:69], v[142:145], v[178:181], v[66:69]
	v_mfma_f32_16x16x32_f16 v[70:73], v[146:149], v[174:177], v[186:189]
	v_mfma_f32_16x16x32_f16 v[70:73], v[150:153], v[178:181], v[70:73]
	s_setprio 0
	ds_read_b128 v[194:197], v235 offset:16384
	ds_read_b128 v[198:201], v235 offset:17408
	ds_read_b128 v[186:189], v235 offset:18432
	ds_read_b128 v[190:193], v235 offset:19456
	ds_read_b128 v[178:181], v235 offset:20480
	ds_read_b128 v[182:185], v235 offset:21504
	ds_read_b128 v[170:173], v235 offset:22528
	ds_read_b128 v[174:177], v235 offset:23552
	s_mov_b64 s[8:9], -1
	s_and_b64 vcc, exec, s[4:5]
	s_cbranch_vccz .LBB0_880
	s_waitcnt vmcnt(2)
	s_mov_b64 s[8:9], 0

; #define PG8_STAGE(bufoff, gbase, voff) do { if constexpr (ABL & 1) break; glds16s<(bufoff)>((voff)[0], (const void*)(gbase), ldsbw); glds16s<(bufoff) + 8192>((voff)[1], (const void*)(gbase), ldsbw); } while (0)
; #define PG8_LDA(dst, b, h) do { if constexpr (ABL & 4) break; _Pragma("unroll") for (int m = 0; m < 4; ++m) _Pragma("unroll") for (int k = 0; k < 2; ++k) dst[m][k] = *(const LAS f16x8*)(lds + PG8_SA(b, h) + aoff + m * 2048 + k * 1024); } while (0)
; #define PG8_LDB(dst, b, h) do { if constexpr (ABL & 4) break; _Pragma("unroll") for (int n = 0; n < 2; ++n) _Pragma("unroll") for (int k = 0; k < 2; ++k) dst[n][k] = *(const LAS f16x8*)(lds + PG8_SB(b, h) + boff + n * 2048 + k * 1024); } while (0)
; #define PG8_MMAF(ai, bj, At, Bt) do { if (t == 0) PG8_MMA0(ai, bj, At, Bt); else PG8_MMA(ai, bj, At, Bt); } while (0)
; #define PG8_WAIT_V(n) asm volatile("s_waitcnt vmcnt(" #n ")" ::: "memory")
; #define PG8_WAIT_L(n) asm volatile("s_waitcnt lgkmcnt(" #n ")" ::: "memory")
; #define PG8_BAR __builtin_amdgcn_s_barrier()
; #define PG8_SCHED __builtin_amdgcn_sched_barrier(0)
;     ...
;             if (!fin) PG8_WAIT_V(8); else PG8_WAIT_V(2); PG8_WAIT_L(0); PG8_BAR; PG8_MMAF(1, 0, At, B0); PG8_MMAF(1, 1, At, B1); PG8_BAR; PG8_SCHED;
;             PG8_LDB(B0, 1, 0); PG8_LDB(B1, 1, 1); PG8_SCHED; PG8_LDA(At, 1, 0); if (!fin) PG8_STAGE(PG8_SA(0, 1), a2 + hstep, voffA);
.LBB0_882:
	s_waitcnt lgkmcnt(0)
	s_barrier
	v_mfma_f32_16x16x32_f16 v[34:37], v[154:157], v[194:197], v[34:37]
	s_setprio 1
	v_mfma_f32_16x16x32_f16 v[74:77], v[158:161], v[198:201], v[34:37]
	v_mfma_f32_16x16x32_f16 v[34:37], v[162:165], v[194:197], v[38:41]
	v_mfma_f32_16x16x32_f16 v[78:81], v[166:169], v[198:201], v[34:37]
	v_mfma_f32_16x16x32_f16 v[34:37], v[154:157], v[186:189], v[82:85]
	v_mfma_f32_16x16x32_f16 v[82:85], v[158:161], v[190:193], v[34:37]
	v_mfma_f32_16x16x32_f16 v[34:37], v[162:165], v[186:189], v[86:89]
	v_mfma_f32_16x16x32_f16 v[86:89], v[166:169], v[190:193], v[34:37]
	v_mfma_f32_16x16x32_f16 v[34:37], v[154:157], v[178:181], v[90:93]
	v_mfma_f32_16x16x32_f16 v[90:93], v[158:161], v[182:185], v[34:37]
	v_mfma_f32_16x16x32_f16 v[34:37], v[162:165], v[178:181], v[94:97]
	v_mfma_f32_16x16x32_f16 v[94:97], v[166:169], v[182:185], v[34:37]
	v_mfma_f32_16x16x32_f16 v[34:37], v[154:157], v[170:173], v[98:101]
	v_mfma_f32_16x16x32_f16 v[98:101], v[158:161], v[174:177], v[34:37]
	v_mfma_f32_16x16x32_f16 v[34:37], v[162:165], v[170:173], v[102:105]
	v_mfma_f32_16x16x32_f16 v[102:105], v[166:169], v[174:177], v[34:37]
	v_mfma_f32_16x16x32_f16 v[34:37], v[138:141], v[194:197], v[106:109]
	v_mfma_f32_16x16x32_f16 v[106:109], v[142:145], v[198:201], v[34:37]
	v_mfma_f32_16x16x32_f16 v[34:37], v[146:149], v[194:197], v[110:113]
	v_mfma_f32_16x16x32_f16 v[110:113], v[150:153], v[198:201], v[34:37]
	v_mfma_f32_16x16x32_f16 v[34:37], v[138:141], v[186:189], v[114:117]
	v_mfma_f32_16x16x32_f16 v[114:117], v[142:145], v[190:193], v[34:37]
	v_mfma_f32_16x16x32_f16 v[34:37], v[146:149], v[186:189], v[118:121]
	v_mfma_f32_16x16x32_f16 v[118:121], v[150:153], v[190:193], v[34:37]
	v_mfma_f32_16x16x32_f16 v[34:37], v[138:141], v[178:181], v[122:125]
	v_mfma_f32_16x16x32_f16 v[122:125], v[142:145], v[182:185], v[34:37]
	s_barrier
	v_mfma_f32_16x16x32_f16 v[34:37], v[146:149], v[178:181], v[126:129]
	v_mfma_f32_16x16x32_f16 v[126:129], v[150:153], v[182:185], v[34:37]
	v_mfma_f32_16x16x32_f16 v[34:37], v[138:141], v[170:173], v[130:133]
	v_mfma_f32_16x16x32_f16 v[130:133], v[142:145], v[174:177], v[34:37]
	v_mfma_f32_16x16x32_f16 v[34:37], v[146:149], v[170:173], v[134:137]
	v_mfma_f32_16x16x32_f16 v[134:137], v[150:153], v[174:177], v[34:37]
	s_setprio 0
	ds_read_b128 v[170:173], v236
	ds_read_b128 v[174:177], v236 offset:1024
	ds_read_b128 v[178:181], v236 offset:2048
	ds_read_b128 v[182:185], v236 offset:3072
	ds_read_b128 v[146:149], v237
	ds_read_b128 v[150:153], v237 offset:1024
	ds_read_b128 v[154:157], v237 offset:2048
	ds_read_b128 v[158:161], v237 offset:3072
	ds_read_b128 v[162:165], v235 offset:32768
	ds_read_b128 v[206:209], v235 offset:33792
	ds_read_b128 v[166:169], v235 offset:34816
	ds_read_b128 v[218:221], v235 offset:35840
	ds_read_b128 v[210:213], v235 offset:36864
	ds_read_b128 v[214:217], v235 offset:37888
	ds_read_b128 v[194:197], v235 offset:38912
	ds_read_b128 v[198:201], v235 offset:39936
	s_mov_b64 s[8:9], -1
	s_and_b64 vcc, exec, s[4:5]
	s_cbranch_vccz .LBB0_884
	s_waitcnt vmcnt(0)
	s_mov_b64 s[8:9], 0

; #define PG8_STAGE(bufoff, gbase, voff) do { if constexpr (ABL & 1) break; glds16s<(bufoff)>((voff)[0], (const void*)(gbase), ldsbw); glds16s<(bufoff) + 8192>((voff)[1], (const void*)(gbase), ldsbw); } while (0)
; #define PG8_LDA(dst, b, h) do { if constexpr (ABL & 4) break; _Pragma("unroll") for (int m = 0; m < 4; ++m) _Pragma("unroll") for (int k = 0; k < 2; ++k) dst[m][k] = *(const LAS f16x8*)(lds + PG8_SA(b, h) + aoff + m * 2048 + k * 1024); } while (0)
; #define PG8_MMA(ai, bj, At, Bt) do { if constexpr (ABL & 2) break; __builtin_amdgcn_s_setprio(1); _Pragma("unroll") for (int m = 0; m < 4; ++m) _Pragma("unroll") for (int n = 0; n < 2; ++n) _Pragma("unroll") for (int k = 0; k < 2; ++k) \
;         acc[ai][bj][m][n] = __builtin_amdgcn_mfma_f32_16x16x32_f16(Bt[n][k], At[m][k], acc[ai][bj][m][n], 0, 0, 0); __builtin_amdgcn_s_setprio(0); } while (0)
; #define PG8_WAIT_V(n) asm volatile("s_waitcnt vmcnt(" #n ")" ::: "memory")
; #define PG8_WAIT_L(n) asm volatile("s_waitcnt lgkmcnt(" #n ")" ::: "memory")
; #define PG8_BAR __builtin_amdgcn_s_barrier()
; #define PG8_SCHED __builtin_amdgcn_sched_barrier(0)
;     ...
;             if (!fin) PG8_WAIT_V(8); else PG8_WAIT_V(0); PG8_WAIT_L(0); PG8_BAR; PG8_MMA(0, 0, At, B0); PG8_MMA(0, 1, At, B1); PG8_BAR; PG8_SCHED;
;             PG8_LDA(At, 1, 1); if (!fin) { PG8_STAGE(PG8_SB(1, 0), b3, voffB); PG8_STAGE(PG8_SB(1, 1), b3 + hstep, voffB); PG8_STAGE(PG8_SA(1, 0), a3, voffA); }
;             if (!fin) PG8_WAIT_V(8); PG8_WAIT_L(0); PG8_BAR; PG8_MMA(1, 0, At, B0); PG8_MMA(1, 1, At, B1); PG8_BAR; PG8_SCHED;
;     ...
;         if constexpr (ALIGN_EPI) { if (wr == 0) PG8_BAR; }
.LBB0_886:
	s_waitcnt lgkmcnt(0)
	s_barrier
	v_mfma_f32_16x16x32_f16 v[2:5], v[170:173], v[162:165], v[2:5]
	s_setprio 1
	v_mfma_f32_16x16x32_f16 v[186:189], v[174:177], v[206:209], v[2:5]
	v_mfma_f32_16x16x32_f16 v[2:5], v[178:181], v[162:165], v[6:9]
	v_mfma_f32_16x16x32_f16 v[190:193], v[182:185], v[206:209], v[2:5]
	v_mfma_f32_16x16x32_f16 v[2:5], v[170:173], v[166:169], v[10:13]
	v_mfma_f32_16x16x32_f16 v[138:141], v[174:177], v[218:221], v[2:5]
	v_mfma_f32_16x16x32_f16 v[2:5], v[178:181], v[166:169], v[14:17]
	v_mfma_f32_16x16x32_f16 v[142:145], v[182:185], v[218:221], v[2:5]
	v_mfma_f32_16x16x32_f16 v[2:5], v[170:173], v[210:213], v[18:21]
	v_mfma_f32_16x16x32_f16 v[34:37], v[174:177], v[214:217], v[2:5]
	v_mfma_f32_16x16x32_f16 v[2:5], v[178:181], v[210:213], v[22:25]
	v_mfma_f32_16x16x32_f16 v[38:41], v[182:185], v[214:217], v[2:5]
	v_mfma_f32_16x16x32_f16 v[2:5], v[170:173], v[194:197], v[26:29]
	v_mfma_f32_16x16x32_f16 v[2:5], v[174:177], v[198:201], v[2:5]
	v_mfma_f32_16x16x32_f16 v[6:9], v[178:181], v[194:197], v[30:33]
	v_mfma_f32_16x16x32_f16 v[6:9], v[182:185], v[198:201], v[6:9]
	v_mfma_f32_16x16x32_f16 v[10:13], v[146:149], v[162:165], v[42:45]
	v_mfma_f32_16x16x32_f16 v[202:205], v[150:153], v[206:209], v[10:13]
	v_mfma_f32_16x16x32_f16 v[10:13], v[154:157], v[162:165], v[46:49]
	v_mfma_f32_16x16x32_f16 v[206:209], v[158:161], v[206:209], v[10:13]
	v_mfma_f32_16x16x32_f16 v[10:13], v[146:149], v[166:169], v[50:53]
	v_mfma_f32_16x16x32_f16 v[162:165], v[150:153], v[218:221], v[10:13]
	v_mfma_f32_16x16x32_f16 v[10:13], v[154:157], v[166:169], v[54:57]
	v_mfma_f32_16x16x32_f16 v[166:169], v[158:161], v[218:221], v[10:13]
	v_mfma_f32_16x16x32_f16 v[10:13], v[146:149], v[210:213], v[58:61]
	v_mfma_f32_16x16x32_f16 v[50:53], v[150:153], v[214:217], v[10:13]
	s_barrier
	v_mfma_f32_16x16x32_f16 v[10:13], v[154:157], v[210:213], v[62:65]
	v_mfma_f32_16x16x32_f16 v[54:57], v[158:161], v[214:217], v[10:13]
	v_mfma_f32_16x16x32_f16 v[10:13], v[146:149], v[194:197], v[66:69]
	v_mfma_f32_16x16x32_f16 v[18:21], v[150:153], v[198:201], v[10:13]
	v_mfma_f32_16x16x32_f16 v[10:13], v[154:157], v[194:197], v[70:73]
	v_mfma_f32_16x16x32_f16 v[22:25], v[158:161], v[198:201], v[10:13]
	s_setprio 0
	ds_read_b128 v[218:221], v235 offset:49152
	ds_read_b128 v[222:225], v235 offset:50176
	ds_read_b128 v[58:61], v235 offset:51200
	ds_read_b128 v[214:217], v235 offset:52224
	ds_read_b128 v[26:29], v235 offset:53248
	ds_read_b128 v[62:65], v235 offset:54272
	ds_read_b128 v[30:33], v235 offset:55296
	ds_read_b128 v[210:213], v235 offset:56320
	v_cndmask_b32_e64 v10, 0, 1, s[2:3]
	v_cmp_ne_u32_e64 s[4:5], 1, v10
	s_andn2_b64 vcc, exec, s[2:3]
	s_cbranch_vccnz .LBB0_888
	s_and_b64 s[2:3], s[2:3], exec
	s_cselect_b32 s2, s48, s52
	s_cselect_b32 s3, s49, s53
	s_cselect_b32 s9, s51, s55
	s_cselect_b32 s8, s50, s54
	s_add_u32 s2, s2, 0x80
	s_addc_u32 s3, s3, 0
	s_add_u32 s8, s8, 0x80
	s_addc_u32 s9, s9, 0
	s_add_u32 m0, s14, 0x18000
	s_nop 0
	global_load_lds_dwordx4 v231, s[8:9]
	s_nop 0
	s_add_u32 m0, s14, 0x1a000
	s_nop 0
	global_load_lds_dwordx4 v233, s[8:9]
	s_add_u32 s8, s50, 0x10080
	s_addc_u32 s9, s51, 0
	s_add_u32 m0, s14, 0x1c000
	s_nop 0
	global_load_lds_dwordx4 v231, s[8:9]
	s_nop 0
	s_add_u32 m0, s14, 0x1e000
	s_nop 0
	global_load_lds_dwordx4 v233, s[8:9]
	s_nop 0
	s_add_u32 m0, s14, 0x8000
	s_nop 0
	global_load_lds_dwordx4 v230, s[2:3]
	s_nop 0
	s_add_u32 m0, s14, 0xa000
	s_nop 0
	global_load_lds_dwordx4 v232, s[2:3]
	s_waitcnt vmcnt(8)
.LBB0_888:
	s_waitcnt lgkmcnt(0)
	s_barrier
	v_mfma_f32_16x16x32_f16 v[10:13], v[170:173], v[218:221], v[74:77]
	s_setprio 1
	v_mfma_f32_16x16x32_f16 v[194:197], v[174:177], v[222:225], v[10:13]
	v_mfma_f32_16x16x32_f16 v[10:13], v[178:181], v[218:221], v[78:81]
	v_mfma_f32_16x16x32_f16 v[198:201], v[182:185], v[222:225], v[10:13]
	v_mfma_f32_16x16x32_f16 v[10:13], v[170:173], v[58:61], v[82:85]
	v_mfma_f32_16x16x32_f16 v[66:69], v[174:177], v[214:217], v[10:13]
	v_mfma_f32_16x16x32_f16 v[10:13], v[178:181], v[58:61], v[86:89]
	v_mfma_f32_16x16x32_f16 v[70:73], v[182:185], v[214:217], v[10:13]
	v_mfma_f32_16x16x32_f16 v[10:13], v[170:173], v[26:29], v[90:93]
	v_mfma_f32_16x16x32_f16 v[42:45], v[174:177], v[62:65], v[10:13]
	v_mfma_f32_16x16x32_f16 v[10:13], v[178:181], v[26:29], v[94:97]
	v_mfma_f32_16x16x32_f16 v[46:49], v[182:185], v[62:65], v[10:13]
	v_mfma_f32_16x16x32_f16 v[10:13], v[170:173], v[30:33], v[98:101]
	v_mfma_f32_16x16x32_f16 v[10:13], v[174:177], v[210:213], v[10:13]
	v_mfma_f32_16x16x32_f16 v[14:17], v[178:181], v[30:33], v[102:105]
	v_mfma_f32_16x16x32_f16 v[14:17], v[182:185], v[210:213], v[14:17]
	v_mfma_f32_16x16x32_f16 v[74:77], v[146:149], v[218:221], v[106:109]
	v_mfma_f32_16x16x32_f16 v[82:85], v[150:153], v[222:225], v[74:77]
	v_mfma_f32_16x16x32_f16 v[74:77], v[154:157], v[218:221], v[110:113]
	v_mfma_f32_16x16x32_f16 v[86:89], v[158:161], v[222:225], v[74:77]
	v_mfma_f32_16x16x32_f16 v[74:77], v[146:149], v[58:61], v[114:117]
	v_mfma_f32_16x16x32_f16 v[74:77], v[150:153], v[214:217], v[74:77]
	v_mfma_f32_16x16x32_f16 v[58:61], v[154:157], v[58:61], v[118:121]
	v_mfma_f32_16x16x32_f16 v[78:81], v[158:161], v[214:217], v[58:61]
	v_mfma_f32_16x16x32_f16 v[58:61], v[146:149], v[26:29], v[122:125]
	v_mfma_f32_16x16x32_f16 v[58:61], v[150:153], v[62:65], v[58:61]
	s_barrier
	v_mfma_f32_16x16x32_f16 v[26:29], v[154:157], v[26:29], v[126:129]
	v_mfma_f32_16x16x32_f16 v[62:65], v[158:161], v[62:65], v[26:29]
	v_mfma_f32_16x16x32_f16 v[26:29], v[146:149], v[30:33], v[130:133]
	v_mfma_f32_16x16x32_f16 v[26:29], v[150:153], v[210:213], v[26:29]
	v_mfma_f32_16x16x32_f16 v[30:33], v[154:157], v[30:33], v[134:137]
	v_mfma_f32_16x16x32_f16 v[30:33], v[158:161], v[210:213], v[30:33]
	s_setprio 0
	s_andn2_b64 vcc, exec, s[6:7]
	s_cbranch_vccnz .LBB0_890
	s_barrier

; #define PG8_STAGE(bufoff, gbase, voff) do { if constexpr (ABL & 1) break; glds16s<(bufoff)>((voff)[0], (const void*)(gbase), ldsbw); glds16s<(bufoff) + 8192>((voff)[1], (const void*)(gbase), ldsbw); } while (0)
; #define PG8_LDA(dst, b, h) do { if constexpr (ABL & 4) break; _Pragma("unroll") for (int m = 0; m < 4; ++m) _Pragma("unroll") for (int k = 0; k < 2; ++k) dst[m][k] = *(const LAS f16x8*)(lds + PG8_SA(b, h) + aoff + m * 2048 + k * 1024); } while (0)
; #define PG8_LDB(dst, b, h) do { if constexpr (ABL & 4) break; _Pragma("unroll") for (int n = 0; n < 2; ++n) _Pragma("unroll") for (int k = 0; k < 2; ++k) dst[n][k] = *(const LAS f16x8*)(lds + PG8_SB(b, h) + boff + n * 2048 + k * 1024); } while (0)
; #define PG8_MMAF(ai, bj, At, Bt) do { if (t == 0) PG8_MMA0(ai, bj, At, Bt); else PG8_MMA(ai, bj, At, Bt); } while (0)
; #define PG8_WAIT_V(n) asm volatile("s_waitcnt vmcnt(" #n ")" ::: "memory")
; #define PG8_WAIT_L(n) asm volatile("s_waitcnt lgkmcnt(" #n ")" ::: "memory")
; #define PG8_BAR __builtin_amdgcn_s_barrier()
; #define PG8_SCHED __builtin_amdgcn_sched_barrier(0)
;     ...
;         const char* nA = has_next ? (const char*)g.A + (size_t)nxt.pm * tstep : cA; const char* nB = has_next ? (const char*)g.Bt + (size_t)nxt.pn * tstep : cB;
;         for (int t = 0; t < nt; t += 2) {
;             const bool last = (t == nt - 2);
;             const char* a1 = cA + (size_t)(t + 1) * kstep;
;             const char* a2 = last ? nA : cA + (size_t)(t + 2) * kstep; const char* b2 = last ? nB : cB + (size_t)(t + 2) * kstep;
;             const char* a3 = a2 + kstep; const char* b3 = b2 + kstep;
;             if (last && has_next) S.a_ready(nxt);
;             if constexpr (SP2) {
;             PG8_LDB(B0, 0, 0); PG8_LDB(B1, 0, 1); PG8_SCHED; PG8_LDA(At, 0, 0); PG8_STAGE(PG8_SA(1, 1), a1 + hstep, voffA);
;             PG8_WAIT_V(8); PG8_WAIT_L(0); PG8_BAR; PG8_MMAF(0, 0, At, B0); PG8_MMAF(0, 1, At, B1); PG8_BAR; PG8_SCHED;
;             const bool fin = last && !has_next;
;             PG8_LDA(At, 0, 1); if (!fin) { PG8_STAGE(PG8_SB(0, 0), b2, voffB); PG8_STAGE(PG8_SB(0, 1), b2 + hstep, voffB); PG8_STAGE(PG8_SA(0, 0), a2, voffA); }
;             if (!fin) PG8_WAIT_V(8); else PG8_WAIT_V(2); PG8_WAIT_L(0); PG8_BAR; PG8_MMAF(1, 0, At, B0); PG8_MMAF(1, 1, At, B1); PG8_BAR; PG8_SCHED;
.LBB0_987:
	s_waitcnt lgkmcnt(0)
	ds_read_b128 v[2:5], v213
	ds_read_b128 v[6:9], v213 offset:1024
	ds_read_b128 v[10:13], v213 offset:2048
	ds_read_b128 v[14:17], v213 offset:3072
	ds_read_b128 v[18:21], v214
	ds_read_b128 v[22:25], v214 offset:1024
	ds_read_b128 v[26:29], v214 offset:2048
	ds_read_b128 v[30:33], v214 offset:3072
	s_add_u32 s50, s54, 0x100
	s_addc_u32 s51, s55, 0
	s_add_u32 s24, s52, 0x100
	s_addc_u32 s25, s53, 0
	s_add_u32 s6, s54, 0x180
	s_addc_u32 s7, s55, 0
	ds_read_b128 v[34:37], v215
	ds_read_b128 v[38:41], v215 offset:1024
	ds_read_b128 v[42:45], v215 offset:2048
	ds_read_b128 v[46:49], v215 offset:3072
	ds_read_b128 v[50:53], v215 offset:4096
	ds_read_b128 v[54:57], v215 offset:5120
	ds_read_b128 v[58:61], v215 offset:6144
	ds_read_b128 v[62:65], v215 offset:7168
	s_add_u32 s8, s52, 0x180
	s_addc_u32 s9, s53, 0
	s_add_u32 s26, s54, 0xb0080
	s_addc_u32 s27, s55, 0
	s_add_u32 m0, s28, 0xc000
	s_nop 0
	global_load_lds_dwordx4 v1, s[26:27]
	s_nop 0
	s_add_u32 m0, s28, 0xe000
	s_nop 0
	global_load_lds_dwordx4 v211, s[26:27]
	s_waitcnt vmcnt(8)
	s_waitcnt lgkmcnt(0)
	s_barrier
	v_mfma_f32_16x16x32_f16 v[70:73], v[10:13], v[34:37], 0
	s_setprio 1
	v_mfma_f32_16x16x32_f16 v[70:73], v[14:17], v[38:41], v[70:73]
	v_mfma_f32_16x16x32_f16 v[74:77], v[2:5], v[42:45], 0
	v_mfma_f32_16x16x32_f16 v[74:77], v[6:9], v[46:49], v[74:77]
	v_mfma_f32_16x16x32_f16 v[82:85], v[2:5], v[50:53], 0
	v_mfma_f32_16x16x32_f16 v[82:85], v[6:9], v[54:57], v[82:85]
	v_mfma_f32_16x16x32_f16 v[86:89], v[10:13], v[50:53], 0
	v_mfma_f32_16x16x32_f16 v[86:89], v[14:17], v[54:57], v[86:89]
	v_mfma_f32_16x16x32_f16 v[94:97], v[10:13], v[58:61], 0
	v_mfma_f32_16x16x32_f16 v[94:97], v[14:17], v[62:65], v[94:97]
	v_mfma_f32_16x16x32_f16 v[66:69], v[2:5], v[34:37], 0
	v_mfma_f32_16x16x32_f16 v[66:69], v[6:9], v[38:41], v[66:69]
	v_mfma_f32_16x16x32_f16 v[78:81], v[10:13], v[42:45], 0
	v_mfma_f32_16x16x32_f16 v[78:81], v[14:17], v[46:49], v[78:81]
	v_mfma_f32_16x16x32_f16 v[90:93], v[2:5], v[58:61], 0
	v_mfma_f32_16x16x32_f16 v[90:93], v[6:9], v[62:65], v[90:93]
	v_mfma_f32_16x16x32_f16 v[98:101], v[18:21], v[34:37], 0
	v_mfma_f32_16x16x32_f16 v[98:101], v[22:25], v[38:41], v[98:101]
	v_mfma_f32_16x16x32_f16 v[34:37], v[26:29], v[34:37], 0
	v_mfma_f32_16x16x32_f16 v[34:37], v[30:33], v[38:41], v[34:37]
	v_mfma_f32_16x16x32_f16 v[38:41], v[18:21], v[42:45], 0
	v_mfma_f32_16x16x32_f16 v[38:41], v[22:25], v[46:49], v[38:41]
	v_mfma_f32_16x16x32_f16 v[42:45], v[26:29], v[42:45], 0
	v_mfma_f32_16x16x32_f16 v[42:45], v[30:33], v[46:49], v[42:45]
	v_mfma_f32_16x16x32_f16 v[46:49], v[18:21], v[50:53], 0
	v_mfma_f32_16x16x32_f16 v[46:49], v[22:25], v[54:57], v[46:49]
	s_barrier
	v_mfma_f32_16x16x32_f16 v[50:53], v[26:29], v[50:53], 0
	v_mfma_f32_16x16x32_f16 v[50:53], v[30:33], v[54:57], v[50:53]
	v_mfma_f32_16x16x32_f16 v[54:57], v[18:21], v[58:61], 0
	v_mfma_f32_16x16x32_f16 v[54:57], v[22:25], v[62:65], v[54:57]
	v_mfma_f32_16x16x32_f16 v[58:61], v[26:29], v[58:61], 0
	v_mfma_f32_16x16x32_f16 v[58:61], v[30:33], v[62:65], v[58:61]
	s_setprio 0
	ds_read_b128 v[62:65], v215 offset:16384
	ds_read_b128 v[102:105], v215 offset:17408
	ds_read_b128 v[106:109], v215 offset:18432
	ds_read_b128 v[110:113], v215 offset:19456
	ds_read_b128 v[114:117], v215 offset:20480
	ds_read_b128 v[118:121], v215 offset:21504
	ds_read_b128 v[122:125], v215 offset:22528
	ds_read_b128 v[126:129], v215 offset:23552
	s_add_u32 m0, s28, 0x10000
	s_nop 0
	global_load_lds_dwordx4 v210, s[24:25]
	s_nop 0
	s_add_u32 m0, s28, 0x12000
	s_nop 0
	global_load_lds_dwordx4 v212, s[24:25]
	s_add_u32 s24, s52, 0xb0100
	s_addc_u32 s25, s53, 0
	s_add_u32 m0, s28, 0x14000
	s_nop 0
	global_load_lds_dwordx4 v210, s[24:25]
	s_nop 0
	s_add_u32 m0, s28, 0x16000
	s_nop 0
	global_load_lds_dwordx4 v212, s[24:25]
	s_nop 0
	s_add_u32 m0, s28, 0
	s_nop 0
	global_load_lds_dwordx4 v1, s[50:51]
	s_nop 0
	s_add_u32 m0, s28, 0x2000
	s_nop 0
	global_load_lds_dwordx4 v211, s[50:51]
	s_waitcnt vmcnt(8)
	s_waitcnt lgkmcnt(0)
	s_barrier
	v_mfma_f32_16x16x32_f16 v[130:133], v[2:5], v[62:65], 0
	s_setprio 1
	v_mfma_f32_16x16x32_f16 v[138:141], v[6:9], v[102:105], v[130:133]
	v_mfma_f32_16x16x32_f16 v[130:133], v[10:13], v[62:65], 0
	v_mfma_f32_16x16x32_f16 v[158:161], v[14:17], v[102:105], v[130:133]
	v_mfma_f32_16x16x32_f16 v[130:133], v[2:5], v[106:109], 0
	v_mfma_f32_16x16x32_f16 v[162:165], v[6:9], v[110:113], v[130:133]
	v_mfma_f32_16x16x32_f16 v[130:133], v[10:13], v[106:109], 0
	v_mfma_f32_16x16x32_f16 v[166:169], v[14:17], v[110:113], v[130:133]
	v_mfma_f32_16x16x32_f16 v[130:133], v[2:5], v[114:117], 0
	v_mfma_f32_16x16x32_f16 v[170:173], v[6:9], v[118:121], v[130:133]
	v_mfma_f32_16x16x32_f16 v[2:5], v[2:5], v[122:125], 0
	v_mfma_f32_16x16x32_f16 v[2:5], v[6:9], v[126:129], v[2:5]
	v_mfma_f32_16x16x32_f16 v[6:9], v[10:13], v[122:125], 0
	v_mfma_f32_16x16x32_f16 v[6:9], v[14:17], v[126:129], v[6:9]
	v_mfma_f32_16x16x32_f16 v[130:133], v[10:13], v[114:117], 0
	v_mfma_f32_16x16x32_f16 v[174:177], v[14:17], v[118:121], v[130:133]
	v_mfma_f32_16x16x32_f16 v[10:13], v[18:21], v[62:65], 0
	v_mfma_f32_16x16x32_f16 v[178:181], v[22:25], v[102:105], v[10:13]
	v_mfma_f32_16x16x32_f16 v[10:13], v[26:29], v[62:65], 0
	v_mfma_f32_16x16x32_f16 v[102:105], v[30:33], v[102:105], v[10:13]
	v_mfma_f32_16x16x32_f16 v[10:13], v[18:21], v[106:109], 0
	v_mfma_f32_16x16x32_f16 v[182:185], v[22:25], v[110:113], v[10:13]
	v_mfma_f32_16x16x32_f16 v[10:13], v[26:29], v[106:109], 0
	v_mfma_f32_16x16x32_f16 v[186:189], v[30:33], v[110:113], v[10:13]
	v_mfma_f32_16x16x32_f16 v[10:13], v[18:21], v[114:117], 0
	v_mfma_f32_16x16x32_f16 v[190:193], v[22:25], v[118:121], v[10:13]
	s_barrier
; #define PG8_STAGE(bufoff, gbase, voff) do { if constexpr (ABL & 1) break; glds16s<(bufoff)>((voff)[0], (const void*)(gbase), ldsbw); glds16s<(bufoff) + 8192>((voff)[1], (const void*)(gbase), ldsbw); } while (0)
; #define PG8_LDA(dst, b, h) do { if constexpr (ABL & 4) break; _Pragma("unroll") for (int m = 0; m < 4; ++m) _Pragma("unroll") for (int k = 0; k < 2; ++k) dst[m][k] = *(const LAS f16x8*)(lds + PG8_SA(b, h) + aoff + m * 2048 + k * 1024); } while (0)
; #define PG8_LDB(dst, b, h) do { if constexpr (ABL & 4) break; _Pragma("unroll") for (int n = 0; n < 2; ++n) _Pragma("unroll") for (int k = 0; k < 2; ++k) dst[n][k] = *(const LAS f16x8*)(lds + PG8_SB(b, h) + boff + n * 2048 + k * 1024); } while (0)
; #define PG8_MMA(ai, bj, At, Bt) do { if constexpr (ABL & 2) break; __builtin_amdgcn_s_setprio(1); _Pragma("unroll") for (int m = 0; m < 4; ++m) _Pragma("unroll") for (int n = 0; n < 2; ++n) _Pragma("unroll") for (int k = 0; k < 2; ++k) \
;         acc[ai][bj][m][n] = __builtin_amdgcn_mfma_f32_16x16x32_f16(Bt[n][k], At[m][k], acc[ai][bj][m][n], 0, 0, 0); __builtin_amdgcn_s_setprio(0); } while (0)
; #define PG8_MMAF(ai, bj, At, Bt) do { if (t == 0) PG8_MMA0(ai, bj, At, Bt); else PG8_MMA(ai, bj, At, Bt); } while (0)
; #define PG8_WAIT_V(n) asm volatile("s_waitcnt vmcnt(" #n ")" ::: "memory")
; #define PG8_WAIT_L(n) asm volatile("s_waitcnt lgkmcnt(" #n ")" ::: "memory")
; #define PG8_BAR __builtin_amdgcn_s_barrier()
; #define PG8_SCHED __builtin_amdgcn_sched_barrier(0)
;     ...
;             if (!fin) PG8_WAIT_V(8); else PG8_WAIT_V(2); PG8_WAIT_L(0); PG8_BAR; PG8_MMAF(1, 0, At, B0); PG8_MMAF(1, 1, At, B1); PG8_BAR; PG8_SCHED;
;             PG8_LDB(B0, 1, 0); PG8_LDB(B1, 1, 1); PG8_SCHED; PG8_LDA(At, 1, 0); if (!fin) PG8_STAGE(PG8_SA(0, 1), a2 + hstep, voffA);
;             if (!fin) PG8_WAIT_V(8); else PG8_WAIT_V(0); PG8_WAIT_L(0); PG8_BAR; PG8_MMA(0, 0, At, B0); PG8_MMA(0, 1, At, B1); PG8_BAR; PG8_SCHED;
;             PG8_LDA(At, 1, 1); if (!fin) { PG8_STAGE(PG8_SB(1, 0), b3, voffB); PG8_STAGE(PG8_SB(1, 1), b3 + hstep, voffB); PG8_STAGE(PG8_SA(1, 0), a3, voffA); }
;             if (!fin) PG8_WAIT_V(8); PG8_WAIT_L(0); PG8_BAR; PG8_MMA(1, 0, At, B0); PG8_MMA(1, 1, At, B1); PG8_BAR; PG8_SCHED;
	v_mfma_f32_16x16x32_f16 v[10:13], v[26:29], v[114:117], 0
	v_mfma_f32_16x16x32_f16 v[114:117], v[30:33], v[118:121], v[10:13]
	v_mfma_f32_16x16x32_f16 v[10:13], v[18:21], v[122:125], 0
	v_mfma_f32_16x16x32_f16 v[194:197], v[22:25], v[126:129], v[10:13]
	v_mfma_f32_16x16x32_f16 v[10:13], v[26:29], v[122:125], 0
	v_mfma_f32_16x16x32_f16 v[126:129], v[30:33], v[126:129], v[10:13]
	s_setprio 0
	s_nop 4
	ds_read_b128 v[10:13], v216
	ds_read_b128 v[14:17], v216 offset:1024
	ds_read_b128 v[18:21], v216 offset:2048
	ds_read_b128 v[22:25], v216 offset:3072
	ds_read_b128 v[198:201], v217
	ds_read_b128 v[202:205], v217 offset:1024
	ds_read_b128 v[220:223], v217 offset:2048
	ds_read_b128 v[224:227], v217 offset:3072
	ds_read_b128 v[26:29], v215 offset:32768
	ds_read_b128 v[30:33], v215 offset:33792
	ds_read_b128 v[62:65], v215 offset:34816
	ds_read_b128 v[118:121], v215 offset:35840
	ds_read_b128 v[228:231], v215 offset:36864
	ds_read_b128 v[232:235], v215 offset:37888
	ds_read_b128 v[236:239], v215 offset:38912
	ds_read_b128 v[240:243], v215 offset:39936
	s_add_u32 s24, s54, 0xb0100
	s_addc_u32 s25, s55, 0
	s_add_u32 m0, s28, 0x4000
	s_nop 0
	global_load_lds_dwordx4 v1, s[24:25]
	s_nop 0
	s_add_u32 m0, s28, 0x6000
	s_nop 0
	global_load_lds_dwordx4 v211, s[24:25]
	s_waitcnt vmcnt(8)
	s_waitcnt lgkmcnt(0)
	s_barrier
	v_mfma_f32_16x16x32_f16 v[66:69], v[10:13], v[26:29], v[66:69]
	s_setprio 1
	v_mfma_f32_16x16x32_f16 v[154:157], v[14:17], v[30:33], v[66:69]
	v_mfma_f32_16x16x32_f16 v[66:69], v[18:21], v[26:29], v[70:73]
	v_mfma_f32_16x16x32_f16 v[150:153], v[22:25], v[30:33], v[66:69]
	v_mfma_f32_16x16x32_f16 v[66:69], v[10:13], v[62:65], v[74:77]
	v_mfma_f32_16x16x32_f16 v[134:137], v[14:17], v[118:121], v[66:69]
	v_mfma_f32_16x16x32_f16 v[66:69], v[18:21], v[62:65], v[78:81]
	v_mfma_f32_16x16x32_f16 v[130:133], v[22:25], v[118:121], v[66:69]
	v_mfma_f32_16x16x32_f16 v[66:69], v[10:13], v[228:231], v[82:85]
	v_mfma_f32_16x16x32_f16 v[110:113], v[14:17], v[232:235], v[66:69]
	v_mfma_f32_16x16x32_f16 v[66:69], v[18:21], v[228:231], v[86:89]
	v_mfma_f32_16x16x32_f16 v[106:109], v[22:25], v[232:235], v[66:69]
	v_mfma_f32_16x16x32_f16 v[66:69], v[10:13], v[236:239], v[90:93]
	v_mfma_f32_16x16x32_f16 v[86:89], v[14:17], v[240:243], v[66:69]
	v_mfma_f32_16x16x32_f16 v[66:69], v[18:21], v[236:239], v[94:97]
	v_mfma_f32_16x16x32_f16 v[82:85], v[22:25], v[240:243], v[66:69]
	v_mfma_f32_16x16x32_f16 v[66:69], v[198:201], v[26:29], v[98:101]
	v_mfma_f32_16x16x32_f16 v[146:149], v[202:205], v[30:33], v[66:69]
	v_mfma_f32_16x16x32_f16 v[26:29], v[220:223], v[26:29], v[34:37]
	v_mfma_f32_16x16x32_f16 v[142:145], v[224:227], v[30:33], v[26:29]
	v_mfma_f32_16x16x32_f16 v[26:29], v[198:201], v[62:65], v[38:41]
	v_mfma_f32_16x16x32_f16 v[122:125], v[202:205], v[118:121], v[26:29]
	v_mfma_f32_16x16x32_f16 v[26:29], v[220:223], v[62:65], v[42:45]
	v_mfma_f32_16x16x32_f16 v[118:121], v[224:227], v[118:121], v[26:29]
	v_mfma_f32_16x16x32_f16 v[26:29], v[198:201], v[228:231], v[46:49]
	v_mfma_f32_16x16x32_f16 v[98:101], v[202:205], v[232:235], v[26:29]
	s_barrier
	v_mfma_f32_16x16x32_f16 v[26:29], v[220:223], v[228:231], v[50:53]
	v_mfma_f32_16x16x32_f16 v[94:97], v[224:227], v[232:235], v[26:29]
	v_mfma_f32_16x16x32_f16 v[26:29], v[198:201], v[236:239], v[54:57]
	v_mfma_f32_16x16x32_f16 v[74:77], v[202:205], v[240:243], v[26:29]
	v_mfma_f32_16x16x32_f16 v[26:29], v[220:223], v[236:239], v[58:61]
	v_mfma_f32_16x16x32_f16 v[70:73], v[224:227], v[240:243], v[26:29]
	s_setprio 0
	ds_read_b128 v[34:37], v215 offset:49152
	ds_read_b128 v[38:41], v215 offset:50176
	ds_read_b128 v[66:69], v215 offset:51200
	ds_read_b128 v[78:81], v215 offset:52224
	ds_read_b128 v[90:93], v215 offset:53248
	ds_read_b128 v[228:231], v215 offset:54272
	ds_read_b128 v[232:235], v215 offset:55296
	ds_read_b128 v[236:239], v215 offset:56320
	s_add_u32 m0, s28, 0x18000
	s_nop 0
	global_load_lds_dwordx4 v210, s[8:9]
	s_nop 0
	s_add_u32 m0, s28, 0x1a000
	s_nop 0
	global_load_lds_dwordx4 v212, s[8:9]
	s_add_u32 s8, s52, 0xb0180
	s_addc_u32 s9, s53, 0
	s_add_u32 m0, s28, 0x1c000
	s_nop 0
	global_load_lds_dwordx4 v210, s[8:9]
	s_nop 0
	s_add_u32 m0, s28, 0x1e000
	s_nop 0
	global_load_lds_dwordx4 v212, s[8:9]
	s_nop 0
	s_add_u32 m0, s28, 0x8000
	s_nop 0
	global_load_lds_dwordx4 v1, s[6:7]
	s_nop 0
	s_add_u32 m0, s28, 0xa000
	s_nop 0
	global_load_lds_dwordx4 v211, s[6:7]
	s_waitcnt vmcnt(8)
	s_waitcnt lgkmcnt(0)
	s_barrier
	v_mfma_f32_16x16x32_f16 v[26:29], v[10:13], v[34:37], v[138:141]
	s_setprio 1
	v_mfma_f32_16x16x32_f16 v[62:65], v[14:17], v[38:41], v[26:29]
	v_mfma_f32_16x16x32_f16 v[26:29], v[22:25], v[38:41], v[158:161]
	v_mfma_f32_16x16x32_f16 v[58:61], v[18:21], v[34:37], v[26:29]
	v_mfma_f32_16x16x32_f16 v[26:29], v[10:13], v[66:69], v[162:165]
	v_mfma_f32_16x16x32_f16 v[46:49], v[14:17], v[78:81], v[26:29]
	v_mfma_f32_16x16x32_f16 v[26:29], v[22:25], v[78:81], v[166:169]
	v_mfma_f32_16x16x32_f16 v[42:45], v[18:21], v[66:69], v[26:29]
	v_mfma_f32_16x16x32_f16 v[26:29], v[10:13], v[90:93], v[170:173]
	v_mfma_f32_16x16x32_f16 v[30:33], v[14:17], v[228:231], v[26:29]
	v_mfma_f32_16x16x32_f16 v[2:5], v[14:17], v[236:239], v[2:5]
	v_mfma_f32_16x16x32_f16 v[14:17], v[10:13], v[232:235], v[2:5]
	v_mfma_f32_16x16x32_f16 v[2:5], v[18:21], v[232:235], v[6:9]
	v_mfma_f32_16x16x32_f16 v[10:13], v[22:25], v[236:239], v[2:5]
	v_mfma_f32_16x16x32_f16 v[26:29], v[22:25], v[228:231], v[174:177]
	v_mfma_f32_16x16x32_f16 v[26:29], v[18:21], v[90:93], v[26:29]
	v_mfma_f32_16x16x32_f16 v[2:5], v[198:201], v[34:37], v[178:181]
	v_mfma_f32_16x16x32_f16 v[54:57], v[202:205], v[38:41], v[2:5]
	v_mfma_f32_16x16x32_f16 v[2:5], v[224:227], v[38:41], v[102:105]
	v_mfma_f32_16x16x32_f16 v[50:53], v[220:223], v[34:37], v[2:5]
	v_mfma_f32_16x16x32_f16 v[2:5], v[198:201], v[66:69], v[182:185]
	v_mfma_f32_16x16x32_f16 v[38:41], v[202:205], v[78:81], v[2:5]
	v_mfma_f32_16x16x32_f16 v[2:5], v[224:227], v[78:81], v[186:189]
	v_mfma_f32_16x16x32_f16 v[34:37], v[220:223], v[66:69], v[2:5]
	v_mfma_f32_16x16x32_f16 v[2:5], v[198:201], v[90:93], v[190:193]
	v_mfma_f32_16x16x32_f16 v[22:25], v[202:205], v[228:231], v[2:5]
	s_barrier
	v_mfma_f32_16x16x32_f16 v[2:5], v[224:227], v[228:231], v[114:117]
	v_mfma_f32_16x16x32_f16 v[18:21], v[220:223], v[90:93], v[2:5]
	v_mfma_f32_16x16x32_f16 v[2:5], v[198:201], v[232:235], v[194:197]
	v_mfma_f32_16x16x32_f16 v[6:9], v[202:205], v[236:239], v[2:5]
	v_mfma_f32_16x16x32_f16 v[2:5], v[224:227], v[236:239], v[126:129]
	v_mfma_f32_16x16x32_f16 v[2:5], v[220:223], v[232:235], v[2:5]
	s_setprio 0
	s_add_u32 s52, s52, 0x200
	s_addc_u32 s53, s53, 0
	s_mov_b32 s54, 0
	s_branch .LBB0_989
; #define PG8_STAGE(bufoff, gbase, voff) do { if constexpr (ABL & 1) break; glds16s<(bufoff)>((voff)[0], (const void*)(gbase), ldsbw); glds16s<(bufoff) + 8192>((voff)[1], (const void*)(gbase), ldsbw); } while (0)
; #define PG8_LDA(dst, b, h) do { if constexpr (ABL & 4) break; _Pragma("unroll") for (int m = 0; m < 4; ++m) _Pragma("unroll") for (int k = 0; k < 2; ++k) dst[m][k] = *(const LAS f16x8*)(lds + PG8_SA(b, h) + aoff + m * 2048 + k * 1024); } while (0)
; #define PG8_LDB(dst, b, h) do { if constexpr (ABL & 4) break; _Pragma("unroll") for (int n = 0; n < 2; ++n) _Pragma("unroll") for (int k = 0; k < 2; ++k) dst[n][k] = *(const LAS f16x8*)(lds + PG8_SB(b, h) + boff + n * 2048 + k * 1024); } while (0)
; #define PG8_MMA(ai, bj, At, Bt) do { if constexpr (ABL & 2) break; __builtin_amdgcn_s_setprio(1); _Pragma("unroll") for (int m = 0; m < 4; ++m) _Pragma("unroll") for (int n = 0; n < 2; ++n) _Pragma("unroll") for (int k = 0; k < 2; ++k) \
;         acc[ai][bj][m][n] = __builtin_amdgcn_mfma_f32_16x16x32_f16(Bt[n][k], At[m][k], acc[ai][bj][m][n], 0, 0, 0); __builtin_amdgcn_s_setprio(0); } while (0)
; #define PG8_WAIT_V(n) asm volatile("s_waitcnt vmcnt(" #n ")" ::: "memory")
;     ...
;             PG8_LDB(B0, 0, 0); PG8_LDB(B1, 0, 1); PG8_SCHED; PG8_LDA(At, 0, 0); PG8_STAGE(PG8_SA(1, 1), a1 + hstep, voffA);
;             PG8_WAIT_V(8); PG8_WAIT_L(0); PG8_BAR; PG8_MMAF(0, 0, At, B0); PG8_MMAF(0, 1, At, B1); PG8_BAR; PG8_SCHED;
;             const bool fin = last && !has_next;
;             PG8_LDA(At, 0, 1); if (!fin) { PG8_STAGE(PG8_SB(0, 0), b2, voffB); PG8_STAGE(PG8_SB(0, 1), b2 + hstep, voffB); PG8_STAGE(PG8_SA(0, 0), a2, voffA); }
;             if (!fin) PG8_WAIT_V(8); else PG8_WAIT_V(2); PG8_WAIT_L(0); PG8_BAR; PG8_MMAF(1, 0, At, B0); PG8_MMAF(1, 1, At, B1); PG8_BAR; PG8_SCHED;
;             PG8_LDB(B0, 1, 0); PG8_LDB(B1, 1, 1); PG8_SCHED; PG8_LDA(At, 1, 0); if (!fin) PG8_STAGE(PG8_SA(0, 1), a2 + hstep, voffA);
;             if (!fin) PG8_WAIT_V(8); else PG8_WAIT_V(0); PG8_WAIT_L(0); PG8_BAR; PG8_MMA(0, 0, At, B0); PG8_MMA(0, 1, At, B1); PG8_BAR; PG8_SCHED;
;             PG8_LDA(At, 1, 1); if (!fin) { PG8_STAGE(PG8_SB(1, 0), b3, voffB); PG8_STAGE(PG8_SB(1, 1), b3 + hstep, voffB); PG8_STAGE(PG8_SA(1, 0), a3, voffA); }
;             if (!fin) PG8_WAIT_V(8); PG8_WAIT_L(0); PG8_BAR; PG8_MMA(1, 0, At, B0); PG8_MMA(1, 1, At, B1); PG8_BAR; PG8_SCHED;
.LBB0_988:
	s_waitcnt lgkmcnt(0)
	s_barrier
	v_mfma_f32_16x16x32_f16 v[62:65], v[166:169], v[186:189], v[62:65]
	s_setprio 1
	v_mfma_f32_16x16x32_f16 v[62:65], v[170:173], v[190:193], v[62:65]
	v_mfma_f32_16x16x32_f16 v[58:61], v[162:165], v[190:193], v[58:61]
	v_mfma_f32_16x16x32_f16 v[58:61], v[158:161], v[186:189], v[58:61]
	v_mfma_f32_16x16x32_f16 v[42:45], v[158:161], v[178:181], v[42:45]
	v_mfma_f32_16x16x32_f16 v[42:45], v[162:165], v[182:185], v[42:45]
	v_mfma_f32_16x16x32_f16 v[46:49], v[170:173], v[182:185], v[46:49]
	v_mfma_f32_16x16x32_f16 v[46:49], v[166:169], v[178:181], v[46:49]
	v_mfma_f32_16x16x32_f16 v[30:33], v[166:169], v[138:141], v[30:33]
	v_mfma_f32_16x16x32_f16 v[30:33], v[170:173], v[174:177], v[30:33]
	v_mfma_f32_16x16x32_f16 v[26:29], v[162:165], v[174:177], v[26:29]
	v_mfma_f32_16x16x32_f16 v[26:29], v[158:161], v[138:141], v[26:29]
	v_mfma_f32_16x16x32_f16 v[10:13], v[158:161], v[114:117], v[10:13]
	v_mfma_f32_16x16x32_f16 v[10:13], v[162:165], v[126:129], v[10:13]
	v_mfma_f32_16x16x32_f16 v[14:17], v[170:173], v[126:129], v[14:17]
	v_mfma_f32_16x16x32_f16 v[14:17], v[166:169], v[114:117], v[14:17]
	v_mfma_f32_16x16x32_f16 v[6:9], v[90:93], v[114:117], v[6:9]
	v_mfma_f32_16x16x32_f16 v[6:9], v[102:105], v[126:129], v[6:9]
	v_mfma_f32_16x16x32_f16 v[54:57], v[102:105], v[190:193], v[54:57]
	v_mfma_f32_16x16x32_f16 v[54:57], v[90:93], v[186:189], v[54:57]
	v_mfma_f32_16x16x32_f16 v[50:53], v[66:69], v[186:189], v[50:53]
	v_mfma_f32_16x16x32_f16 v[50:53], v[78:81], v[190:193], v[50:53]
	v_mfma_f32_16x16x32_f16 v[34:37], v[78:81], v[182:185], v[34:37]
	v_mfma_f32_16x16x32_f16 v[34:37], v[66:69], v[178:181], v[34:37]
	v_mfma_f32_16x16x32_f16 v[38:41], v[90:93], v[178:181], v[38:41]
	v_mfma_f32_16x16x32_f16 v[38:41], v[102:105], v[182:185], v[38:41]
	s_barrier
	v_mfma_f32_16x16x32_f16 v[22:25], v[102:105], v[174:177], v[22:25]
	v_mfma_f32_16x16x32_f16 v[22:25], v[90:93], v[138:141], v[22:25]
	v_mfma_f32_16x16x32_f16 v[18:21], v[66:69], v[138:141], v[18:21]
	v_mfma_f32_16x16x32_f16 v[18:21], v[78:81], v[174:177], v[18:21]
	v_mfma_f32_16x16x32_f16 v[2:5], v[78:81], v[126:129], v[2:5]
	v_mfma_f32_16x16x32_f16 v[2:5], v[66:69], v[114:117], v[2:5]
	s_setprio 0
	s_add_i32 s54, s54, 2
	s_add_u32 s52, s52, 0x100
	s_addc_u32 s53, s53, 0
	s_cmp_gt_u32 s54, 41
	s_cbranch_scc1 .LBB0_999
.LBB0_989:
	ds_read_b128 v[158:161], v213
	ds_read_b128 v[162:165], v213 offset:1024
	ds_read_b128 v[166:169], v213 offset:2048
	ds_read_b128 v[170:173], v213 offset:3072
	ds_read_b128 v[66:69], v214
	ds_read_b128 v[78:81], v214 offset:1024
	ds_read_b128 v[90:93], v214 offset:2048
	ds_read_b128 v[102:105], v214 offset:3072
	s_mov_b64 s[6:7], s[50:51]
	s_add_u32 s50, s6, 0x100
	s_addc_u32 s51, s7, 0
	s_cmp_eq_u32 s54, 40
	s_cselect_b64 s[26:27], -1, 0
	s_and_b64 s[8:9], s[26:27], exec
	s_cselect_b32 s25, s47, s51
	s_cselect_b32 s24, s46, s50
	s_cselect_b32 s9, s49, s53
	s_cselect_b32 s8, s48, s52
	ds_read_b128 v[174:177], v215
	ds_read_b128 v[178:181], v215 offset:1024
	ds_read_b128 v[182:185], v215 offset:2048
	ds_read_b128 v[186:189], v215 offset:3072
	ds_read_b128 v[190:193], v215 offset:4096
	ds_read_b128 v[194:197], v215 offset:5120
	ds_read_b128 v[198:201], v215 offset:6144
	ds_read_b128 v[202:205], v215 offset:7168
	s_add_u32 s6, s6, 0xb0080
	s_addc_u32 s7, s7, 0
	s_add_u32 m0, s28, 0xc000
	s_nop 0
	global_load_lds_dwordx4 v1, s[6:7]
	s_nop 0
	s_add_u32 m0, s28, 0xe000
	s_nop 0
	global_load_lds_dwordx4 v211, s[6:7]
	s_waitcnt vmcnt(8)
	s_waitcnt lgkmcnt(0)
	s_barrier
	v_mfma_f32_16x16x32_f16 v[114:117], v[158:161], v[174:177], v[154:157]
	s_setprio 1
	v_mfma_f32_16x16x32_f16 v[114:117], v[162:165], v[178:181], v[114:117]
	v_mfma_f32_16x16x32_f16 v[126:129], v[170:173], v[178:181], v[150:153]
	v_mfma_f32_16x16x32_f16 v[126:129], v[166:169], v[174:177], v[126:129]
	v_mfma_f32_16x16x32_f16 v[130:133], v[166:169], v[182:185], v[130:133]
	v_mfma_f32_16x16x32_f16 v[130:133], v[170:173], v[186:189], v[130:133]
	v_mfma_f32_16x16x32_f16 v[134:137], v[162:165], v[186:189], v[134:137]
	v_mfma_f32_16x16x32_f16 v[134:137], v[158:161], v[182:185], v[134:137]
	v_mfma_f32_16x16x32_f16 v[110:113], v[158:161], v[190:193], v[110:113]
	v_mfma_f32_16x16x32_f16 v[110:113], v[162:165], v[194:197], v[110:113]
	v_mfma_f32_16x16x32_f16 v[106:109], v[170:173], v[194:197], v[106:109]
	v_mfma_f32_16x16x32_f16 v[106:109], v[166:169], v[190:193], v[106:109]
	v_mfma_f32_16x16x32_f16 v[82:85], v[166:169], v[198:201], v[82:85]
	v_mfma_f32_16x16x32_f16 v[82:85], v[170:173], v[202:205], v[82:85]
	v_mfma_f32_16x16x32_f16 v[86:89], v[162:165], v[202:205], v[86:89]
	v_mfma_f32_16x16x32_f16 v[86:89], v[158:161], v[198:201], v[86:89]
	v_mfma_f32_16x16x32_f16 v[74:77], v[66:69], v[198:201], v[74:77]
	v_mfma_f32_16x16x32_f16 v[74:77], v[78:81], v[202:205], v[74:77]
	v_mfma_f32_16x16x32_f16 v[138:141], v[78:81], v[178:181], v[146:149]
	v_mfma_f32_16x16x32_f16 v[138:141], v[66:69], v[174:177], v[138:141]
	v_mfma_f32_16x16x32_f16 v[142:145], v[90:93], v[174:177], v[142:145]
	v_mfma_f32_16x16x32_f16 v[142:145], v[102:105], v[178:181], v[142:145]
	v_mfma_f32_16x16x32_f16 v[118:121], v[102:105], v[186:189], v[118:121]
	v_mfma_f32_16x16x32_f16 v[118:121], v[90:93], v[182:185], v[118:121]
	v_mfma_f32_16x16x32_f16 v[122:125], v[66:69], v[182:185], v[122:125]
	v_mfma_f32_16x16x32_f16 v[122:125], v[78:81], v[186:189], v[122:125]
	s_barrier
	v_mfma_f32_16x16x32_f16 v[98:101], v[78:81], v[194:197], v[98:101]
	v_mfma_f32_16x16x32_f16 v[98:101], v[66:69], v[190:193], v[98:101]
	v_mfma_f32_16x16x32_f16 v[94:97], v[90:93], v[190:193], v[94:97]
	v_mfma_f32_16x16x32_f16 v[94:97], v[102:105], v[194:197], v[94:97]
	v_mfma_f32_16x16x32_f16 v[70:73], v[102:105], v[202:205], v[70:73]
	v_mfma_f32_16x16x32_f16 v[70:73], v[90:93], v[198:201], v[70:73]
	s_setprio 0
	ds_read_b128 v[186:189], v215 offset:16384
	ds_read_b128 v[190:193], v215 offset:17408
	ds_read_b128 v[178:181], v215 offset:18432
	ds_read_b128 v[182:185], v215 offset:19456
	ds_read_b128 v[154:157], v215 offset:20480
	ds_read_b128 v[174:177], v215 offset:21504
	ds_read_b128 v[146:149], v215 offset:22528
	ds_read_b128 v[150:153], v215 offset:23552
	s_and_b64 s[6:7], s[4:5], s[26:27]
	s_mov_b64 s[26:27], -1
	s_and_b64 vcc, exec, s[6:7]
	s_cbranch_vccnz .LBB0_991
	s_add_u32 m0, s28, 0x10000
	s_nop 0
	global_load_lds_dwordx4 v210, s[8:9]
	s_nop 0
	s_add_u32 m0, s28, 0x12000
	s_nop 0
	global_load_lds_dwordx4 v212, s[8:9]
	s_add_u32 s26, s8, 0xb0000
	s_addc_u32 s27, s9, 0
	s_add_u32 m0, s28, 0x14000
	s_nop 0
	global_load_lds_dwordx4 v210, s[26:27]
	s_nop 0
	s_add_u32 m0, s28, 0x16000
	s_nop 0
	global_load_lds_dwordx4 v212, s[26:27]
	s_mov_b64 s[26:27], 0
	s_add_u32 m0, s28, 0
	s_nop 0
	global_load_lds_dwordx4 v1, s[24:25]
	s_nop 0
	s_add_u32 m0, s28, 0x2000
	s_nop 0
	global_load_lds_dwordx4 v211, s[24:25]
	s_waitcnt vmcnt(8)

; #define PG8_STAGE(bufoff, gbase, voff) do { if constexpr (ABL & 1) break; glds16s<(bufoff)>((voff)[0], (const void*)(gbase), ldsbw); glds16s<(bufoff) + 8192>((voff)[1], (const void*)(gbase), ldsbw); } while (0)
; #define PG8_LDA(dst, b, h) do { if constexpr (ABL & 4) break; _Pragma("unroll") for (int m = 0; m < 4; ++m) _Pragma("unroll") for (int k = 0; k < 2; ++k) dst[m][k] = *(const LAS f16x8*)(lds + PG8_SA(b, h) + aoff + m * 2048 + k * 1024); } while (0)
; #define PG8_LDB(dst, b, h) do { if constexpr (ABL & 4) break; _Pragma("unroll") for (int n = 0; n < 2; ++n) _Pragma("unroll") for (int k = 0; k < 2; ++k) dst[n][k] = *(const LAS f16x8*)(lds + PG8_SB(b, h) + boff + n * 2048 + k * 1024); } while (0)
; #define PG8_MMAF(ai, bj, At, Bt) do { if (t == 0) PG8_MMA0(ai, bj, At, Bt); else PG8_MMA(ai, bj, At, Bt); } while (0)
; #define PG8_WAIT_V(n) asm volatile("s_waitcnt vmcnt(" #n ")" ::: "memory")
; #define PG8_WAIT_L(n) asm volatile("s_waitcnt lgkmcnt(" #n ")" ::: "memory")
; #define PG8_BAR __builtin_amdgcn_s_barrier()
; #define PG8_SCHED __builtin_amdgcn_sched_barrier(0)
;     ...
;             if (!fin) PG8_WAIT_V(8); else PG8_WAIT_V(2); PG8_WAIT_L(0); PG8_BAR; PG8_MMAF(1, 0, At, B0); PG8_MMAF(1, 1, At, B1); PG8_BAR; PG8_SCHED;
;             PG8_LDB(B0, 1, 0); PG8_LDB(B1, 1, 1); PG8_SCHED; PG8_LDA(At, 1, 0); if (!fin) PG8_STAGE(PG8_SA(0, 1), a2 + hstep, voffA);
.LBB0_993:
	s_waitcnt lgkmcnt(0)
	s_xor_b64 s[26:27], s[6:7], -1
	s_barrier
	v_mfma_f32_16x16x32_f16 v[62:65], v[158:161], v[186:189], v[62:65]
	s_setprio 1
	v_mfma_f32_16x16x32_f16 v[62:65], v[162:165], v[190:193], v[62:65]
	v_mfma_f32_16x16x32_f16 v[58:61], v[170:173], v[190:193], v[58:61]
	v_mfma_f32_16x16x32_f16 v[58:61], v[166:169], v[186:189], v[58:61]
	v_mfma_f32_16x16x32_f16 v[42:45], v[166:169], v[178:181], v[42:45]
	v_mfma_f32_16x16x32_f16 v[42:45], v[170:173], v[182:185], v[42:45]
	v_mfma_f32_16x16x32_f16 v[46:49], v[162:165], v[182:185], v[46:49]
	v_mfma_f32_16x16x32_f16 v[46:49], v[158:161], v[178:181], v[46:49]
	v_mfma_f32_16x16x32_f16 v[30:33], v[158:161], v[154:157], v[30:33]
	v_mfma_f32_16x16x32_f16 v[30:33], v[162:165], v[174:177], v[30:33]
	v_mfma_f32_16x16x32_f16 v[26:29], v[170:173], v[174:177], v[26:29]
	v_mfma_f32_16x16x32_f16 v[26:29], v[166:169], v[154:157], v[26:29]
	v_mfma_f32_16x16x32_f16 v[10:13], v[166:169], v[146:149], v[10:13]
	v_mfma_f32_16x16x32_f16 v[10:13], v[170:173], v[150:153], v[10:13]
	v_mfma_f32_16x16x32_f16 v[14:17], v[162:165], v[150:153], v[14:17]
	v_mfma_f32_16x16x32_f16 v[14:17], v[158:161], v[146:149], v[14:17]
	v_mfma_f32_16x16x32_f16 v[6:9], v[66:69], v[146:149], v[6:9]
	v_mfma_f32_16x16x32_f16 v[6:9], v[78:81], v[150:153], v[6:9]
	v_mfma_f32_16x16x32_f16 v[54:57], v[78:81], v[190:193], v[54:57]
	v_mfma_f32_16x16x32_f16 v[54:57], v[66:69], v[186:189], v[54:57]
	v_mfma_f32_16x16x32_f16 v[50:53], v[90:93], v[186:189], v[50:53]
	v_mfma_f32_16x16x32_f16 v[50:53], v[102:105], v[190:193], v[50:53]
	v_mfma_f32_16x16x32_f16 v[34:37], v[102:105], v[182:185], v[34:37]
	v_mfma_f32_16x16x32_f16 v[34:37], v[90:93], v[178:181], v[34:37]
	v_mfma_f32_16x16x32_f16 v[38:41], v[66:69], v[178:181], v[38:41]
	v_mfma_f32_16x16x32_f16 v[38:41], v[78:81], v[182:185], v[38:41]
	s_barrier
	v_mfma_f32_16x16x32_f16 v[22:25], v[78:81], v[174:177], v[22:25]
	v_mfma_f32_16x16x32_f16 v[22:25], v[66:69], v[154:157], v[22:25]
	v_mfma_f32_16x16x32_f16 v[18:21], v[90:93], v[154:157], v[18:21]
	v_mfma_f32_16x16x32_f16 v[18:21], v[102:105], v[174:177], v[18:21]
	v_mfma_f32_16x16x32_f16 v[2:5], v[102:105], v[150:153], v[2:5]
	v_mfma_f32_16x16x32_f16 v[2:5], v[90:93], v[146:149], v[2:5]
	s_setprio 0
	ds_read_b128 v[166:169], v216
	ds_read_b128 v[170:173], v216 offset:1024
	ds_read_b128 v[158:161], v216 offset:2048
	ds_read_b128 v[162:165], v216 offset:3072
	ds_read_b128 v[90:93], v217
	ds_read_b128 v[102:105], v217 offset:1024
	ds_read_b128 v[66:69], v217 offset:2048
	ds_read_b128 v[78:81], v217 offset:3072
	ds_read_b128 v[198:201], v215 offset:32768
	ds_read_b128 v[202:205], v215 offset:33792
	ds_read_b128 v[190:193], v215 offset:34816
	ds_read_b128 v[194:197], v215 offset:35840
	ds_read_b128 v[182:185], v215 offset:36864
	ds_read_b128 v[186:189], v215 offset:37888
	ds_read_b128 v[174:177], v215 offset:38912
	ds_read_b128 v[178:181], v215 offset:39936
	v_cndmask_b32_e64 v146, 0, 1, s[26:27]
	v_cmp_ne_u32_e64 s[6:7], 1, v146
	s_andn2_b64 vcc, exec, s[26:27]
	s_mov_b64 s[26:27], -1
	s_cbranch_vccnz .LBB0_995
	s_add_u32 s26, s24, 0xb0000
	s_addc_u32 s27, s25, 0
	s_add_u32 m0, s28, 0x4000
	s_nop 0
	global_load_lds_dwordx4 v1, s[26:27]
	s_nop 0
	s_add_u32 m0, s28, 0x6000
	s_nop 0
	global_load_lds_dwordx4 v211, s[26:27]
	s_waitcnt vmcnt(8)
	s_mov_b64 s[26:27], 0

; #define PG8_STAGE(bufoff, gbase, voff) do { if constexpr (ABL & 1) break; glds16s<(bufoff)>((voff)[0], (const void*)(gbase), ldsbw); glds16s<(bufoff) + 8192>((voff)[1], (const void*)(gbase), ldsbw); } while (0)
; #define PG8_LDA(dst, b, h) do { if constexpr (ABL & 4) break; _Pragma("unroll") for (int m = 0; m < 4; ++m) _Pragma("unroll") for (int k = 0; k < 2; ++k) dst[m][k] = *(const LAS f16x8*)(lds + PG8_SA(b, h) + aoff + m * 2048 + k * 1024); } while (0)
; #define PG8_MMA(ai, bj, At, Bt) do { if constexpr (ABL & 2) break; __builtin_amdgcn_s_setprio(1); _Pragma("unroll") for (int m = 0; m < 4; ++m) _Pragma("unroll") for (int n = 0; n < 2; ++n) _Pragma("unroll") for (int k = 0; k < 2; ++k) \
;         acc[ai][bj][m][n] = __builtin_amdgcn_mfma_f32_16x16x32_f16(Bt[n][k], At[m][k], acc[ai][bj][m][n], 0, 0, 0); __builtin_amdgcn_s_setprio(0); } while (0)
; #define PG8_WAIT_V(n) asm volatile("s_waitcnt vmcnt(" #n ")" ::: "memory")
; #define PG8_WAIT_L(n) asm volatile("s_waitcnt lgkmcnt(" #n ")" ::: "memory")
; #define PG8_BAR __builtin_amdgcn_s_barrier()
; #define PG8_SCHED __builtin_amdgcn_sched_barrier(0)
;     ...
;             if (!fin) PG8_WAIT_V(8); else PG8_WAIT_V(0); PG8_WAIT_L(0); PG8_BAR; PG8_MMA(0, 0, At, B0); PG8_MMA(0, 1, At, B1); PG8_BAR; PG8_SCHED;
;             PG8_LDA(At, 1, 1); if (!fin) { PG8_STAGE(PG8_SB(1, 0), b3, voffB); PG8_STAGE(PG8_SB(1, 1), b3 + hstep, voffB); PG8_STAGE(PG8_SA(1, 0), a3, voffA); }
.LBB0_997:
	s_waitcnt lgkmcnt(0)
	s_barrier
	v_mfma_f32_16x16x32_f16 v[114:117], v[166:169], v[198:201], v[114:117]
	s_setprio 1
	v_mfma_f32_16x16x32_f16 v[154:157], v[170:173], v[202:205], v[114:117]
	v_mfma_f32_16x16x32_f16 v[114:117], v[162:165], v[202:205], v[126:129]
	v_mfma_f32_16x16x32_f16 v[150:153], v[158:161], v[198:201], v[114:117]
	v_mfma_f32_16x16x32_f16 v[106:109], v[158:161], v[182:185], v[106:109]
	v_mfma_f32_16x16x32_f16 v[106:109], v[162:165], v[186:189], v[106:109]
	v_mfma_f32_16x16x32_f16 v[110:113], v[170:173], v[186:189], v[110:113]
	v_mfma_f32_16x16x32_f16 v[110:113], v[166:169], v[182:185], v[110:113]
	v_mfma_f32_16x16x32_f16 v[114:117], v[166:169], v[190:193], v[134:137]
	v_mfma_f32_16x16x32_f16 v[134:137], v[170:173], v[194:197], v[114:117]
	v_mfma_f32_16x16x32_f16 v[114:117], v[162:165], v[194:197], v[130:133]
	v_mfma_f32_16x16x32_f16 v[130:133], v[158:161], v[190:193], v[114:117]
	v_mfma_f32_16x16x32_f16 v[82:85], v[158:161], v[174:177], v[82:85]
	v_mfma_f32_16x16x32_f16 v[82:85], v[162:165], v[178:181], v[82:85]
	v_mfma_f32_16x16x32_f16 v[86:89], v[170:173], v[178:181], v[86:89]
	v_mfma_f32_16x16x32_f16 v[86:89], v[166:169], v[174:177], v[86:89]
	v_mfma_f32_16x16x32_f16 v[74:77], v[90:93], v[174:177], v[74:77]
	v_mfma_f32_16x16x32_f16 v[74:77], v[102:105], v[178:181], v[74:77]
	v_mfma_f32_16x16x32_f16 v[114:117], v[102:105], v[202:205], v[138:141]
	v_mfma_f32_16x16x32_f16 v[146:149], v[90:93], v[198:201], v[114:117]
	v_mfma_f32_16x16x32_f16 v[114:117], v[66:69], v[198:201], v[142:145]
	v_mfma_f32_16x16x32_f16 v[142:145], v[78:81], v[202:205], v[114:117]
	v_mfma_f32_16x16x32_f16 v[94:97], v[78:81], v[186:189], v[94:97]
	v_mfma_f32_16x16x32_f16 v[94:97], v[66:69], v[182:185], v[94:97]
	v_mfma_f32_16x16x32_f16 v[98:101], v[90:93], v[182:185], v[98:101]
	v_mfma_f32_16x16x32_f16 v[98:101], v[102:105], v[186:189], v[98:101]
	s_barrier
	v_mfma_f32_16x16x32_f16 v[114:117], v[102:105], v[194:197], v[122:125]
	v_mfma_f32_16x16x32_f16 v[122:125], v[90:93], v[190:193], v[114:117]
	v_mfma_f32_16x16x32_f16 v[114:117], v[66:69], v[190:193], v[118:121]
	v_mfma_f32_16x16x32_f16 v[118:121], v[78:81], v[194:197], v[114:117]
	v_mfma_f32_16x16x32_f16 v[70:73], v[78:81], v[178:181], v[70:73]
	v_mfma_f32_16x16x32_f16 v[70:73], v[66:69], v[174:177], v[70:73]
	s_setprio 0
	ds_read_b128 v[186:189], v215 offset:49152
	ds_read_b128 v[190:193], v215 offset:50176
	ds_read_b128 v[178:181], v215 offset:51200
	ds_read_b128 v[182:185], v215 offset:52224
	ds_read_b128 v[138:141], v215 offset:53248
	ds_read_b128 v[174:177], v215 offset:54272
	ds_read_b128 v[114:117], v215 offset:55296
	ds_read_b128 v[126:129], v215 offset:56320
	s_and_b64 vcc, exec, s[6:7]
	s_cbranch_vccnz .LBB0_988
	s_add_u32 s6, s24, 0x80
	s_addc_u32 s7, s25, 0
	s_add_u32 s24, s8, 0x80
	s_addc_u32 s25, s9, 0
	s_add_u32 m0, s28, 0x18000
	s_nop 0
	global_load_lds_dwordx4 v210, s[24:25]
	s_nop 0
	s_add_u32 m0, s28, 0x1a000
	s_nop 0
	global_load_lds_dwordx4 v212, s[24:25]
	s_add_u32 s8, s8, 0xb0080
	s_addc_u32 s9, s9, 0
	s_add_u32 m0, s28, 0x1c000
	s_nop 0
	global_load_lds_dwordx4 v210, s[8:9]
	s_nop 0
	s_add_u32 m0, s28, 0x1e000
	s_nop 0
	global_load_lds_dwordx4 v212, s[8:9]
	s_nop 0
	s_add_u32 m0, s28, 0x8000
	s_nop 0
	global_load_lds_dwordx4 v1, s[6:7]
	s_nop 0
	s_add_u32 m0, s28, 0xa000
	s_nop 0
	global_load_lds_dwordx4 v211, s[6:7]
	s_waitcnt vmcnt(8)
	s_branch .LBB0_988

; #define PG8_STAGE(bufoff, gbase, voff) do { if constexpr (ABL & 1) break; glds16s<(bufoff)>((voff)[0], (const void*)(gbase), ldsbw); glds16s<(bufoff) + 8192>((voff)[1], (const void*)(gbase), ldsbw); } while (0)
; #define PG8_LDA(dst, b, h) do { if constexpr (ABL & 4) break; _Pragma("unroll") for (int m = 0; m < 4; ++m) _Pragma("unroll") for (int k = 0; k < 2; ++k) dst[m][k] = *(const LAS f16x8*)(lds + PG8_SA(b, h) + aoff + m * 2048 + k * 1024); } while (0)
; #define PG8_LDB(dst, b, h) do { if constexpr (ABL & 4) break; _Pragma("unroll") for (int n = 0; n < 2; ++n) _Pragma("unroll") for (int k = 0; k < 2; ++k) dst[n][k] = *(const LAS f16x8*)(lds + PG8_SB(b, h) + boff + n * 2048 + k * 1024); } while (0)
; #define PG8_MMAF(ai, bj, At, Bt) do { if (t == 0) PG8_MMA0(ai, bj, At, Bt); else PG8_MMA(ai, bj, At, Bt); } while (0)
; #define PG8_WAIT_V(n) asm volatile("s_waitcnt vmcnt(" #n ")" ::: "memory")
; #define PG8_WAIT_L(n) asm volatile("s_waitcnt lgkmcnt(" #n ")" ::: "memory")
; #define PG8_BAR __builtin_amdgcn_s_barrier()
; #define PG8_SCHED __builtin_amdgcn_sched_barrier(0)
;     ...
;         const char* nA = has_next ? (const char*)g.A + (size_t)nxt.pm * tstep : cA; const char* nB = has_next ? (const char*)g.Bt + (size_t)nxt.pn * tstep : cB;
;         for (int t = 0; t < nt; t += 2) {
;             const bool last = (t == nt - 2);
;             const char* a1 = cA + (size_t)(t + 1) * kstep;
;             const char* a2 = last ? nA : cA + (size_t)(t + 2) * kstep; const char* b2 = last ? nB : cB + (size_t)(t + 2) * kstep;
;             const char* a3 = a2 + kstep; const char* b3 = b2 + kstep;
;             if (last && has_next) S.a_ready(nxt);
;             if constexpr (SP2) {
;             PG8_LDB(B0, 0, 0); PG8_LDB(B1, 0, 1); PG8_SCHED; PG8_LDA(At, 0, 0); PG8_STAGE(PG8_SA(1, 1), a1 + hstep, voffA);
;             PG8_WAIT_V(8); PG8_WAIT_L(0); PG8_BAR; PG8_MMAF(0, 0, At, B0); PG8_MMAF(0, 1, At, B1); PG8_BAR; PG8_SCHED;
;             const bool fin = last && !has_next;
;             PG8_LDA(At, 0, 1); if (!fin) { PG8_STAGE(PG8_SB(0, 0), b2, voffB); PG8_STAGE(PG8_SB(0, 1), b2 + hstep, voffB); PG8_STAGE(PG8_SA(0, 0), a2, voffA); }
;             if (!fin) PG8_WAIT_V(8); else PG8_WAIT_V(2); PG8_WAIT_L(0); PG8_BAR; PG8_MMAF(1, 0, At, B0); PG8_MMAF(1, 1, At, B1); PG8_BAR; PG8_SCHED;
.LBB0_1111:
	s_ashr_i32 s43, s42, 31
	s_lshl_b64 s[8:9], s[42:43], 19
	s_add_u32 s44, s74, s8
	s_addc_u32 s45, s75, s9
	s_and_b64 s[8:9], exec, s[4:5]
	s_waitcnt lgkmcnt(0)
	ds_read_b128 v[2:5], v201
	ds_read_b128 v[6:9], v201 offset:1024
	ds_read_b128 v[10:13], v201 offset:2048
	ds_read_b128 v[14:17], v201 offset:3072
	ds_read_b128 v[18:21], v202
	ds_read_b128 v[22:25], v202 offset:1024
	ds_read_b128 v[26:29], v202 offset:2048
	ds_read_b128 v[30:33], v202 offset:3072
	s_cselect_b32 s43, s55, s45
	s_cselect_b32 s56, s54, s44
	s_ashr_i32 s41, s40, 31
	s_lshl_b64 s[8:9], s[40:41], 19
	s_add_u32 s46, s94, s8
	s_addc_u32 s47, s95, s9
	s_and_b64 s[8:9], exec, s[4:5]
	s_cselect_b32 s41, s7, s47
	s_cselect_b32 s57, s6, s46
	s_add_u32 s52, s54, 0x100
	s_addc_u32 s53, s55, 0
	s_add_u32 s26, s6, 0x100
	s_addc_u32 s27, s7, 0
	s_add_u32 s8, s54, 0x180
	s_addc_u32 s9, s55, 0
	ds_read_b128 v[34:37], v203
	ds_read_b128 v[38:41], v203 offset:1024
	ds_read_b128 v[42:45], v203 offset:2048
	ds_read_b128 v[46:49], v203 offset:3072
	ds_read_b128 v[50:53], v203 offset:4096
	ds_read_b128 v[54:57], v203 offset:5120
	ds_read_b128 v[58:61], v203 offset:6144
	ds_read_b128 v[62:65], v203 offset:7168
	s_add_u32 s24, s6, 0x180
	s_addc_u32 s25, s7, 0
	s_add_u32 s58, s54, 0x40080
	s_addc_u32 s59, s55, 0
	s_add_u32 m0, s28, 0xc000
	s_nop 0
	global_load_lds_dwordx4 v1, s[58:59]
	s_nop 0
	s_add_u32 m0, s28, 0xe000
	s_nop 0
	global_load_lds_dwordx4 v199, s[58:59]
	s_waitcnt vmcnt(8)
	s_waitcnt lgkmcnt(0)
	s_barrier
	v_mfma_f32_16x16x32_f16 v[90:93], v[2:5], v[58:61], 0
	s_setprio 1
	v_mfma_f32_16x16x32_f16 v[98:101], v[6:9], v[62:65], v[90:93]
	v_mfma_f32_16x16x32_f16 v[66:69], v[2:5], v[34:37], 0
	v_mfma_f32_16x16x32_f16 v[66:69], v[6:9], v[38:41], v[66:69]
	v_mfma_f32_16x16x32_f16 v[70:73], v[10:13], v[34:37], 0
	v_mfma_f32_16x16x32_f16 v[70:73], v[14:17], v[38:41], v[70:73]
	v_mfma_f32_16x16x32_f16 v[74:77], v[2:5], v[42:45], 0
	v_mfma_f32_16x16x32_f16 v[74:77], v[6:9], v[46:49], v[74:77]
	v_mfma_f32_16x16x32_f16 v[78:81], v[10:13], v[42:45], 0
	v_mfma_f32_16x16x32_f16 v[78:81], v[14:17], v[46:49], v[78:81]
	v_mfma_f32_16x16x32_f16 v[82:85], v[2:5], v[50:53], 0
	v_mfma_f32_16x16x32_f16 v[82:85], v[6:9], v[54:57], v[82:85]
	v_mfma_f32_16x16x32_f16 v[86:89], v[10:13], v[50:53], 0
	v_mfma_f32_16x16x32_f16 v[86:89], v[14:17], v[54:57], v[86:89]
	v_mfma_f32_16x16x32_f16 v[90:93], v[10:13], v[58:61], 0
	v_mfma_f32_16x16x32_f16 v[102:105], v[14:17], v[62:65], v[90:93]
	v_mfma_f32_16x16x32_f16 v[90:93], v[18:21], v[34:37], 0
	v_mfma_f32_16x16x32_f16 v[114:117], v[22:25], v[38:41], v[90:93]
	v_mfma_f32_16x16x32_f16 v[34:37], v[26:29], v[34:37], 0
	v_mfma_f32_16x16x32_f16 v[34:37], v[30:33], v[38:41], v[34:37]
	v_mfma_f32_16x16x32_f16 v[38:41], v[18:21], v[42:45], 0
	v_mfma_f32_16x16x32_f16 v[38:41], v[22:25], v[46:49], v[38:41]
	v_mfma_f32_16x16x32_f16 v[42:45], v[26:29], v[42:45], 0
	v_mfma_f32_16x16x32_f16 v[42:45], v[30:33], v[46:49], v[42:45]
	v_mfma_f32_16x16x32_f16 v[46:49], v[18:21], v[50:53], 0
	v_mfma_f32_16x16x32_f16 v[46:49], v[22:25], v[54:57], v[46:49]
	s_barrier
	v_mfma_f32_16x16x32_f16 v[50:53], v[26:29], v[50:53], 0
	v_mfma_f32_16x16x32_f16 v[50:53], v[30:33], v[54:57], v[50:53]
	v_mfma_f32_16x16x32_f16 v[54:57], v[18:21], v[58:61], 0
	v_mfma_f32_16x16x32_f16 v[54:57], v[22:25], v[62:65], v[54:57]
	v_mfma_f32_16x16x32_f16 v[58:61], v[26:29], v[58:61], 0
	v_mfma_f32_16x16x32_f16 v[58:61], v[30:33], v[62:65], v[58:61]
	s_setprio 0
	ds_read_b128 v[62:65], v203 offset:16384
	ds_read_b128 v[90:93], v203 offset:17408
	ds_read_b128 v[94:97], v203 offset:18432
	ds_read_b128 v[106:109], v203 offset:19456
	ds_read_b128 v[110:113], v203 offset:20480
	ds_read_b128 v[118:121], v203 offset:21504
	ds_read_b128 v[122:125], v203 offset:22528
	ds_read_b128 v[126:129], v203 offset:23552
	s_add_u32 m0, s28, 0x10000
	s_nop 0
	global_load_lds_dwordx4 v198, s[26:27]
	s_nop 0
	s_add_u32 m0, s28, 0x12000
	s_nop 0
	global_load_lds_dwordx4 v200, s[26:27]
	s_add_u32 s26, s6, 0x40100
	s_addc_u32 s27, s7, 0
	s_add_u32 m0, s28, 0x14000
	s_nop 0
	global_load_lds_dwordx4 v198, s[26:27]
	s_nop 0
	s_add_u32 m0, s28, 0x16000
	s_nop 0
	global_load_lds_dwordx4 v200, s[26:27]
	s_nop 0
	s_add_u32 m0, s28, 0
	s_nop 0
	global_load_lds_dwordx4 v1, s[52:53]
	s_nop 0
	s_add_u32 m0, s28, 0x2000
	s_nop 0
	global_load_lds_dwordx4 v199, s[52:53]
	s_waitcnt vmcnt(8)
	s_waitcnt lgkmcnt(0)
	s_barrier
	v_mfma_f32_16x16x32_f16 v[130:133], v[2:5], v[62:65], 0
	s_setprio 1
	v_mfma_f32_16x16x32_f16 v[130:133], v[6:9], v[90:93], v[130:133]
	v_mfma_f32_16x16x32_f16 v[138:141], v[2:5], v[94:97], 0
	v_mfma_f32_16x16x32_f16 v[138:141], v[6:9], v[106:109], v[138:141]
	v_mfma_f32_16x16x32_f16 v[146:149], v[2:5], v[110:113], 0
	v_mfma_f32_16x16x32_f16 v[146:149], v[6:9], v[118:121], v[146:149]
	v_mfma_f32_16x16x32_f16 v[2:5], v[2:5], v[122:125], 0
	v_mfma_f32_16x16x32_f16 v[2:5], v[6:9], v[126:129], v[2:5]
	v_mfma_f32_16x16x32_f16 v[6:9], v[10:13], v[122:125], 0
	v_mfma_f32_16x16x32_f16 v[6:9], v[14:17], v[126:129], v[6:9]
	v_mfma_f32_16x16x32_f16 v[134:137], v[10:13], v[62:65], 0
	v_mfma_f32_16x16x32_f16 v[134:137], v[14:17], v[90:93], v[134:137]
	v_mfma_f32_16x16x32_f16 v[142:145], v[10:13], v[94:97], 0
	v_mfma_f32_16x16x32_f16 v[142:145], v[14:17], v[106:109], v[142:145]
	v_mfma_f32_16x16x32_f16 v[150:153], v[10:13], v[110:113], 0
	v_mfma_f32_16x16x32_f16 v[150:153], v[14:17], v[118:121], v[150:153]
	v_mfma_f32_16x16x32_f16 v[10:13], v[18:21], v[62:65], 0
	v_mfma_f32_16x16x32_f16 v[154:157], v[22:25], v[90:93], v[10:13]
	v_mfma_f32_16x16x32_f16 v[10:13], v[26:29], v[62:65], 0
	v_mfma_f32_16x16x32_f16 v[158:161], v[30:33], v[90:93], v[10:13]
	v_mfma_f32_16x16x32_f16 v[10:13], v[18:21], v[94:97], 0
	v_mfma_f32_16x16x32_f16 v[162:165], v[22:25], v[106:109], v[10:13]
	v_mfma_f32_16x16x32_f16 v[10:13], v[26:29], v[94:97], 0
	v_mfma_f32_16x16x32_f16 v[166:169], v[30:33], v[106:109], v[10:13]
	v_mfma_f32_16x16x32_f16 v[10:13], v[18:21], v[110:113], 0
	v_mfma_f32_16x16x32_f16 v[170:173], v[22:25], v[118:121], v[10:13]
	s_barrier
; #define PG8_STAGE(bufoff, gbase, voff) do { if constexpr (ABL & 1) break; glds16s<(bufoff)>((voff)[0], (const void*)(gbase), ldsbw); glds16s<(bufoff) + 8192>((voff)[1], (const void*)(gbase), ldsbw); } while (0)
; #define PG8_LDA(dst, b, h) do { if constexpr (ABL & 4) break; _Pragma("unroll") for (int m = 0; m < 4; ++m) _Pragma("unroll") for (int k = 0; k < 2; ++k) dst[m][k] = *(const LAS f16x8*)(lds + PG8_SA(b, h) + aoff + m * 2048 + k * 1024); } while (0)
; #define PG8_LDB(dst, b, h) do { if constexpr (ABL & 4) break; _Pragma("unroll") for (int n = 0; n < 2; ++n) _Pragma("unroll") for (int k = 0; k < 2; ++k) dst[n][k] = *(const LAS f16x8*)(lds + PG8_SB(b, h) + boff + n * 2048 + k * 1024); } while (0)
; #define PG8_MMA(ai, bj, At, Bt) do { if constexpr (ABL & 2) break; __builtin_amdgcn_s_setprio(1); _Pragma("unroll") for (int m = 0; m < 4; ++m) _Pragma("unroll") for (int n = 0; n < 2; ++n) _Pragma("unroll") for (int k = 0; k < 2; ++k) \
;         acc[ai][bj][m][n] = __builtin_amdgcn_mfma_f32_16x16x32_f16(Bt[n][k], At[m][k], acc[ai][bj][m][n], 0, 0, 0); __builtin_amdgcn_s_setprio(0); } while (0)
; #define PG8_MMAF(ai, bj, At, Bt) do { if (t == 0) PG8_MMA0(ai, bj, At, Bt); else PG8_MMA(ai, bj, At, Bt); } while (0)
; #define PG8_WAIT_V(n) asm volatile("s_waitcnt vmcnt(" #n ")" ::: "memory")
; #define PG8_WAIT_L(n) asm volatile("s_waitcnt lgkmcnt(" #n ")" ::: "memory")
; #define PG8_BAR __builtin_amdgcn_s_barrier()
; #define PG8_SCHED __builtin_amdgcn_sched_barrier(0)
;     ...
;             if (!fin) PG8_WAIT_V(8); else PG8_WAIT_V(2); PG8_WAIT_L(0); PG8_BAR; PG8_MMAF(1, 0, At, B0); PG8_MMAF(1, 1, At, B1); PG8_BAR; PG8_SCHED;
;             PG8_LDB(B0, 1, 0); PG8_LDB(B1, 1, 1); PG8_SCHED; PG8_LDA(At, 1, 0); if (!fin) PG8_STAGE(PG8_SA(0, 1), a2 + hstep, voffA);
;             if (!fin) PG8_WAIT_V(8); else PG8_WAIT_V(0); PG8_WAIT_L(0); PG8_BAR; PG8_MMA(0, 0, At, B0); PG8_MMA(0, 1, At, B1); PG8_BAR; PG8_SCHED;
;             PG8_LDA(At, 1, 1); if (!fin) { PG8_STAGE(PG8_SB(1, 0), b3, voffB); PG8_STAGE(PG8_SB(1, 1), b3 + hstep, voffB); PG8_STAGE(PG8_SA(1, 0), a3, voffA); }
;             if (!fin) PG8_WAIT_V(8); PG8_WAIT_L(0); PG8_BAR; PG8_MMA(1, 0, At, B0); PG8_MMA(1, 1, At, B1); PG8_BAR; PG8_SCHED;
	v_mfma_f32_16x16x32_f16 v[10:13], v[26:29], v[110:113], 0
	v_mfma_f32_16x16x32_f16 v[174:177], v[30:33], v[118:121], v[10:13]
	v_mfma_f32_16x16x32_f16 v[10:13], v[18:21], v[122:125], 0
	v_mfma_f32_16x16x32_f16 v[178:181], v[22:25], v[126:129], v[10:13]
	v_mfma_f32_16x16x32_f16 v[10:13], v[26:29], v[122:125], 0
	v_mfma_f32_16x16x32_f16 v[182:185], v[30:33], v[126:129], v[10:13]
	s_setprio 0
	s_nop 4
	ds_read_b128 v[10:13], v204
	ds_read_b128 v[14:17], v204 offset:1024
	ds_read_b128 v[18:21], v204 offset:2048
	ds_read_b128 v[22:25], v204 offset:3072
	ds_read_b128 v[186:189], v205
	ds_read_b128 v[190:193], v205 offset:1024
	ds_read_b128 v[210:213], v205 offset:2048
	ds_read_b128 v[214:217], v205 offset:3072
	ds_read_b128 v[26:29], v203 offset:32768
	ds_read_b128 v[30:33], v203 offset:33792
	ds_read_b128 v[62:65], v203 offset:34816
	ds_read_b128 v[218:221], v203 offset:35840
	ds_read_b128 v[222:225], v203 offset:36864
	ds_read_b128 v[226:229], v203 offset:37888
	ds_read_b128 v[230:233], v203 offset:38912
	ds_read_b128 v[234:237], v203 offset:39936
	s_add_u32 s26, s54, 0x40100
	s_addc_u32 s27, s55, 0
	s_add_u32 m0, s28, 0x4000
	s_nop 0
	global_load_lds_dwordx4 v1, s[26:27]
	s_nop 0
	s_add_u32 m0, s28, 0x6000
	s_nop 0
	global_load_lds_dwordx4 v199, s[26:27]
	s_waitcnt vmcnt(8)
	s_waitcnt lgkmcnt(0)
	s_barrier
	v_mfma_f32_16x16x32_f16 v[66:69], v[10:13], v[26:29], v[66:69]
	s_setprio 1
	v_mfma_f32_16x16x32_f16 v[126:129], v[14:17], v[30:33], v[66:69]
	v_mfma_f32_16x16x32_f16 v[66:69], v[18:21], v[26:29], v[70:73]
	v_mfma_f32_16x16x32_f16 v[122:125], v[22:25], v[30:33], v[66:69]
	v_mfma_f32_16x16x32_f16 v[66:69], v[10:13], v[62:65], v[74:77]
	v_mfma_f32_16x16x32_f16 v[110:113], v[14:17], v[218:221], v[66:69]
	v_mfma_f32_16x16x32_f16 v[66:69], v[18:21], v[62:65], v[78:81]
	v_mfma_f32_16x16x32_f16 v[106:109], v[22:25], v[218:221], v[66:69]
	v_mfma_f32_16x16x32_f16 v[66:69], v[10:13], v[222:225], v[82:85]
	v_mfma_f32_16x16x32_f16 v[94:97], v[14:17], v[226:229], v[66:69]
	v_mfma_f32_16x16x32_f16 v[66:69], v[18:21], v[222:225], v[86:89]
	v_mfma_f32_16x16x32_f16 v[90:93], v[22:25], v[226:229], v[66:69]
	v_mfma_f32_16x16x32_f16 v[66:69], v[10:13], v[230:233], v[98:101]
	v_mfma_f32_16x16x32_f16 v[78:81], v[14:17], v[234:237], v[66:69]
	v_mfma_f32_16x16x32_f16 v[66:69], v[18:21], v[230:233], v[102:105]
	v_mfma_f32_16x16x32_f16 v[74:77], v[22:25], v[234:237], v[66:69]
	v_mfma_f32_16x16x32_f16 v[66:69], v[186:189], v[26:29], v[114:117]
	v_mfma_f32_16x16x32_f16 v[118:121], v[190:193], v[30:33], v[66:69]
	v_mfma_f32_16x16x32_f16 v[26:29], v[210:213], v[26:29], v[34:37]
	v_mfma_f32_16x16x32_f16 v[114:117], v[214:217], v[30:33], v[26:29]
	v_mfma_f32_16x16x32_f16 v[26:29], v[186:189], v[62:65], v[38:41]
	v_mfma_f32_16x16x32_f16 v[102:105], v[190:193], v[218:221], v[26:29]
	v_mfma_f32_16x16x32_f16 v[26:29], v[210:213], v[62:65], v[42:45]
	v_mfma_f32_16x16x32_f16 v[98:101], v[214:217], v[218:221], v[26:29]
	v_mfma_f32_16x16x32_f16 v[26:29], v[186:189], v[222:225], v[46:49]
	v_mfma_f32_16x16x32_f16 v[86:89], v[190:193], v[226:229], v[26:29]
	s_barrier
	v_mfma_f32_16x16x32_f16 v[26:29], v[210:213], v[222:225], v[50:53]
	v_mfma_f32_16x16x32_f16 v[82:85], v[214:217], v[226:229], v[26:29]
	v_mfma_f32_16x16x32_f16 v[26:29], v[186:189], v[230:233], v[54:57]
	v_mfma_f32_16x16x32_f16 v[70:73], v[190:193], v[234:237], v[26:29]
	v_mfma_f32_16x16x32_f16 v[26:29], v[210:213], v[230:233], v[58:61]
	v_mfma_f32_16x16x32_f16 v[66:69], v[214:217], v[234:237], v[26:29]
	s_setprio 0
	ds_read_b128 v[34:37], v203 offset:49152
	ds_read_b128 v[38:41], v203 offset:50176
	ds_read_b128 v[218:221], v203 offset:51200
	ds_read_b128 v[222:225], v203 offset:52224
	ds_read_b128 v[226:229], v203 offset:53248
	ds_read_b128 v[230:233], v203 offset:54272
	ds_read_b128 v[234:237], v203 offset:55296
	ds_read_b128 v[238:241], v203 offset:56320
	s_add_u32 m0, s28, 0x18000
	s_nop 0
	global_load_lds_dwordx4 v198, s[24:25]
	s_nop 0
	s_add_u32 m0, s28, 0x1a000
	s_nop 0
	global_load_lds_dwordx4 v200, s[24:25]
	s_add_u32 s24, s6, 0x40180
	s_addc_u32 s25, s7, 0
	s_add_u32 m0, s28, 0x1c000
	s_nop 0
	global_load_lds_dwordx4 v198, s[24:25]
	s_nop 0
	s_add_u32 m0, s28, 0x1e000
	s_nop 0
	global_load_lds_dwordx4 v200, s[24:25]
	s_nop 0
	s_add_u32 m0, s28, 0x8000
	s_nop 0
	global_load_lds_dwordx4 v1, s[8:9]
	s_nop 0
	s_add_u32 m0, s28, 0xa000
	s_nop 0
	global_load_lds_dwordx4 v199, s[8:9]
	s_waitcnt vmcnt(8)
	s_waitcnt lgkmcnt(0)
	s_barrier
	v_mfma_f32_16x16x32_f16 v[26:29], v[10:13], v[34:37], v[130:133]
	s_setprio 1
	v_mfma_f32_16x16x32_f16 v[62:65], v[14:17], v[38:41], v[26:29]
	v_mfma_f32_16x16x32_f16 v[26:29], v[22:25], v[38:41], v[134:137]
	v_mfma_f32_16x16x32_f16 v[58:61], v[18:21], v[34:37], v[26:29]
	v_mfma_f32_16x16x32_f16 v[26:29], v[10:13], v[218:221], v[138:141]
	v_mfma_f32_16x16x32_f16 v[46:49], v[14:17], v[222:225], v[26:29]
	v_mfma_f32_16x16x32_f16 v[26:29], v[22:25], v[222:225], v[142:145]
	v_mfma_f32_16x16x32_f16 v[42:45], v[18:21], v[218:221], v[26:29]
	v_mfma_f32_16x16x32_f16 v[26:29], v[10:13], v[226:229], v[146:149]
	v_mfma_f32_16x16x32_f16 v[30:33], v[14:17], v[230:233], v[26:29]
	v_mfma_f32_16x16x32_f16 v[2:5], v[14:17], v[238:241], v[2:5]
	v_mfma_f32_16x16x32_f16 v[14:17], v[10:13], v[234:237], v[2:5]
	v_mfma_f32_16x16x32_f16 v[2:5], v[18:21], v[234:237], v[6:9]
	v_mfma_f32_16x16x32_f16 v[10:13], v[22:25], v[238:241], v[2:5]
	v_mfma_f32_16x16x32_f16 v[26:29], v[22:25], v[230:233], v[150:153]
	v_mfma_f32_16x16x32_f16 v[26:29], v[18:21], v[226:229], v[26:29]
	v_mfma_f32_16x16x32_f16 v[2:5], v[186:189], v[34:37], v[154:157]
	v_mfma_f32_16x16x32_f16 v[54:57], v[190:193], v[38:41], v[2:5]
	v_mfma_f32_16x16x32_f16 v[2:5], v[214:217], v[38:41], v[158:161]
	v_mfma_f32_16x16x32_f16 v[50:53], v[210:213], v[34:37], v[2:5]
	v_mfma_f32_16x16x32_f16 v[2:5], v[186:189], v[218:221], v[162:165]
	v_mfma_f32_16x16x32_f16 v[38:41], v[190:193], v[222:225], v[2:5]
	v_mfma_f32_16x16x32_f16 v[2:5], v[214:217], v[222:225], v[166:169]
	v_mfma_f32_16x16x32_f16 v[34:37], v[210:213], v[218:221], v[2:5]
	v_mfma_f32_16x16x32_f16 v[2:5], v[186:189], v[226:229], v[170:173]
	v_mfma_f32_16x16x32_f16 v[22:25], v[190:193], v[230:233], v[2:5]
	s_barrier
	v_mfma_f32_16x16x32_f16 v[2:5], v[214:217], v[230:233], v[174:177]
	v_mfma_f32_16x16x32_f16 v[18:21], v[210:213], v[226:229], v[2:5]
	v_mfma_f32_16x16x32_f16 v[2:5], v[186:189], v[234:237], v[178:181]
	v_mfma_f32_16x16x32_f16 v[6:9], v[190:193], v[238:241], v[2:5]
	v_mfma_f32_16x16x32_f16 v[2:5], v[214:217], v[238:241], v[182:185]
	v_mfma_f32_16x16x32_f16 v[2:5], v[210:213], v[234:237], v[2:5]
	s_setprio 0
	s_add_u32 s54, s6, 0x200
	s_addc_u32 s55, s7, 0
	s_mov_b32 s58, 0
	s_branch .LBB0_1113
; #define PG8_STAGE(bufoff, gbase, voff) do { if constexpr (ABL & 1) break; glds16s<(bufoff)>((voff)[0], (const void*)(gbase), ldsbw); glds16s<(bufoff) + 8192>((voff)[1], (const void*)(gbase), ldsbw); } while (0)
; #define PG8_LDA(dst, b, h) do { if constexpr (ABL & 4) break; _Pragma("unroll") for (int m = 0; m < 4; ++m) _Pragma("unroll") for (int k = 0; k < 2; ++k) dst[m][k] = *(const LAS f16x8*)(lds + PG8_SA(b, h) + aoff + m * 2048 + k * 1024); } while (0)
; #define PG8_LDB(dst, b, h) do { if constexpr (ABL & 4) break; _Pragma("unroll") for (int n = 0; n < 2; ++n) _Pragma("unroll") for (int k = 0; k < 2; ++k) dst[n][k] = *(const LAS f16x8*)(lds + PG8_SB(b, h) + boff + n * 2048 + k * 1024); } while (0)
; #define PG8_MMA(ai, bj, At, Bt) do { if constexpr (ABL & 2) break; __builtin_amdgcn_s_setprio(1); _Pragma("unroll") for (int m = 0; m < 4; ++m) _Pragma("unroll") for (int n = 0; n < 2; ++n) _Pragma("unroll") for (int k = 0; k < 2; ++k) \
;         acc[ai][bj][m][n] = __builtin_amdgcn_mfma_f32_16x16x32_f16(Bt[n][k], At[m][k], acc[ai][bj][m][n], 0, 0, 0); __builtin_amdgcn_s_setprio(0); } while (0)
; #define PG8_BAR __builtin_amdgcn_s_barrier()
;     ...
;             if constexpr (SP2) {
;             PG8_LDB(B0, 0, 0); PG8_LDB(B1, 0, 1); PG8_SCHED; PG8_LDA(At, 0, 0); PG8_STAGE(PG8_SA(1, 1), a1 + hstep, voffA);
;             PG8_WAIT_V(8); PG8_WAIT_L(0); PG8_BAR; PG8_MMAF(0, 0, At, B0); PG8_MMAF(0, 1, At, B1); PG8_BAR; PG8_SCHED;
;             const bool fin = last && !has_next;
;             PG8_LDA(At, 0, 1); if (!fin) { PG8_STAGE(PG8_SB(0, 0), b2, voffB); PG8_STAGE(PG8_SB(0, 1), b2 + hstep, voffB); PG8_STAGE(PG8_SA(0, 0), a2, voffA); }
;             if (!fin) PG8_WAIT_V(8); else PG8_WAIT_V(2); PG8_WAIT_L(0); PG8_BAR; PG8_MMAF(1, 0, At, B0); PG8_MMAF(1, 1, At, B1); PG8_BAR; PG8_SCHED;
;             PG8_LDB(B0, 1, 0); PG8_LDB(B1, 1, 1); PG8_SCHED; PG8_LDA(At, 1, 0); if (!fin) PG8_STAGE(PG8_SA(0, 1), a2 + hstep, voffA);
;             if (!fin) PG8_WAIT_V(8); else PG8_WAIT_V(0); PG8_WAIT_L(0); PG8_BAR; PG8_MMA(0, 0, At, B0); PG8_MMA(0, 1, At, B1); PG8_BAR; PG8_SCHED;
;             PG8_LDA(At, 1, 1); if (!fin) { PG8_STAGE(PG8_SB(1, 0), b3, voffB); PG8_STAGE(PG8_SB(1, 1), b3 + hstep, voffB); PG8_STAGE(PG8_SA(1, 0), a3, voffA); }
;             if (!fin) PG8_WAIT_V(8); PG8_WAIT_L(0); PG8_BAR; PG8_MMA(1, 0, At, B0); PG8_MMA(1, 1, At, B1); PG8_BAR; PG8_SCHED;
.LBB0_1112:
	s_waitcnt lgkmcnt(0)
	s_barrier
	v_mfma_f32_16x16x32_f16 v[62:65], v[146:149], v[186:189], v[62:65]
	s_setprio 1
	v_mfma_f32_16x16x32_f16 v[62:65], v[150:153], v[190:193], v[62:65]
	v_mfma_f32_16x16x32_f16 v[58:61], v[158:161], v[190:193], v[58:61]
	v_mfma_f32_16x16x32_f16 v[58:61], v[154:157], v[186:189], v[58:61]
	v_mfma_f32_16x16x32_f16 v[42:45], v[154:157], v[178:181], v[42:45]
	v_mfma_f32_16x16x32_f16 v[42:45], v[158:161], v[182:185], v[42:45]
	v_mfma_f32_16x16x32_f16 v[46:49], v[150:153], v[182:185], v[46:49]
	v_mfma_f32_16x16x32_f16 v[46:49], v[146:149], v[178:181], v[46:49]
	v_mfma_f32_16x16x32_f16 v[30:33], v[146:149], v[170:173], v[30:33]
	v_mfma_f32_16x16x32_f16 v[30:33], v[150:153], v[174:177], v[30:33]
	v_mfma_f32_16x16x32_f16 v[26:29], v[158:161], v[174:177], v[26:29]
	v_mfma_f32_16x16x32_f16 v[26:29], v[154:157], v[170:173], v[26:29]
	v_mfma_f32_16x16x32_f16 v[10:13], v[154:157], v[162:165], v[10:13]
	v_mfma_f32_16x16x32_f16 v[10:13], v[158:161], v[166:169], v[10:13]
	v_mfma_f32_16x16x32_f16 v[14:17], v[150:153], v[166:169], v[14:17]
	v_mfma_f32_16x16x32_f16 v[14:17], v[146:149], v[162:165], v[14:17]
	v_mfma_f32_16x16x32_f16 v[6:9], v[130:133], v[162:165], v[6:9]
	v_mfma_f32_16x16x32_f16 v[6:9], v[134:137], v[166:169], v[6:9]
	v_mfma_f32_16x16x32_f16 v[54:57], v[134:137], v[190:193], v[54:57]
	v_mfma_f32_16x16x32_f16 v[54:57], v[130:133], v[186:189], v[54:57]
	v_mfma_f32_16x16x32_f16 v[50:53], v[138:141], v[186:189], v[50:53]
	v_mfma_f32_16x16x32_f16 v[50:53], v[142:145], v[190:193], v[50:53]
	v_mfma_f32_16x16x32_f16 v[34:37], v[142:145], v[182:185], v[34:37]
	v_mfma_f32_16x16x32_f16 v[34:37], v[138:141], v[178:181], v[34:37]
	v_mfma_f32_16x16x32_f16 v[38:41], v[130:133], v[178:181], v[38:41]
	v_mfma_f32_16x16x32_f16 v[38:41], v[134:137], v[182:185], v[38:41]
	s_barrier
	v_mfma_f32_16x16x32_f16 v[22:25], v[134:137], v[174:177], v[22:25]
	v_mfma_f32_16x16x32_f16 v[22:25], v[130:133], v[170:173], v[22:25]
	v_mfma_f32_16x16x32_f16 v[18:21], v[138:141], v[170:173], v[18:21]
	v_mfma_f32_16x16x32_f16 v[18:21], v[142:145], v[174:177], v[18:21]
	v_mfma_f32_16x16x32_f16 v[2:5], v[142:145], v[166:169], v[2:5]
	v_mfma_f32_16x16x32_f16 v[2:5], v[138:141], v[162:165], v[2:5]
	s_setprio 0
	s_add_i32 s58, s58, 2
	s_add_u32 s54, s54, 0x100
	s_addc_u32 s55, s55, 0
	s_cmp_gt_u32 s58, 13
	s_cbranch_scc1 .LBB0_1123
.LBB0_1113:
	ds_read_b128 v[146:149], v201
	ds_read_b128 v[150:153], v201 offset:1024
	ds_read_b128 v[154:157], v201 offset:2048
	ds_read_b128 v[158:161], v201 offset:3072
	ds_read_b128 v[130:133], v202
	ds_read_b128 v[134:137], v202 offset:1024
	ds_read_b128 v[138:141], v202 offset:2048
	ds_read_b128 v[142:145], v202 offset:3072
	s_mov_b64 s[6:7], s[52:53]
	s_add_u32 s52, s6, 0x100
	s_addc_u32 s53, s7, 0
	s_cmp_eq_u32 s58, 12
	s_cselect_b64 s[26:27], -1, 0
	s_and_b64 s[8:9], s[26:27], exec
	s_cselect_b32 s25, s43, s53
	s_cselect_b32 s24, s56, s52
	s_cselect_b32 s9, s41, s55
	s_cselect_b32 s8, s57, s54
	ds_read_b128 v[162:165], v203
	ds_read_b128 v[166:169], v203 offset:1024
	ds_read_b128 v[170:173], v203 offset:2048
	ds_read_b128 v[174:177], v203 offset:3072
	ds_read_b128 v[178:181], v203 offset:4096
	ds_read_b128 v[182:185], v203 offset:5120
	ds_read_b128 v[186:189], v203 offset:6144
	ds_read_b128 v[190:193], v203 offset:7168
	s_add_u32 s6, s6, 0x40080
	s_addc_u32 s7, s7, 0
	s_add_u32 m0, s28, 0xc000
	s_nop 0
	global_load_lds_dwordx4 v1, s[6:7]
	s_nop 0
	s_add_u32 m0, s28, 0xe000
	s_nop 0
	global_load_lds_dwordx4 v199, s[6:7]
	s_waitcnt vmcnt(8)
	s_waitcnt lgkmcnt(0)
	s_barrier
	v_mfma_f32_16x16x32_f16 v[126:129], v[146:149], v[162:165], v[126:129]
	s_setprio 1
	v_mfma_f32_16x16x32_f16 v[126:129], v[150:153], v[166:169], v[126:129]
	v_mfma_f32_16x16x32_f16 v[122:125], v[158:161], v[166:169], v[122:125]
	v_mfma_f32_16x16x32_f16 v[122:125], v[154:157], v[162:165], v[122:125]
	v_mfma_f32_16x16x32_f16 v[106:109], v[154:157], v[170:173], v[106:109]
	v_mfma_f32_16x16x32_f16 v[106:109], v[158:161], v[174:177], v[106:109]
	v_mfma_f32_16x16x32_f16 v[110:113], v[150:153], v[174:177], v[110:113]
	v_mfma_f32_16x16x32_f16 v[110:113], v[146:149], v[170:173], v[110:113]
	v_mfma_f32_16x16x32_f16 v[94:97], v[146:149], v[178:181], v[94:97]
	v_mfma_f32_16x16x32_f16 v[94:97], v[150:153], v[182:185], v[94:97]
	v_mfma_f32_16x16x32_f16 v[90:93], v[158:161], v[182:185], v[90:93]
	v_mfma_f32_16x16x32_f16 v[90:93], v[154:157], v[178:181], v[90:93]
	v_mfma_f32_16x16x32_f16 v[74:77], v[154:157], v[186:189], v[74:77]
	v_mfma_f32_16x16x32_f16 v[74:77], v[158:161], v[190:193], v[74:77]
	v_mfma_f32_16x16x32_f16 v[78:81], v[150:153], v[190:193], v[78:81]
	v_mfma_f32_16x16x32_f16 v[78:81], v[146:149], v[186:189], v[78:81]
	v_mfma_f32_16x16x32_f16 v[70:73], v[130:133], v[186:189], v[70:73]
	v_mfma_f32_16x16x32_f16 v[70:73], v[134:137], v[190:193], v[70:73]
	v_mfma_f32_16x16x32_f16 v[118:121], v[134:137], v[166:169], v[118:121]
	v_mfma_f32_16x16x32_f16 v[118:121], v[130:133], v[162:165], v[118:121]
	v_mfma_f32_16x16x32_f16 v[114:117], v[138:141], v[162:165], v[114:117]
	v_mfma_f32_16x16x32_f16 v[114:117], v[142:145], v[166:169], v[114:117]
	v_mfma_f32_16x16x32_f16 v[98:101], v[142:145], v[174:177], v[98:101]
	v_mfma_f32_16x16x32_f16 v[98:101], v[138:141], v[170:173], v[98:101]
	v_mfma_f32_16x16x32_f16 v[102:105], v[130:133], v[170:173], v[102:105]
	v_mfma_f32_16x16x32_f16 v[102:105], v[134:137], v[174:177], v[102:105]
	s_barrier
	v_mfma_f32_16x16x32_f16 v[86:89], v[134:137], v[182:185], v[86:89]
	v_mfma_f32_16x16x32_f16 v[86:89], v[130:133], v[178:181], v[86:89]
	v_mfma_f32_16x16x32_f16 v[82:85], v[138:141], v[178:181], v[82:85]
	v_mfma_f32_16x16x32_f16 v[82:85], v[142:145], v[182:185], v[82:85]
	v_mfma_f32_16x16x32_f16 v[66:69], v[142:145], v[190:193], v[66:69]
	v_mfma_f32_16x16x32_f16 v[66:69], v[138:141], v[186:189], v[66:69]
	s_setprio 0
	ds_read_b128 v[186:189], v203 offset:16384
	ds_read_b128 v[190:193], v203 offset:17408
	ds_read_b128 v[178:181], v203 offset:18432
	ds_read_b128 v[182:185], v203 offset:19456
	ds_read_b128 v[170:173], v203 offset:20480
	ds_read_b128 v[174:177], v203 offset:21504
	ds_read_b128 v[162:165], v203 offset:22528
	ds_read_b128 v[166:169], v203 offset:23552
	s_and_b64 s[6:7], s[4:5], s[26:27]
	s_mov_b64 s[26:27], -1
	s_and_b64 vcc, exec, s[6:7]
	s_cbranch_vccnz .LBB0_1115
	s_add_u32 m0, s28, 0x10000
	s_nop 0
	global_load_lds_dwordx4 v198, s[8:9]
	s_nop 0
	s_add_u32 m0, s28, 0x12000
	s_nop 0
	global_load_lds_dwordx4 v200, s[8:9]
	s_add_u32 s26, s8, 0x40000
	s_addc_u32 s27, s9, 0
	s_add_u32 m0, s28, 0x14000
	s_nop 0
	global_load_lds_dwordx4 v198, s[26:27]
	s_nop 0
	s_add_u32 m0, s28, 0x16000
	s_nop 0
	global_load_lds_dwordx4 v200, s[26:27]
	s_mov_b64 s[26:27], 0
	s_add_u32 m0, s28, 0
	s_nop 0
	global_load_lds_dwordx4 v1, s[24:25]
	s_nop 0
	s_add_u32 m0, s28, 0x2000
	s_nop 0
	global_load_lds_dwordx4 v199, s[24:25]
	s_waitcnt vmcnt(8)

; #define PG8_STAGE(bufoff, gbase, voff) do { if constexpr (ABL & 1) break; glds16s<(bufoff)>((voff)[0], (const void*)(gbase), ldsbw); glds16s<(bufoff) + 8192>((voff)[1], (const void*)(gbase), ldsbw); } while (0)
; #define PG8_LDA(dst, b, h) do { if constexpr (ABL & 4) break; _Pragma("unroll") for (int m = 0; m < 4; ++m) _Pragma("unroll") for (int k = 0; k < 2; ++k) dst[m][k] = *(const LAS f16x8*)(lds + PG8_SA(b, h) + aoff + m * 2048 + k * 1024); } while (0)
; #define PG8_LDB(dst, b, h) do { if constexpr (ABL & 4) break; _Pragma("unroll") for (int n = 0; n < 2; ++n) _Pragma("unroll") for (int k = 0; k < 2; ++k) dst[n][k] = *(const LAS f16x8*)(lds + PG8_SB(b, h) + boff + n * 2048 + k * 1024); } while (0)
; #define PG8_MMAF(ai, bj, At, Bt) do { if (t == 0) PG8_MMA0(ai, bj, At, Bt); else PG8_MMA(ai, bj, At, Bt); } while (0)
; #define PG8_WAIT_V(n) asm volatile("s_waitcnt vmcnt(" #n ")" ::: "memory")
; #define PG8_WAIT_L(n) asm volatile("s_waitcnt lgkmcnt(" #n ")" ::: "memory")
; #define PG8_BAR __builtin_amdgcn_s_barrier()
; #define PG8_SCHED __builtin_amdgcn_sched_barrier(0)
;     ...
;             if constexpr (SP2) {
;             PG8_LDB(B0, 0, 0); PG8_LDB(B1, 0, 1); PG8_SCHED; PG8_LDA(At, 0, 0); PG8_STAGE(PG8_SA(1, 1), a1 + hstep, voffA);
;             PG8_WAIT_V(8); PG8_WAIT_L(0); PG8_BAR; PG8_MMAF(0, 0, At, B0); PG8_MMAF(0, 1, At, B1); PG8_BAR; PG8_SCHED;
;             const bool fin = last && !has_next;
;             PG8_LDA(At, 0, 1); if (!fin) { PG8_STAGE(PG8_SB(0, 0), b2, voffB); PG8_STAGE(PG8_SB(0, 1), b2 + hstep, voffB); PG8_STAGE(PG8_SA(0, 0), a2, voffA); }
;             if (!fin) PG8_WAIT_V(8); else PG8_WAIT_V(2); PG8_WAIT_L(0); PG8_BAR; PG8_MMAF(1, 0, At, B0); PG8_MMAF(1, 1, At, B1); PG8_BAR; PG8_SCHED;
;             PG8_LDB(B0, 1, 0); PG8_LDB(B1, 1, 1); PG8_SCHED; PG8_LDA(At, 1, 0); if (!fin) PG8_STAGE(PG8_SA(0, 1), a2 + hstep, voffA);
.LBB0_1117:
	s_waitcnt lgkmcnt(0)
	s_xor_b64 s[26:27], s[6:7], -1
	s_barrier
	v_mfma_f32_16x16x32_f16 v[62:65], v[146:149], v[186:189], v[62:65]
	s_setprio 1
	v_mfma_f32_16x16x32_f16 v[62:65], v[150:153], v[190:193], v[62:65]
	v_mfma_f32_16x16x32_f16 v[58:61], v[158:161], v[190:193], v[58:61]
	v_mfma_f32_16x16x32_f16 v[58:61], v[154:157], v[186:189], v[58:61]
	v_mfma_f32_16x16x32_f16 v[42:45], v[154:157], v[178:181], v[42:45]
	v_mfma_f32_16x16x32_f16 v[42:45], v[158:161], v[182:185], v[42:45]
	v_mfma_f32_16x16x32_f16 v[46:49], v[150:153], v[182:185], v[46:49]
	v_mfma_f32_16x16x32_f16 v[46:49], v[146:149], v[178:181], v[46:49]
	v_mfma_f32_16x16x32_f16 v[30:33], v[146:149], v[170:173], v[30:33]
	v_mfma_f32_16x16x32_f16 v[30:33], v[150:153], v[174:177], v[30:33]
	v_mfma_f32_16x16x32_f16 v[26:29], v[158:161], v[174:177], v[26:29]
	v_mfma_f32_16x16x32_f16 v[26:29], v[154:157], v[170:173], v[26:29]
	v_mfma_f32_16x16x32_f16 v[10:13], v[154:157], v[162:165], v[10:13]
	v_mfma_f32_16x16x32_f16 v[10:13], v[158:161], v[166:169], v[10:13]
	v_mfma_f32_16x16x32_f16 v[14:17], v[150:153], v[166:169], v[14:17]
	v_mfma_f32_16x16x32_f16 v[14:17], v[146:149], v[162:165], v[14:17]
	v_mfma_f32_16x16x32_f16 v[6:9], v[130:133], v[162:165], v[6:9]
	v_mfma_f32_16x16x32_f16 v[6:9], v[134:137], v[166:169], v[6:9]
	v_mfma_f32_16x16x32_f16 v[54:57], v[134:137], v[190:193], v[54:57]
	v_mfma_f32_16x16x32_f16 v[54:57], v[130:133], v[186:189], v[54:57]
	v_mfma_f32_16x16x32_f16 v[50:53], v[138:141], v[186:189], v[50:53]
	v_mfma_f32_16x16x32_f16 v[50:53], v[142:145], v[190:193], v[50:53]
	v_mfma_f32_16x16x32_f16 v[34:37], v[142:145], v[182:185], v[34:37]
	v_mfma_f32_16x16x32_f16 v[34:37], v[138:141], v[178:181], v[34:37]
	v_mfma_f32_16x16x32_f16 v[38:41], v[130:133], v[178:181], v[38:41]
	v_mfma_f32_16x16x32_f16 v[38:41], v[134:137], v[182:185], v[38:41]
	s_barrier
	v_mfma_f32_16x16x32_f16 v[22:25], v[134:137], v[174:177], v[22:25]
	v_mfma_f32_16x16x32_f16 v[22:25], v[130:133], v[170:173], v[22:25]
	v_mfma_f32_16x16x32_f16 v[18:21], v[138:141], v[170:173], v[18:21]
	v_mfma_f32_16x16x32_f16 v[18:21], v[142:145], v[174:177], v[18:21]
	v_mfma_f32_16x16x32_f16 v[2:5], v[142:145], v[166:169], v[2:5]
	v_mfma_f32_16x16x32_f16 v[2:5], v[138:141], v[162:165], v[2:5]
	s_setprio 0
	ds_read_b128 v[146:149], v204
	ds_read_b128 v[150:153], v204 offset:1024
	ds_read_b128 v[154:157], v204 offset:2048
	ds_read_b128 v[158:161], v204 offset:3072
	ds_read_b128 v[130:133], v205
	ds_read_b128 v[134:137], v205 offset:1024
	ds_read_b128 v[138:141], v205 offset:2048
	ds_read_b128 v[142:145], v205 offset:3072
	ds_read_b128 v[186:189], v203 offset:32768
	ds_read_b128 v[190:193], v203 offset:33792
	ds_read_b128 v[178:181], v203 offset:34816
	ds_read_b128 v[182:185], v203 offset:35840
	ds_read_b128 v[170:173], v203 offset:36864
	ds_read_b128 v[174:177], v203 offset:37888
	ds_read_b128 v[162:165], v203 offset:38912
	ds_read_b128 v[166:169], v203 offset:39936
	v_cndmask_b32_e64 v209, 0, 1, s[26:27]
	v_cmp_ne_u32_e64 s[6:7], 1, v209
	s_andn2_b64 vcc, exec, s[26:27]
	s_mov_b64 s[26:27], -1
	s_cbranch_vccnz .LBB0_1119
	s_add_u32 s26, s24, 0x40000
	s_addc_u32 s27, s25, 0
	s_add_u32 m0, s28, 0x4000
	s_nop 0
	global_load_lds_dwordx4 v1, s[26:27]
	s_nop 0
	s_add_u32 m0, s28, 0x6000
	s_nop 0
	global_load_lds_dwordx4 v199, s[26:27]
	s_waitcnt vmcnt(8)
	s_mov_b64 s[26:27], 0

; #define PG8_STAGE(bufoff, gbase, voff) do { if constexpr (ABL & 1) break; glds16s<(bufoff)>((voff)[0], (const void*)(gbase), ldsbw); glds16s<(bufoff) + 8192>((voff)[1], (const void*)(gbase), ldsbw); } while (0)
; #define PG8_LDA(dst, b, h) do { if constexpr (ABL & 4) break; _Pragma("unroll") for (int m = 0; m < 4; ++m) _Pragma("unroll") for (int k = 0; k < 2; ++k) dst[m][k] = *(const LAS f16x8*)(lds + PG8_SA(b, h) + aoff + m * 2048 + k * 1024); } while (0)
; #define PG8_LDB(dst, b, h) do { if constexpr (ABL & 4) break; _Pragma("unroll") for (int n = 0; n < 2; ++n) _Pragma("unroll") for (int k = 0; k < 2; ++k) dst[n][k] = *(const LAS f16x8*)(lds + PG8_SB(b, h) + boff + n * 2048 + k * 1024); } while (0)
; #define PG8_MMA(ai, bj, At, Bt) do { if constexpr (ABL & 2) break; __builtin_amdgcn_s_setprio(1); _Pragma("unroll") for (int m = 0; m < 4; ++m) _Pragma("unroll") for (int n = 0; n < 2; ++n) _Pragma("unroll") for (int k = 0; k < 2; ++k) \
;         acc[ai][bj][m][n] = __builtin_amdgcn_mfma_f32_16x16x32_f16(Bt[n][k], At[m][k], acc[ai][bj][m][n], 0, 0, 0); __builtin_amdgcn_s_setprio(0); } while (0)
; #define PG8_WAIT_V(n) asm volatile("s_waitcnt vmcnt(" #n ")" ::: "memory")
; #define PG8_WAIT_L(n) asm volatile("s_waitcnt lgkmcnt(" #n ")" ::: "memory")
; #define PG8_BAR __builtin_amdgcn_s_barrier()
; #define PG8_SCHED __builtin_amdgcn_sched_barrier(0)
;     ...
;             PG8_LDB(B0, 1, 0); PG8_LDB(B1, 1, 1); PG8_SCHED; PG8_LDA(At, 1, 0); if (!fin) PG8_STAGE(PG8_SA(0, 1), a2 + hstep, voffA);
;             if (!fin) PG8_WAIT_V(8); else PG8_WAIT_V(0); PG8_WAIT_L(0); PG8_BAR; PG8_MMA(0, 0, At, B0); PG8_MMA(0, 1, At, B1); PG8_BAR; PG8_SCHED;
;             PG8_LDA(At, 1, 1); if (!fin) { PG8_STAGE(PG8_SB(1, 0), b3, voffB); PG8_STAGE(PG8_SB(1, 1), b3 + hstep, voffB); PG8_STAGE(PG8_SA(1, 0), a3, voffA); }
;             if (!fin) PG8_WAIT_V(8); PG8_WAIT_L(0); PG8_BAR; PG8_MMA(1, 0, At, B0); PG8_MMA(1, 1, At, B1); PG8_BAR; PG8_SCHED;
.LBB0_1121:
	s_waitcnt lgkmcnt(0)
	s_barrier
	v_mfma_f32_16x16x32_f16 v[126:129], v[146:149], v[186:189], v[126:129]
	s_setprio 1
	v_mfma_f32_16x16x32_f16 v[126:129], v[150:153], v[190:193], v[126:129]
	v_mfma_f32_16x16x32_f16 v[122:125], v[158:161], v[190:193], v[122:125]
	v_mfma_f32_16x16x32_f16 v[122:125], v[154:157], v[186:189], v[122:125]
	v_mfma_f32_16x16x32_f16 v[106:109], v[154:157], v[178:181], v[106:109]
	v_mfma_f32_16x16x32_f16 v[106:109], v[158:161], v[182:185], v[106:109]
	v_mfma_f32_16x16x32_f16 v[110:113], v[150:153], v[182:185], v[110:113]
	v_mfma_f32_16x16x32_f16 v[110:113], v[146:149], v[178:181], v[110:113]
	v_mfma_f32_16x16x32_f16 v[94:97], v[146:149], v[170:173], v[94:97]
	v_mfma_f32_16x16x32_f16 v[94:97], v[150:153], v[174:177], v[94:97]
	v_mfma_f32_16x16x32_f16 v[90:93], v[158:161], v[174:177], v[90:93]
	v_mfma_f32_16x16x32_f16 v[90:93], v[154:157], v[170:173], v[90:93]
	v_mfma_f32_16x16x32_f16 v[74:77], v[154:157], v[162:165], v[74:77]
	v_mfma_f32_16x16x32_f16 v[74:77], v[158:161], v[166:169], v[74:77]
	v_mfma_f32_16x16x32_f16 v[78:81], v[150:153], v[166:169], v[78:81]
	v_mfma_f32_16x16x32_f16 v[78:81], v[146:149], v[162:165], v[78:81]
	v_mfma_f32_16x16x32_f16 v[70:73], v[130:133], v[162:165], v[70:73]
	v_mfma_f32_16x16x32_f16 v[70:73], v[134:137], v[166:169], v[70:73]
	v_mfma_f32_16x16x32_f16 v[118:121], v[134:137], v[190:193], v[118:121]
	v_mfma_f32_16x16x32_f16 v[118:121], v[130:133], v[186:189], v[118:121]
	v_mfma_f32_16x16x32_f16 v[114:117], v[138:141], v[186:189], v[114:117]
	v_mfma_f32_16x16x32_f16 v[114:117], v[142:145], v[190:193], v[114:117]
	v_mfma_f32_16x16x32_f16 v[98:101], v[142:145], v[182:185], v[98:101]
	v_mfma_f32_16x16x32_f16 v[98:101], v[138:141], v[178:181], v[98:101]
	v_mfma_f32_16x16x32_f16 v[102:105], v[130:133], v[178:181], v[102:105]
	v_mfma_f32_16x16x32_f16 v[102:105], v[134:137], v[182:185], v[102:105]
	s_barrier
	v_mfma_f32_16x16x32_f16 v[86:89], v[134:137], v[174:177], v[86:89]
	v_mfma_f32_16x16x32_f16 v[86:89], v[130:133], v[170:173], v[86:89]
	v_mfma_f32_16x16x32_f16 v[82:85], v[138:141], v[170:173], v[82:85]
	v_mfma_f32_16x16x32_f16 v[82:85], v[142:145], v[174:177], v[82:85]
	v_mfma_f32_16x16x32_f16 v[66:69], v[142:145], v[166:169], v[66:69]
	v_mfma_f32_16x16x32_f16 v[66:69], v[138:141], v[162:165], v[66:69]
	s_setprio 0
	ds_read_b128 v[186:189], v203 offset:49152
	ds_read_b128 v[190:193], v203 offset:50176
	ds_read_b128 v[178:181], v203 offset:51200
	ds_read_b128 v[182:185], v203 offset:52224
	ds_read_b128 v[170:173], v203 offset:53248
	ds_read_b128 v[174:177], v203 offset:54272
	ds_read_b128 v[162:165], v203 offset:55296
	ds_read_b128 v[166:169], v203 offset:56320
	s_and_b64 vcc, exec, s[6:7]
	s_cbranch_vccnz .LBB0_1112
	s_add_u32 s6, s24, 0x80
	s_addc_u32 s7, s25, 0
	s_add_u32 s24, s8, 0x80
	s_addc_u32 s25, s9, 0
	s_add_u32 m0, s28, 0x18000
	s_nop 0
	global_load_lds_dwordx4 v198, s[24:25]
	s_nop 0
	s_add_u32 m0, s28, 0x1a000
	s_nop 0
	global_load_lds_dwordx4 v200, s[24:25]
	s_add_u32 s8, s8, 0x40080
	s_addc_u32 s9, s9, 0
	s_add_u32 m0, s28, 0x1c000
	s_nop 0
	global_load_lds_dwordx4 v198, s[8:9]
	s_nop 0
	s_add_u32 m0, s28, 0x1e000
	s_nop 0
	global_load_lds_dwordx4 v200, s[8:9]
	s_nop 0
	s_add_u32 m0, s28, 0x8000
	s_nop 0
	global_load_lds_dwordx4 v1, s[6:7]
	s_nop 0
	s_add_u32 m0, s28, 0xa000
	s_nop 0
	global_load_lds_dwordx4 v199, s[6:7]
	s_waitcnt vmcnt(8)
	s_branch .LBB0_1112

;     __device__ __forceinline__ bool next(int i, Unit& u) const { if (i >= count) return false; const int L = first + i; u.pm = L / nN; u.pn = L % nN; return true; }
; #define PG8_STAGE(bufoff, gbase, voff) do { if constexpr (ABL & 1) break; glds16s<(bufoff)>((voff)[0], (const void*)(gbase), ldsbw); glds16s<(bufoff) + 8192>((voff)[1], (const void*)(gbase), ldsbw); } while (0)
; #define PG8_LDA(dst, b, h) do { if constexpr (ABL & 4) break; _Pragma("unroll") for (int m = 0; m < 4; ++m) _Pragma("unroll") for (int k = 0; k < 2; ++k) dst[m][k] = *(const LAS f16x8*)(lds + PG8_SA(b, h) + aoff + m * 2048 + k * 1024); } while (0)
; #define PG8_LDB(dst, b, h) do { if constexpr (ABL & 4) break; _Pragma("unroll") for (int n = 0; n < 2; ++n) _Pragma("unroll") for (int k = 0; k < 2; ++k) dst[n][k] = *(const LAS f16x8*)(lds + PG8_SB(b, h) + boff + n * 2048 + k * 1024); } while (0)
; #define PG8_MMAF(ai, bj, At, Bt) do { if (t == 0) PG8_MMA0(ai, bj, At, Bt); else PG8_MMA(ai, bj, At, Bt); } while (0)
; #define PG8_WAIT_V(n) asm volatile("s_waitcnt vmcnt(" #n ")" ::: "memory")
; #define PG8_BAR __builtin_amdgcn_s_barrier()
;     ...
;         const bool has_next = S.next(ui + 1, nxt);
;         const char* nA = has_next ? (const char*)g.A + (size_t)nxt.pm * tstep : cA; const char* nB = has_next ? (const char*)g.Bt + (size_t)nxt.pn * tstep : cB;
;         for (int t = 0; t < nt; t += 2) {
;             const bool last = (t == nt - 2);
;             const char* a1 = cA + (size_t)(t + 1) * kstep;
;             const char* a2 = last ? nA : cA + (size_t)(t + 2) * kstep; const char* b2 = last ? nB : cB + (size_t)(t + 2) * kstep;
;             const char* a3 = a2 + kstep; const char* b3 = b2 + kstep;
;             if (last && has_next) S.a_ready(nxt);
;             if constexpr (SP2) {
;             PG8_LDB(B0, 0, 0); PG8_LDB(B1, 0, 1); PG8_SCHED; PG8_LDA(At, 0, 0); PG8_STAGE(PG8_SA(1, 1), a1 + hstep, voffA);
;             PG8_WAIT_V(8); PG8_WAIT_L(0); PG8_BAR; PG8_MMAF(0, 0, At, B0); PG8_MMAF(0, 1, At, B1); PG8_BAR; PG8_SCHED;
;             const bool fin = last && !has_next;
;             PG8_LDA(At, 0, 1); if (!fin) { PG8_STAGE(PG8_SB(0, 0), b2, voffB); PG8_STAGE(PG8_SB(0, 1), b2 + hstep, voffB); PG8_STAGE(PG8_SA(0, 0), a2, voffA); }
;             if (!fin) PG8_WAIT_V(8); else PG8_WAIT_V(2); PG8_WAIT_L(0); PG8_BAR; PG8_MMAF(1, 0, At, B0); PG8_MMAF(1, 1, At, B1); PG8_BAR; PG8_SCHED;
.LBB0_1163:
	s_ashr_i32 s49, s48, 31
	s_lshl_b64 s[6:7], s[48:49], 19
	s_add_u32 s50, s74, s6
	s_addc_u32 s51, s75, s7
	s_and_b64 s[6:7], exec, s[2:3]
	ds_read_b128 v[2:5], v213
	ds_read_b128 v[6:9], v213 offset:1024
	ds_read_b128 v[10:13], v213 offset:2048
	ds_read_b128 v[14:17], v213 offset:3072
	ds_read_b128 v[18:21], v214
	ds_read_b128 v[22:25], v214 offset:1024
	ds_read_b128 v[26:29], v214 offset:2048
	ds_read_b128 v[30:33], v214 offset:3072
	s_cselect_b32 s45, s37, s51
	s_cselect_b32 s49, s36, s50
	s_ashr_i32 s47, s46, 31
	s_lshl_b64 s[6:7], s[46:47], 19
	s_add_u32 s52, s94, s6
	s_addc_u32 s53, s95, s7
	s_and_b64 s[6:7], exec, s[2:3]
	s_cselect_b32 s47, s39, s53
	s_cselect_b32 s57, s38, s52
	s_add_u32 s24, s36, 0x100
	s_addc_u32 s25, s37, 0
	s_add_u32 s26, s38, 0x100
	s_addc_u32 s27, s39, 0
	s_add_u32 s6, s36, 0x180
	s_addc_u32 s7, s37, 0
	ds_read_b128 v[34:37], v215
	ds_read_b128 v[38:41], v215 offset:1024
	ds_read_b128 v[42:45], v215 offset:2048
	ds_read_b128 v[46:49], v215 offset:3072
	ds_read_b128 v[50:53], v215 offset:4096
	ds_read_b128 v[54:57], v215 offset:5120
	ds_read_b128 v[58:61], v215 offset:6144
	ds_read_b128 v[62:65], v215 offset:7168
	s_add_u32 s8, s38, 0x180
	s_addc_u32 s9, s39, 0
	s_add_u32 s54, s36, 0x40080
	s_addc_u32 s55, s37, 0
	s_add_u32 m0, s35, 0xc000
	s_nop 0
	global_load_lds_dwordx4 v1, s[54:55]
	s_nop 0
	s_add_u32 m0, s35, 0xe000
	s_nop 0
	global_load_lds_dwordx4 v211, s[54:55]
	s_waitcnt vmcnt(8)
	s_waitcnt lgkmcnt(0)
	s_barrier
	v_mfma_f32_16x16x32_f16 v[90:93], v[2:5], v[58:61], 0
	s_setprio 1
	v_mfma_f32_16x16x32_f16 v[98:101], v[6:9], v[62:65], v[90:93]
	v_mfma_f32_16x16x32_f16 v[66:69], v[2:5], v[34:37], 0
	v_mfma_f32_16x16x32_f16 v[66:69], v[6:9], v[38:41], v[66:69]
	v_mfma_f32_16x16x32_f16 v[70:73], v[10:13], v[34:37], 0
	v_mfma_f32_16x16x32_f16 v[70:73], v[14:17], v[38:41], v[70:73]
	v_mfma_f32_16x16x32_f16 v[74:77], v[2:5], v[42:45], 0
	v_mfma_f32_16x16x32_f16 v[74:77], v[6:9], v[46:49], v[74:77]
	v_mfma_f32_16x16x32_f16 v[78:81], v[10:13], v[42:45], 0
	v_mfma_f32_16x16x32_f16 v[78:81], v[14:17], v[46:49], v[78:81]
	v_mfma_f32_16x16x32_f16 v[82:85], v[2:5], v[50:53], 0
	v_mfma_f32_16x16x32_f16 v[82:85], v[6:9], v[54:57], v[82:85]
	v_mfma_f32_16x16x32_f16 v[86:89], v[10:13], v[50:53], 0
	v_mfma_f32_16x16x32_f16 v[86:89], v[14:17], v[54:57], v[86:89]
	v_mfma_f32_16x16x32_f16 v[90:93], v[10:13], v[58:61], 0
	v_mfma_f32_16x16x32_f16 v[102:105], v[14:17], v[62:65], v[90:93]
	v_mfma_f32_16x16x32_f16 v[90:93], v[18:21], v[34:37], 0
	v_mfma_f32_16x16x32_f16 v[114:117], v[22:25], v[38:41], v[90:93]
	v_mfma_f32_16x16x32_f16 v[34:37], v[26:29], v[34:37], 0
	v_mfma_f32_16x16x32_f16 v[34:37], v[30:33], v[38:41], v[34:37]
	v_mfma_f32_16x16x32_f16 v[38:41], v[18:21], v[42:45], 0
	v_mfma_f32_16x16x32_f16 v[38:41], v[22:25], v[46:49], v[38:41]
	v_mfma_f32_16x16x32_f16 v[42:45], v[26:29], v[42:45], 0
	v_mfma_f32_16x16x32_f16 v[42:45], v[30:33], v[46:49], v[42:45]
	v_mfma_f32_16x16x32_f16 v[46:49], v[18:21], v[50:53], 0
	v_mfma_f32_16x16x32_f16 v[46:49], v[22:25], v[54:57], v[46:49]
	s_barrier
	v_mfma_f32_16x16x32_f16 v[50:53], v[26:29], v[50:53], 0
	v_mfma_f32_16x16x32_f16 v[50:53], v[30:33], v[54:57], v[50:53]
	v_mfma_f32_16x16x32_f16 v[54:57], v[18:21], v[58:61], 0
	v_mfma_f32_16x16x32_f16 v[54:57], v[22:25], v[62:65], v[54:57]
	v_mfma_f32_16x16x32_f16 v[58:61], v[26:29], v[58:61], 0
	v_mfma_f32_16x16x32_f16 v[58:61], v[30:33], v[62:65], v[58:61]
	s_setprio 0
	ds_read_b128 v[62:65], v215 offset:16384
	ds_read_b128 v[90:93], v215 offset:17408
	ds_read_b128 v[94:97], v215 offset:18432
	ds_read_b128 v[106:109], v215 offset:19456
	ds_read_b128 v[110:113], v215 offset:20480
	ds_read_b128 v[118:121], v215 offset:21504
	ds_read_b128 v[122:125], v215 offset:22528
	ds_read_b128 v[126:129], v215 offset:23552
	s_add_u32 m0, s35, 0x10000
	s_nop 0
	global_load_lds_dwordx4 v210, s[26:27]
	s_nop 0
	s_add_u32 m0, s35, 0x12000
	s_nop 0
	global_load_lds_dwordx4 v212, s[26:27]
	s_add_u32 s26, s38, 0x40100
	s_addc_u32 s27, s39, 0
	s_add_u32 m0, s35, 0x14000
	s_nop 0
	global_load_lds_dwordx4 v210, s[26:27]
	s_nop 0
	s_add_u32 m0, s35, 0x16000
	s_nop 0
	global_load_lds_dwordx4 v212, s[26:27]
	s_nop 0
	s_add_u32 m0, s35, 0
	s_nop 0
	global_load_lds_dwordx4 v1, s[24:25]
	s_nop 0
	s_add_u32 m0, s35, 0x2000
	s_nop 0
	global_load_lds_dwordx4 v211, s[24:25]
	s_waitcnt vmcnt(8)
	s_waitcnt lgkmcnt(0)
	s_barrier
	v_mfma_f32_16x16x32_f16 v[134:137], v[10:13], v[62:65], 0
	s_setprio 1
	v_mfma_f32_16x16x32_f16 v[146:149], v[14:17], v[90:93], v[134:137]
	v_mfma_f32_16x16x32_f16 v[134:137], v[2:5], v[94:97], 0
	v_mfma_f32_16x16x32_f16 v[150:153], v[6:9], v[106:109], v[134:137]
	v_mfma_f32_16x16x32_f16 v[134:137], v[10:13], v[94:97], 0
	v_mfma_f32_16x16x32_f16 v[154:157], v[14:17], v[106:109], v[134:137]
	v_mfma_f32_16x16x32_f16 v[130:133], v[2:5], v[62:65], 0
	v_mfma_f32_16x16x32_f16 v[130:133], v[6:9], v[90:93], v[130:133]
	v_mfma_f32_16x16x32_f16 v[134:137], v[2:5], v[110:113], 0
	v_mfma_f32_16x16x32_f16 v[158:161], v[6:9], v[118:121], v[134:137]
	v_mfma_f32_16x16x32_f16 v[2:5], v[2:5], v[122:125], 0
	v_mfma_f32_16x16x32_f16 v[2:5], v[6:9], v[126:129], v[2:5]
	v_mfma_f32_16x16x32_f16 v[6:9], v[10:13], v[122:125], 0
	v_mfma_f32_16x16x32_f16 v[6:9], v[14:17], v[126:129], v[6:9]
	v_mfma_f32_16x16x32_f16 v[134:137], v[10:13], v[110:113], 0
	v_mfma_f32_16x16x32_f16 v[162:165], v[14:17], v[118:121], v[134:137]
	v_mfma_f32_16x16x32_f16 v[10:13], v[18:21], v[62:65], 0
	v_mfma_f32_16x16x32_f16 v[166:169], v[22:25], v[90:93], v[10:13]
	v_mfma_f32_16x16x32_f16 v[10:13], v[26:29], v[62:65], 0
	v_mfma_f32_16x16x32_f16 v[170:173], v[30:33], v[90:93], v[10:13]
	v_mfma_f32_16x16x32_f16 v[10:13], v[18:21], v[94:97], 0
	v_mfma_f32_16x16x32_f16 v[174:177], v[22:25], v[106:109], v[10:13]
	v_mfma_f32_16x16x32_f16 v[10:13], v[26:29], v[94:97], 0
	v_mfma_f32_16x16x32_f16 v[178:181], v[30:33], v[106:109], v[10:13]
	v_mfma_f32_16x16x32_f16 v[10:13], v[18:21], v[110:113], 0
	v_mfma_f32_16x16x32_f16 v[182:185], v[22:25], v[118:121], v[10:13]
	s_barrier
; #define PG8_STAGE(bufoff, gbase, voff) do { if constexpr (ABL & 1) break; glds16s<(bufoff)>((voff)[0], (const void*)(gbase), ldsbw); glds16s<(bufoff) + 8192>((voff)[1], (const void*)(gbase), ldsbw); } while (0)
; #define PG8_LDA(dst, b, h) do { if constexpr (ABL & 4) break; _Pragma("unroll") for (int m = 0; m < 4; ++m) _Pragma("unroll") for (int k = 0; k < 2; ++k) dst[m][k] = *(const LAS f16x8*)(lds + PG8_SA(b, h) + aoff + m * 2048 + k * 1024); } while (0)
; #define PG8_LDB(dst, b, h) do { if constexpr (ABL & 4) break; _Pragma("unroll") for (int n = 0; n < 2; ++n) _Pragma("unroll") for (int k = 0; k < 2; ++k) dst[n][k] = *(const LAS f16x8*)(lds + PG8_SB(b, h) + boff + n * 2048 + k * 1024); } while (0)
; #define PG8_MMA(ai, bj, At, Bt) do { if constexpr (ABL & 2) break; __builtin_amdgcn_s_setprio(1); _Pragma("unroll") for (int m = 0; m < 4; ++m) _Pragma("unroll") for (int n = 0; n < 2; ++n) _Pragma("unroll") for (int k = 0; k < 2; ++k) \
;         acc[ai][bj][m][n] = __builtin_amdgcn_mfma_f32_16x16x32_f16(Bt[n][k], At[m][k], acc[ai][bj][m][n], 0, 0, 0); __builtin_amdgcn_s_setprio(0); } while (0)
; #define PG8_MMAF(ai, bj, At, Bt) do { if (t == 0) PG8_MMA0(ai, bj, At, Bt); else PG8_MMA(ai, bj, At, Bt); } while (0)
; #define PG8_WAIT_V(n) asm volatile("s_waitcnt vmcnt(" #n ")" ::: "memory")
; #define PG8_WAIT_L(n) asm volatile("s_waitcnt lgkmcnt(" #n ")" ::: "memory")
; #define PG8_BAR __builtin_amdgcn_s_barrier()
; #define PG8_SCHED __builtin_amdgcn_sched_barrier(0)
;     ...
;             if (!fin) PG8_WAIT_V(8); else PG8_WAIT_V(2); PG8_WAIT_L(0); PG8_BAR; PG8_MMAF(1, 0, At, B0); PG8_MMAF(1, 1, At, B1); PG8_BAR; PG8_SCHED;
;             PG8_LDB(B0, 1, 0); PG8_LDB(B1, 1, 1); PG8_SCHED; PG8_LDA(At, 1, 0); if (!fin) PG8_STAGE(PG8_SA(0, 1), a2 + hstep, voffA);
;             if (!fin) PG8_WAIT_V(8); else PG8_WAIT_V(0); PG8_WAIT_L(0); PG8_BAR; PG8_MMA(0, 0, At, B0); PG8_MMA(0, 1, At, B1); PG8_BAR; PG8_SCHED;
;             PG8_LDA(At, 1, 1); if (!fin) { PG8_STAGE(PG8_SB(1, 0), b3, voffB); PG8_STAGE(PG8_SB(1, 1), b3 + hstep, voffB); PG8_STAGE(PG8_SA(1, 0), a3, voffA); }
;             if (!fin) PG8_WAIT_V(8); PG8_WAIT_L(0); PG8_BAR; PG8_MMA(1, 0, At, B0); PG8_MMA(1, 1, At, B1); PG8_BAR; PG8_SCHED;
	v_mfma_f32_16x16x32_f16 v[10:13], v[26:29], v[110:113], 0
	v_mfma_f32_16x16x32_f16 v[118:121], v[30:33], v[118:121], v[10:13]
	v_mfma_f32_16x16x32_f16 v[10:13], v[18:21], v[122:125], 0
	v_mfma_f32_16x16x32_f16 v[186:189], v[22:25], v[126:129], v[10:13]
	v_mfma_f32_16x16x32_f16 v[10:13], v[26:29], v[122:125], 0
	v_mfma_f32_16x16x32_f16 v[122:125], v[30:33], v[126:129], v[10:13]
	s_setprio 0
	s_nop 4
	ds_read_b128 v[10:13], v216
	ds_read_b128 v[14:17], v216 offset:1024
	ds_read_b128 v[18:21], v216 offset:2048
	ds_read_b128 v[22:25], v216 offset:3072
	ds_read_b128 v[190:193], v217
	ds_read_b128 v[194:197], v217 offset:1024
	ds_read_b128 v[198:201], v217 offset:2048
	ds_read_b128 v[202:205], v217 offset:3072
	ds_read_b128 v[26:29], v215 offset:32768
	ds_read_b128 v[30:33], v215 offset:33792
	ds_read_b128 v[62:65], v215 offset:34816
	ds_read_b128 v[218:221], v215 offset:35840
	ds_read_b128 v[222:225], v215 offset:36864
	ds_read_b128 v[226:229], v215 offset:37888
	ds_read_b128 v[230:233], v215 offset:38912
	ds_read_b128 v[234:237], v215 offset:39936
	s_add_u32 s24, s36, 0x40100
	s_addc_u32 s25, s37, 0
	s_add_u32 m0, s35, 0x4000
	s_nop 0
	global_load_lds_dwordx4 v1, s[24:25]
	s_nop 0
	s_add_u32 m0, s35, 0x6000
	s_nop 0
	global_load_lds_dwordx4 v211, s[24:25]
	s_waitcnt vmcnt(8)
	s_waitcnt lgkmcnt(0)
	s_barrier
	v_mfma_f32_16x16x32_f16 v[66:69], v[10:13], v[26:29], v[66:69]
	s_setprio 1
	v_mfma_f32_16x16x32_f16 v[142:145], v[14:17], v[30:33], v[66:69]
	v_mfma_f32_16x16x32_f16 v[66:69], v[18:21], v[26:29], v[70:73]
	v_mfma_f32_16x16x32_f16 v[138:141], v[22:25], v[30:33], v[66:69]
	v_mfma_f32_16x16x32_f16 v[66:69], v[10:13], v[62:65], v[74:77]
	v_mfma_f32_16x16x32_f16 v[110:113], v[14:17], v[218:221], v[66:69]
	v_mfma_f32_16x16x32_f16 v[66:69], v[18:21], v[62:65], v[78:81]
	v_mfma_f32_16x16x32_f16 v[106:109], v[22:25], v[218:221], v[66:69]
	v_mfma_f32_16x16x32_f16 v[66:69], v[10:13], v[222:225], v[82:85]
	v_mfma_f32_16x16x32_f16 v[94:97], v[14:17], v[226:229], v[66:69]
	v_mfma_f32_16x16x32_f16 v[66:69], v[18:21], v[222:225], v[86:89]
	v_mfma_f32_16x16x32_f16 v[90:93], v[22:25], v[226:229], v[66:69]
	v_mfma_f32_16x16x32_f16 v[66:69], v[10:13], v[230:233], v[98:101]
	v_mfma_f32_16x16x32_f16 v[78:81], v[14:17], v[234:237], v[66:69]
	v_mfma_f32_16x16x32_f16 v[66:69], v[18:21], v[230:233], v[102:105]
	v_mfma_f32_16x16x32_f16 v[74:77], v[22:25], v[234:237], v[66:69]
	v_mfma_f32_16x16x32_f16 v[66:69], v[190:193], v[26:29], v[114:117]
	v_mfma_f32_16x16x32_f16 v[134:137], v[194:197], v[30:33], v[66:69]
	v_mfma_f32_16x16x32_f16 v[26:29], v[198:201], v[26:29], v[34:37]
	v_mfma_f32_16x16x32_f16 v[126:129], v[202:205], v[30:33], v[26:29]
	v_mfma_f32_16x16x32_f16 v[26:29], v[190:193], v[62:65], v[38:41]
	v_mfma_f32_16x16x32_f16 v[102:105], v[194:197], v[218:221], v[26:29]
	v_mfma_f32_16x16x32_f16 v[26:29], v[198:201], v[62:65], v[42:45]
	v_mfma_f32_16x16x32_f16 v[98:101], v[202:205], v[218:221], v[26:29]
	v_mfma_f32_16x16x32_f16 v[26:29], v[190:193], v[222:225], v[46:49]
	v_mfma_f32_16x16x32_f16 v[86:89], v[194:197], v[226:229], v[26:29]
	s_barrier
	v_mfma_f32_16x16x32_f16 v[26:29], v[198:201], v[222:225], v[50:53]
	v_mfma_f32_16x16x32_f16 v[82:85], v[202:205], v[226:229], v[26:29]
	v_mfma_f32_16x16x32_f16 v[26:29], v[190:193], v[230:233], v[54:57]
	v_mfma_f32_16x16x32_f16 v[70:73], v[194:197], v[234:237], v[26:29]
	v_mfma_f32_16x16x32_f16 v[26:29], v[198:201], v[230:233], v[58:61]
	v_mfma_f32_16x16x32_f16 v[66:69], v[202:205], v[234:237], v[26:29]
	s_setprio 0
	ds_read_b128 v[34:37], v215 offset:49152
	ds_read_b128 v[38:41], v215 offset:50176
	ds_read_b128 v[114:117], v215 offset:51200
	ds_read_b128 v[218:221], v215 offset:52224
	ds_read_b128 v[222:225], v215 offset:53248
	ds_read_b128 v[226:229], v215 offset:54272
	ds_read_b128 v[230:233], v215 offset:55296
	ds_read_b128 v[234:237], v215 offset:56320
	s_add_u32 m0, s35, 0x18000
	s_nop 0
	global_load_lds_dwordx4 v210, s[8:9]
	s_nop 0
	s_add_u32 m0, s35, 0x1a000
	s_nop 0
	global_load_lds_dwordx4 v212, s[8:9]
	s_add_u32 s8, s38, 0x40180
	s_addc_u32 s9, s39, 0
	s_add_u32 m0, s35, 0x1c000
	s_nop 0
	global_load_lds_dwordx4 v210, s[8:9]
	s_nop 0
	s_add_u32 m0, s35, 0x1e000
	s_nop 0
	global_load_lds_dwordx4 v212, s[8:9]
	s_nop 0
	s_add_u32 m0, s35, 0x8000
	s_nop 0
	global_load_lds_dwordx4 v1, s[6:7]
	s_nop 0
	s_add_u32 m0, s35, 0xa000
	s_nop 0
	global_load_lds_dwordx4 v211, s[6:7]
	s_waitcnt vmcnt(8)
	s_waitcnt lgkmcnt(0)
	s_barrier
	v_mfma_f32_16x16x32_f16 v[26:29], v[10:13], v[34:37], v[130:133]
	s_setprio 1
	v_mfma_f32_16x16x32_f16 v[62:65], v[14:17], v[38:41], v[26:29]
	v_mfma_f32_16x16x32_f16 v[26:29], v[22:25], v[38:41], v[146:149]
	v_mfma_f32_16x16x32_f16 v[58:61], v[18:21], v[34:37], v[26:29]
	v_mfma_f32_16x16x32_f16 v[26:29], v[10:13], v[114:117], v[150:153]
	v_mfma_f32_16x16x32_f16 v[46:49], v[14:17], v[218:221], v[26:29]
	v_mfma_f32_16x16x32_f16 v[26:29], v[22:25], v[218:221], v[154:157]
	v_mfma_f32_16x16x32_f16 v[42:45], v[18:21], v[114:117], v[26:29]
	v_mfma_f32_16x16x32_f16 v[26:29], v[10:13], v[222:225], v[158:161]
	v_mfma_f32_16x16x32_f16 v[30:33], v[14:17], v[226:229], v[26:29]
	v_mfma_f32_16x16x32_f16 v[2:5], v[14:17], v[234:237], v[2:5]
	v_mfma_f32_16x16x32_f16 v[14:17], v[10:13], v[230:233], v[2:5]
	v_mfma_f32_16x16x32_f16 v[2:5], v[18:21], v[230:233], v[6:9]
	v_mfma_f32_16x16x32_f16 v[10:13], v[22:25], v[234:237], v[2:5]
	v_mfma_f32_16x16x32_f16 v[26:29], v[22:25], v[226:229], v[162:165]
	v_mfma_f32_16x16x32_f16 v[26:29], v[18:21], v[222:225], v[26:29]
	v_mfma_f32_16x16x32_f16 v[2:5], v[190:193], v[34:37], v[166:169]
	v_mfma_f32_16x16x32_f16 v[54:57], v[194:197], v[38:41], v[2:5]
	v_mfma_f32_16x16x32_f16 v[2:5], v[202:205], v[38:41], v[170:173]
	v_mfma_f32_16x16x32_f16 v[50:53], v[198:201], v[34:37], v[2:5]
	v_mfma_f32_16x16x32_f16 v[2:5], v[190:193], v[114:117], v[174:177]
	v_mfma_f32_16x16x32_f16 v[38:41], v[194:197], v[218:221], v[2:5]
	v_mfma_f32_16x16x32_f16 v[2:5], v[202:205], v[218:221], v[178:181]
	v_mfma_f32_16x16x32_f16 v[34:37], v[198:201], v[114:117], v[2:5]
	v_mfma_f32_16x16x32_f16 v[2:5], v[190:193], v[222:225], v[182:185]
	v_mfma_f32_16x16x32_f16 v[22:25], v[194:197], v[226:229], v[2:5]
	s_barrier
	v_mfma_f32_16x16x32_f16 v[2:5], v[202:205], v[226:229], v[118:121]
	v_mfma_f32_16x16x32_f16 v[18:21], v[198:201], v[222:225], v[2:5]
	v_mfma_f32_16x16x32_f16 v[2:5], v[190:193], v[230:233], v[186:189]
	v_mfma_f32_16x16x32_f16 v[6:9], v[194:197], v[234:237], v[2:5]
	v_mfma_f32_16x16x32_f16 v[2:5], v[202:205], v[234:237], v[122:125]
	v_mfma_f32_16x16x32_f16 v[2:5], v[198:201], v[230:233], v[2:5]
	s_setprio 0
	s_mov_b32 s58, 0
	s_mov_b64 s[54:55], 0
	s_branch .LBB0_1165
; #define PG8_STAGE(bufoff, gbase, voff) do { if constexpr (ABL & 1) break; glds16s<(bufoff)>((voff)[0], (const void*)(gbase), ldsbw); glds16s<(bufoff) + 8192>((voff)[1], (const void*)(gbase), ldsbw); } while (0)
; #define PG8_LDA(dst, b, h) do { if constexpr (ABL & 4) break; _Pragma("unroll") for (int m = 0; m < 4; ++m) _Pragma("unroll") for (int k = 0; k < 2; ++k) dst[m][k] = *(const LAS f16x8*)(lds + PG8_SA(b, h) + aoff + m * 2048 + k * 1024); } while (0)
; #define PG8_LDB(dst, b, h) do { if constexpr (ABL & 4) break; _Pragma("unroll") for (int n = 0; n < 2; ++n) _Pragma("unroll") for (int k = 0; k < 2; ++k) dst[n][k] = *(const LAS f16x8*)(lds + PG8_SB(b, h) + boff + n * 2048 + k * 1024); } while (0)
; #define PG8_MMA(ai, bj, At, Bt) do { if constexpr (ABL & 2) break; __builtin_amdgcn_s_setprio(1); _Pragma("unroll") for (int m = 0; m < 4; ++m) _Pragma("unroll") for (int n = 0; n < 2; ++n) _Pragma("unroll") for (int k = 0; k < 2; ++k) \
;         acc[ai][bj][m][n] = __builtin_amdgcn_mfma_f32_16x16x32_f16(Bt[n][k], At[m][k], acc[ai][bj][m][n], 0, 0, 0); __builtin_amdgcn_s_setprio(0); } while (0)
; #define PG8_BAR __builtin_amdgcn_s_barrier()
;     ...
;             if constexpr (SP2) {
;             PG8_LDB(B0, 0, 0); PG8_LDB(B1, 0, 1); PG8_SCHED; PG8_LDA(At, 0, 0); PG8_STAGE(PG8_SA(1, 1), a1 + hstep, voffA);
;             PG8_WAIT_V(8); PG8_WAIT_L(0); PG8_BAR; PG8_MMAF(0, 0, At, B0); PG8_MMAF(0, 1, At, B1); PG8_BAR; PG8_SCHED;
;             const bool fin = last && !has_next;
;             PG8_LDA(At, 0, 1); if (!fin) { PG8_STAGE(PG8_SB(0, 0), b2, voffB); PG8_STAGE(PG8_SB(0, 1), b2 + hstep, voffB); PG8_STAGE(PG8_SA(0, 0), a2, voffA); }
;             if (!fin) PG8_WAIT_V(8); else PG8_WAIT_V(2); PG8_WAIT_L(0); PG8_BAR; PG8_MMAF(1, 0, At, B0); PG8_MMAF(1, 1, At, B1); PG8_BAR; PG8_SCHED;
;             PG8_LDB(B0, 1, 0); PG8_LDB(B1, 1, 1); PG8_SCHED; PG8_LDA(At, 1, 0); if (!fin) PG8_STAGE(PG8_SA(0, 1), a2 + hstep, voffA);
;             if (!fin) PG8_WAIT_V(8); else PG8_WAIT_V(0); PG8_WAIT_L(0); PG8_BAR; PG8_MMA(0, 0, At, B0); PG8_MMA(0, 1, At, B1); PG8_BAR; PG8_SCHED;
;             PG8_LDA(At, 1, 1); if (!fin) { PG8_STAGE(PG8_SB(1, 0), b3, voffB); PG8_STAGE(PG8_SB(1, 1), b3 + hstep, voffB); PG8_STAGE(PG8_SA(1, 0), a3, voffA); }
;             if (!fin) PG8_WAIT_V(8); PG8_WAIT_L(0); PG8_BAR; PG8_MMA(1, 0, At, B0); PG8_MMA(1, 1, At, B1); PG8_BAR; PG8_SCHED;
.LBB0_1164:
	s_waitcnt lgkmcnt(0)
	s_barrier
	v_mfma_f32_16x16x32_f16 v[62:65], v[158:161], v[186:189], v[62:65]
	s_setprio 1
	v_mfma_f32_16x16x32_f16 v[62:65], v[162:165], v[190:193], v[62:65]
	v_mfma_f32_16x16x32_f16 v[58:61], v[170:173], v[190:193], v[58:61]
	v_mfma_f32_16x16x32_f16 v[58:61], v[166:169], v[186:189], v[58:61]
	v_mfma_f32_16x16x32_f16 v[42:45], v[166:169], v[178:181], v[42:45]
	v_mfma_f32_16x16x32_f16 v[42:45], v[170:173], v[182:185], v[42:45]
	v_mfma_f32_16x16x32_f16 v[46:49], v[162:165], v[182:185], v[46:49]
	v_mfma_f32_16x16x32_f16 v[46:49], v[158:161], v[178:181], v[46:49]
	v_mfma_f32_16x16x32_f16 v[30:33], v[158:161], v[122:125], v[30:33]
	v_mfma_f32_16x16x32_f16 v[30:33], v[162:165], v[174:177], v[30:33]
	v_mfma_f32_16x16x32_f16 v[26:29], v[170:173], v[174:177], v[26:29]
	v_mfma_f32_16x16x32_f16 v[26:29], v[166:169], v[122:125], v[26:29]
	v_mfma_f32_16x16x32_f16 v[10:13], v[166:169], v[114:117], v[10:13]
	v_mfma_f32_16x16x32_f16 v[10:13], v[170:173], v[118:121], v[10:13]
	v_mfma_f32_16x16x32_f16 v[14:17], v[162:165], v[118:121], v[14:17]
	v_mfma_f32_16x16x32_f16 v[14:17], v[158:161], v[114:117], v[14:17]
	v_mfma_f32_16x16x32_f16 v[6:9], v[130:133], v[114:117], v[6:9]
	v_mfma_f32_16x16x32_f16 v[6:9], v[146:149], v[118:121], v[6:9]
	v_mfma_f32_16x16x32_f16 v[54:57], v[146:149], v[190:193], v[54:57]
	v_mfma_f32_16x16x32_f16 v[54:57], v[130:133], v[186:189], v[54:57]
	v_mfma_f32_16x16x32_f16 v[50:53], v[150:153], v[186:189], v[50:53]
	v_mfma_f32_16x16x32_f16 v[50:53], v[154:157], v[190:193], v[50:53]
	v_mfma_f32_16x16x32_f16 v[34:37], v[154:157], v[182:185], v[34:37]
	v_mfma_f32_16x16x32_f16 v[34:37], v[150:153], v[178:181], v[34:37]
	v_mfma_f32_16x16x32_f16 v[38:41], v[130:133], v[178:181], v[38:41]
	v_mfma_f32_16x16x32_f16 v[38:41], v[146:149], v[182:185], v[38:41]
	s_barrier
	v_mfma_f32_16x16x32_f16 v[22:25], v[146:149], v[174:177], v[22:25]
	v_mfma_f32_16x16x32_f16 v[22:25], v[130:133], v[122:125], v[22:25]
	v_mfma_f32_16x16x32_f16 v[18:21], v[150:153], v[122:125], v[18:21]
	v_mfma_f32_16x16x32_f16 v[18:21], v[154:157], v[174:177], v[18:21]
	v_mfma_f32_16x16x32_f16 v[2:5], v[154:157], v[118:121], v[2:5]
	v_mfma_f32_16x16x32_f16 v[2:5], v[150:153], v[114:117], v[2:5]
	s_setprio 0
	s_add_i32 s58, s58, 2
	s_add_u32 s54, s54, 0x100
	s_addc_u32 s55, s55, 0
	s_cmp_gt_u32 s58, 13
	s_cbranch_scc1 .LBB0_1175
.LBB0_1165:
	s_add_u32 s26, s36, s54
	s_addc_u32 s27, s37, s55
	ds_read_b128 v[158:161], v213
	ds_read_b128 v[162:165], v213 offset:1024
	ds_read_b128 v[166:169], v213 offset:2048
	ds_read_b128 v[170:173], v213 offset:3072
	ds_read_b128 v[130:133], v214
	ds_read_b128 v[146:149], v214 offset:1024
	ds_read_b128 v[150:153], v214 offset:2048
	ds_read_b128 v[154:157], v214 offset:3072
	s_add_u32 s24, s26, 0x200
	s_addc_u32 s25, s27, 0
	s_add_u32 s6, s38, s54
	s_addc_u32 s7, s39, s55
	s_add_u32 s59, s6, 0x200
	s_addc_u32 s60, s7, 0
	s_cmp_eq_u32 s58, 12
	s_cselect_b64 s[6:7], -1, 0
	s_and_b64 s[8:9], s[6:7], exec
	s_cselect_b32 s25, s45, s25
	s_cselect_b32 s24, s49, s24
	s_cselect_b32 s9, s47, s60
	s_cselect_b32 s8, s57, s59
	ds_read_b128 v[174:177], v215
	ds_read_b128 v[178:181], v215 offset:1024
	ds_read_b128 v[182:185], v215 offset:2048
	ds_read_b128 v[186:189], v215 offset:3072
	ds_read_b128 v[190:193], v215 offset:4096
	ds_read_b128 v[194:197], v215 offset:5120
	ds_read_b128 v[198:201], v215 offset:6144
	ds_read_b128 v[202:205], v215 offset:7168
	s_add_u32 s26, s26, 0x40180
	s_addc_u32 s27, s27, 0
	s_add_u32 m0, s35, 0xc000
	s_nop 0
	global_load_lds_dwordx4 v1, s[26:27]
	s_nop 0
	s_add_u32 m0, s35, 0xe000
	s_nop 0
	global_load_lds_dwordx4 v211, s[26:27]
	s_waitcnt vmcnt(8)
	s_waitcnt lgkmcnt(0)
	s_barrier
	v_mfma_f32_16x16x32_f16 v[114:117], v[158:161], v[174:177], v[142:145]
	s_setprio 1
	v_mfma_f32_16x16x32_f16 v[114:117], v[162:165], v[178:181], v[114:117]
	v_mfma_f32_16x16x32_f16 v[118:121], v[170:173], v[178:181], v[138:141]
	v_mfma_f32_16x16x32_f16 v[118:121], v[166:169], v[174:177], v[118:121]
	v_mfma_f32_16x16x32_f16 v[106:109], v[166:169], v[182:185], v[106:109]
	v_mfma_f32_16x16x32_f16 v[106:109], v[170:173], v[186:189], v[106:109]
	v_mfma_f32_16x16x32_f16 v[110:113], v[162:165], v[186:189], v[110:113]
	v_mfma_f32_16x16x32_f16 v[110:113], v[158:161], v[182:185], v[110:113]
	v_mfma_f32_16x16x32_f16 v[94:97], v[158:161], v[190:193], v[94:97]
	v_mfma_f32_16x16x32_f16 v[94:97], v[162:165], v[194:197], v[94:97]
	v_mfma_f32_16x16x32_f16 v[90:93], v[170:173], v[194:197], v[90:93]
	v_mfma_f32_16x16x32_f16 v[90:93], v[166:169], v[190:193], v[90:93]
	v_mfma_f32_16x16x32_f16 v[74:77], v[166:169], v[198:201], v[74:77]
	v_mfma_f32_16x16x32_f16 v[74:77], v[170:173], v[202:205], v[74:77]
	v_mfma_f32_16x16x32_f16 v[78:81], v[162:165], v[202:205], v[78:81]
	v_mfma_f32_16x16x32_f16 v[78:81], v[158:161], v[198:201], v[78:81]
	v_mfma_f32_16x16x32_f16 v[70:73], v[130:133], v[198:201], v[70:73]
	v_mfma_f32_16x16x32_f16 v[70:73], v[146:149], v[202:205], v[70:73]
	v_mfma_f32_16x16x32_f16 v[122:125], v[146:149], v[178:181], v[134:137]
	v_mfma_f32_16x16x32_f16 v[122:125], v[130:133], v[174:177], v[122:125]
	v_mfma_f32_16x16x32_f16 v[126:129], v[150:153], v[174:177], v[126:129]
	v_mfma_f32_16x16x32_f16 v[126:129], v[154:157], v[178:181], v[126:129]
	v_mfma_f32_16x16x32_f16 v[98:101], v[154:157], v[186:189], v[98:101]
	v_mfma_f32_16x16x32_f16 v[98:101], v[150:153], v[182:185], v[98:101]
	v_mfma_f32_16x16x32_f16 v[102:105], v[130:133], v[182:185], v[102:105]
	v_mfma_f32_16x16x32_f16 v[102:105], v[146:149], v[186:189], v[102:105]
	s_barrier
	v_mfma_f32_16x16x32_f16 v[86:89], v[146:149], v[194:197], v[86:89]
	v_mfma_f32_16x16x32_f16 v[86:89], v[130:133], v[190:193], v[86:89]
	v_mfma_f32_16x16x32_f16 v[82:85], v[150:153], v[190:193], v[82:85]
	v_mfma_f32_16x16x32_f16 v[82:85], v[154:157], v[194:197], v[82:85]
	v_mfma_f32_16x16x32_f16 v[66:69], v[154:157], v[202:205], v[66:69]
	v_mfma_f32_16x16x32_f16 v[66:69], v[150:153], v[198:201], v[66:69]
	s_setprio 0
	ds_read_b128 v[186:189], v215 offset:16384
	ds_read_b128 v[190:193], v215 offset:17408
	ds_read_b128 v[178:181], v215 offset:18432
	ds_read_b128 v[182:185], v215 offset:19456
	ds_read_b128 v[142:145], v215 offset:20480
	ds_read_b128 v[174:177], v215 offset:21504
	ds_read_b128 v[134:137], v215 offset:22528
	ds_read_b128 v[138:141], v215 offset:23552
	s_and_b64 s[6:7], s[2:3], s[6:7]
	s_mov_b64 s[26:27], -1
	s_and_b64 vcc, exec, s[6:7]
	s_cbranch_vccnz .LBB0_1167
	s_add_u32 m0, s35, 0x10000
	s_nop 0
	global_load_lds_dwordx4 v210, s[8:9]
	s_nop 0
	s_add_u32 m0, s35, 0x12000
	s_nop 0
	global_load_lds_dwordx4 v212, s[8:9]
	s_add_u32 s26, s8, 0x40000
	s_addc_u32 s27, s9, 0
	s_add_u32 m0, s35, 0x14000
	s_nop 0
	global_load_lds_dwordx4 v210, s[26:27]
	s_nop 0
	s_add_u32 m0, s35, 0x16000
	s_nop 0
	global_load_lds_dwordx4 v212, s[26:27]
	s_mov_b64 s[26:27], 0
	s_add_u32 m0, s35, 0
	s_nop 0
	global_load_lds_dwordx4 v1, s[24:25]
	s_nop 0
	s_add_u32 m0, s35, 0x2000
	s_nop 0
	global_load_lds_dwordx4 v211, s[24:25]
	s_waitcnt vmcnt(8)

; #define PG8_STAGE(bufoff, gbase, voff) do { if constexpr (ABL & 1) break; glds16s<(bufoff)>((voff)[0], (const void*)(gbase), ldsbw); glds16s<(bufoff) + 8192>((voff)[1], (const void*)(gbase), ldsbw); } while (0)
; #define PG8_LDA(dst, b, h) do { if constexpr (ABL & 4) break; _Pragma("unroll") for (int m = 0; m < 4; ++m) _Pragma("unroll") for (int k = 0; k < 2; ++k) dst[m][k] = *(const LAS f16x8*)(lds + PG8_SA(b, h) + aoff + m * 2048 + k * 1024); } while (0)
; #define PG8_LDB(dst, b, h) do { if constexpr (ABL & 4) break; _Pragma("unroll") for (int n = 0; n < 2; ++n) _Pragma("unroll") for (int k = 0; k < 2; ++k) dst[n][k] = *(const LAS f16x8*)(lds + PG8_SB(b, h) + boff + n * 2048 + k * 1024); } while (0)
; #define PG8_MMAF(ai, bj, At, Bt) do { if (t == 0) PG8_MMA0(ai, bj, At, Bt); else PG8_MMA(ai, bj, At, Bt); } while (0)
; #define PG8_WAIT_V(n) asm volatile("s_waitcnt vmcnt(" #n ")" ::: "memory")
; #define PG8_WAIT_L(n) asm volatile("s_waitcnt lgkmcnt(" #n ")" ::: "memory")
; #define PG8_BAR __builtin_amdgcn_s_barrier()
; #define PG8_SCHED __builtin_amdgcn_sched_barrier(0)
;     ...
;             if constexpr (SP2) {
;             PG8_LDB(B0, 0, 0); PG8_LDB(B1, 0, 1); PG8_SCHED; PG8_LDA(At, 0, 0); PG8_STAGE(PG8_SA(1, 1), a1 + hstep, voffA);
;             PG8_WAIT_V(8); PG8_WAIT_L(0); PG8_BAR; PG8_MMAF(0, 0, At, B0); PG8_MMAF(0, 1, At, B1); PG8_BAR; PG8_SCHED;
;             const bool fin = last && !has_next;
;             PG8_LDA(At, 0, 1); if (!fin) { PG8_STAGE(PG8_SB(0, 0), b2, voffB); PG8_STAGE(PG8_SB(0, 1), b2 + hstep, voffB); PG8_STAGE(PG8_SA(0, 0), a2, voffA); }
;             if (!fin) PG8_WAIT_V(8); else PG8_WAIT_V(2); PG8_WAIT_L(0); PG8_BAR; PG8_MMAF(1, 0, At, B0); PG8_MMAF(1, 1, At, B1); PG8_BAR; PG8_SCHED;
;             PG8_LDB(B0, 1, 0); PG8_LDB(B1, 1, 1); PG8_SCHED; PG8_LDA(At, 1, 0); if (!fin) PG8_STAGE(PG8_SA(0, 1), a2 + hstep, voffA);
.LBB0_1169:
	s_waitcnt lgkmcnt(0)
	s_xor_b64 s[26:27], s[6:7], -1
	s_barrier
	v_mfma_f32_16x16x32_f16 v[62:65], v[158:161], v[186:189], v[62:65]
	s_setprio 1
	v_mfma_f32_16x16x32_f16 v[62:65], v[162:165], v[190:193], v[62:65]
	v_mfma_f32_16x16x32_f16 v[58:61], v[170:173], v[190:193], v[58:61]
	v_mfma_f32_16x16x32_f16 v[58:61], v[166:169], v[186:189], v[58:61]
	v_mfma_f32_16x16x32_f16 v[42:45], v[166:169], v[178:181], v[42:45]
	v_mfma_f32_16x16x32_f16 v[42:45], v[170:173], v[182:185], v[42:45]
	v_mfma_f32_16x16x32_f16 v[46:49], v[162:165], v[182:185], v[46:49]
	v_mfma_f32_16x16x32_f16 v[46:49], v[158:161], v[178:181], v[46:49]
	v_mfma_f32_16x16x32_f16 v[30:33], v[158:161], v[142:145], v[30:33]
	v_mfma_f32_16x16x32_f16 v[30:33], v[162:165], v[174:177], v[30:33]
	v_mfma_f32_16x16x32_f16 v[26:29], v[170:173], v[174:177], v[26:29]
	v_mfma_f32_16x16x32_f16 v[26:29], v[166:169], v[142:145], v[26:29]
	v_mfma_f32_16x16x32_f16 v[10:13], v[166:169], v[134:137], v[10:13]
	v_mfma_f32_16x16x32_f16 v[10:13], v[170:173], v[138:141], v[10:13]
	v_mfma_f32_16x16x32_f16 v[14:17], v[162:165], v[138:141], v[14:17]
	v_mfma_f32_16x16x32_f16 v[14:17], v[158:161], v[134:137], v[14:17]
	v_mfma_f32_16x16x32_f16 v[6:9], v[130:133], v[134:137], v[6:9]
	v_mfma_f32_16x16x32_f16 v[6:9], v[146:149], v[138:141], v[6:9]
	v_mfma_f32_16x16x32_f16 v[54:57], v[146:149], v[190:193], v[54:57]
	v_mfma_f32_16x16x32_f16 v[54:57], v[130:133], v[186:189], v[54:57]
	v_mfma_f32_16x16x32_f16 v[50:53], v[150:153], v[186:189], v[50:53]
	v_mfma_f32_16x16x32_f16 v[50:53], v[154:157], v[190:193], v[50:53]
	v_mfma_f32_16x16x32_f16 v[34:37], v[154:157], v[182:185], v[34:37]
	v_mfma_f32_16x16x32_f16 v[34:37], v[150:153], v[178:181], v[34:37]
	v_mfma_f32_16x16x32_f16 v[38:41], v[130:133], v[178:181], v[38:41]
	v_mfma_f32_16x16x32_f16 v[38:41], v[146:149], v[182:185], v[38:41]
	s_barrier
	v_mfma_f32_16x16x32_f16 v[22:25], v[146:149], v[174:177], v[22:25]
	v_mfma_f32_16x16x32_f16 v[22:25], v[130:133], v[142:145], v[22:25]
	v_mfma_f32_16x16x32_f16 v[18:21], v[150:153], v[142:145], v[18:21]
	v_mfma_f32_16x16x32_f16 v[18:21], v[154:157], v[174:177], v[18:21]
	v_mfma_f32_16x16x32_f16 v[2:5], v[154:157], v[138:141], v[2:5]
	v_mfma_f32_16x16x32_f16 v[2:5], v[150:153], v[134:137], v[2:5]
	s_setprio 0
	ds_read_b128 v[158:161], v216
	ds_read_b128 v[162:165], v216 offset:1024
	ds_read_b128 v[166:169], v216 offset:2048
	ds_read_b128 v[170:173], v216 offset:3072
	ds_read_b128 v[130:133], v217
	ds_read_b128 v[146:149], v217 offset:1024
	ds_read_b128 v[150:153], v217 offset:2048
	ds_read_b128 v[154:157], v217 offset:3072
	ds_read_b128 v[198:201], v215 offset:32768
	ds_read_b128 v[202:205], v215 offset:33792
	ds_read_b128 v[190:193], v215 offset:34816
	ds_read_b128 v[194:197], v215 offset:35840
	ds_read_b128 v[182:185], v215 offset:36864
	ds_read_b128 v[186:189], v215 offset:37888
	ds_read_b128 v[174:177], v215 offset:38912
	ds_read_b128 v[178:181], v215 offset:39936
	v_cndmask_b32_e64 v134, 0, 1, s[26:27]
	v_cmp_ne_u32_e64 s[6:7], 1, v134
	s_andn2_b64 vcc, exec, s[26:27]
	s_mov_b64 s[26:27], -1
	s_cbranch_vccnz .LBB0_1171
	s_add_u32 s26, s24, 0x40000
	s_addc_u32 s27, s25, 0
	s_add_u32 m0, s35, 0x4000
	s_nop 0
	global_load_lds_dwordx4 v1, s[26:27]
	s_nop 0
	s_add_u32 m0, s35, 0x6000
	s_nop 0
	global_load_lds_dwordx4 v211, s[26:27]
	s_waitcnt vmcnt(8)
	s_mov_b64 s[26:27], 0

; #define PG8_STAGE(bufoff, gbase, voff) do { if constexpr (ABL & 1) break; glds16s<(bufoff)>((voff)[0], (const void*)(gbase), ldsbw); glds16s<(bufoff) + 8192>((voff)[1], (const void*)(gbase), ldsbw); } while (0)
; #define PG8_LDA(dst, b, h) do { if constexpr (ABL & 4) break; _Pragma("unroll") for (int m = 0; m < 4; ++m) _Pragma("unroll") for (int k = 0; k < 2; ++k) dst[m][k] = *(const LAS f16x8*)(lds + PG8_SA(b, h) + aoff + m * 2048 + k * 1024); } while (0)
; #define PG8_LDB(dst, b, h) do { if constexpr (ABL & 4) break; _Pragma("unroll") for (int n = 0; n < 2; ++n) _Pragma("unroll") for (int k = 0; k < 2; ++k) dst[n][k] = *(const LAS f16x8*)(lds + PG8_SB(b, h) + boff + n * 2048 + k * 1024); } while (0)
; #define PG8_MMA(ai, bj, At, Bt) do { if constexpr (ABL & 2) break; __builtin_amdgcn_s_setprio(1); _Pragma("unroll") for (int m = 0; m < 4; ++m) _Pragma("unroll") for (int n = 0; n < 2; ++n) _Pragma("unroll") for (int k = 0; k < 2; ++k) \
;         acc[ai][bj][m][n] = __builtin_amdgcn_mfma_f32_16x16x32_f16(Bt[n][k], At[m][k], acc[ai][bj][m][n], 0, 0, 0); __builtin_amdgcn_s_setprio(0); } while (0)
; #define PG8_WAIT_V(n) asm volatile("s_waitcnt vmcnt(" #n ")" ::: "memory")
; #define PG8_WAIT_L(n) asm volatile("s_waitcnt lgkmcnt(" #n ")" ::: "memory")
; #define PG8_BAR __builtin_amdgcn_s_barrier()
; #define PG8_SCHED __builtin_amdgcn_sched_barrier(0)
;     ...
;             PG8_LDB(B0, 1, 0); PG8_LDB(B1, 1, 1); PG8_SCHED; PG8_LDA(At, 1, 0); if (!fin) PG8_STAGE(PG8_SA(0, 1), a2 + hstep, voffA);
;             if (!fin) PG8_WAIT_V(8); else PG8_WAIT_V(0); PG8_WAIT_L(0); PG8_BAR; PG8_MMA(0, 0, At, B0); PG8_MMA(0, 1, At, B1); PG8_BAR; PG8_SCHED;
;             PG8_LDA(At, 1, 1); if (!fin) { PG8_STAGE(PG8_SB(1, 0), b3, voffB); PG8_STAGE(PG8_SB(1, 1), b3 + hstep, voffB); PG8_STAGE(PG8_SA(1, 0), a3, voffA); }
;             if (!fin) PG8_WAIT_V(8); PG8_WAIT_L(0); PG8_BAR; PG8_MMA(1, 0, At, B0); PG8_MMA(1, 1, At, B1); PG8_BAR; PG8_SCHED;
.LBB0_1173:
	s_waitcnt lgkmcnt(0)
	s_barrier
	v_mfma_f32_16x16x32_f16 v[114:117], v[158:161], v[198:201], v[114:117]
	s_setprio 1
	v_mfma_f32_16x16x32_f16 v[142:145], v[162:165], v[202:205], v[114:117]
	v_mfma_f32_16x16x32_f16 v[114:117], v[170:173], v[202:205], v[118:121]
	v_mfma_f32_16x16x32_f16 v[138:141], v[166:169], v[198:201], v[114:117]
	v_mfma_f32_16x16x32_f16 v[106:109], v[166:169], v[190:193], v[106:109]
	v_mfma_f32_16x16x32_f16 v[106:109], v[170:173], v[194:197], v[106:109]
	v_mfma_f32_16x16x32_f16 v[110:113], v[162:165], v[194:197], v[110:113]
	v_mfma_f32_16x16x32_f16 v[110:113], v[158:161], v[190:193], v[110:113]
	v_mfma_f32_16x16x32_f16 v[94:97], v[158:161], v[182:185], v[94:97]
	v_mfma_f32_16x16x32_f16 v[94:97], v[162:165], v[186:189], v[94:97]
	v_mfma_f32_16x16x32_f16 v[90:93], v[170:173], v[186:189], v[90:93]
	v_mfma_f32_16x16x32_f16 v[90:93], v[166:169], v[182:185], v[90:93]
	v_mfma_f32_16x16x32_f16 v[74:77], v[166:169], v[174:177], v[74:77]
	v_mfma_f32_16x16x32_f16 v[74:77], v[170:173], v[178:181], v[74:77]
	v_mfma_f32_16x16x32_f16 v[78:81], v[162:165], v[178:181], v[78:81]
	v_mfma_f32_16x16x32_f16 v[78:81], v[158:161], v[174:177], v[78:81]
	v_mfma_f32_16x16x32_f16 v[70:73], v[130:133], v[174:177], v[70:73]
	v_mfma_f32_16x16x32_f16 v[70:73], v[146:149], v[178:181], v[70:73]
	v_mfma_f32_16x16x32_f16 v[114:117], v[146:149], v[202:205], v[122:125]
	v_mfma_f32_16x16x32_f16 v[134:137], v[130:133], v[198:201], v[114:117]
	v_mfma_f32_16x16x32_f16 v[114:117], v[150:153], v[198:201], v[126:129]
	v_mfma_f32_16x16x32_f16 v[126:129], v[154:157], v[202:205], v[114:117]
	v_mfma_f32_16x16x32_f16 v[98:101], v[154:157], v[194:197], v[98:101]
	v_mfma_f32_16x16x32_f16 v[98:101], v[150:153], v[190:193], v[98:101]
	v_mfma_f32_16x16x32_f16 v[102:105], v[130:133], v[190:193], v[102:105]
	v_mfma_f32_16x16x32_f16 v[102:105], v[146:149], v[194:197], v[102:105]
	s_barrier
	v_mfma_f32_16x16x32_f16 v[86:89], v[146:149], v[186:189], v[86:89]
	v_mfma_f32_16x16x32_f16 v[86:89], v[130:133], v[182:185], v[86:89]
	v_mfma_f32_16x16x32_f16 v[82:85], v[150:153], v[182:185], v[82:85]
	v_mfma_f32_16x16x32_f16 v[82:85], v[154:157], v[186:189], v[82:85]
	v_mfma_f32_16x16x32_f16 v[66:69], v[154:157], v[178:181], v[66:69]
	v_mfma_f32_16x16x32_f16 v[66:69], v[150:153], v[174:177], v[66:69]
	s_setprio 0
	ds_read_b128 v[186:189], v215 offset:49152
	ds_read_b128 v[190:193], v215 offset:50176
	ds_read_b128 v[178:181], v215 offset:51200
	ds_read_b128 v[182:185], v215 offset:52224
	ds_read_b128 v[122:125], v215 offset:53248
	ds_read_b128 v[174:177], v215 offset:54272
	ds_read_b128 v[114:117], v215 offset:55296
	ds_read_b128 v[118:121], v215 offset:56320
	s_and_b64 vcc, exec, s[6:7]
	s_cbranch_vccnz .LBB0_1164
	s_add_u32 s6, s24, 0x80
	s_addc_u32 s7, s25, 0
	s_add_u32 s24, s8, 0x80
	s_addc_u32 s25, s9, 0
	s_add_u32 m0, s35, 0x18000
	s_nop 0
	global_load_lds_dwordx4 v210, s[24:25]
	s_nop 0
	s_add_u32 m0, s35, 0x1a000
	s_nop 0
	global_load_lds_dwordx4 v212, s[24:25]
	s_add_u32 s8, s8, 0x40080
	s_addc_u32 s9, s9, 0
	s_add_u32 m0, s35, 0x1c000
	s_nop 0
	global_load_lds_dwordx4 v210, s[8:9]
	s_nop 0
	s_add_u32 m0, s35, 0x1e000
	s_nop 0
	global_load_lds_dwordx4 v212, s[8:9]
	s_nop 0
	s_add_u32 m0, s35, 0x8000
	s_nop 0
	global_load_lds_dwordx4 v1, s[6:7]
	s_nop 0
	s_add_u32 m0, s35, 0xa000
	s_nop 0
	global_load_lds_dwordx4 v211, s[6:7]
	s_waitcnt vmcnt(8)
	s_branch .LBB0_1164
